# pipelined adaln K-loops (3 row-batches in flight, LDS reads double-buffered) in the up-GEMM tail and P0; batched silu init
# speedup vs baseline: 1.0567x; 1.0140x over previous
; DI void adaln_layer(const Frame& F, int l, int b_idx, int b_cnt) {
;     ...
;     for (int i = F.tid; i < NSEQ * DM; i += 512) { const int s = i >> 10, k = i & 1023; const float c = s < 2 ? cp[s * DM + k] : cs[(s - 2) * DM + k]; sc[i] = c / (1.f + __expf(-c)); }
.LBB0_4:
	s_or_b64 exec, exec, s[0:1]
	s_add_i32 s0, 0, 0x23010
	v_mov_b32_e32 v1, s0
	s_add_i32 s0, 0, 0x23018
	ds_read_b64 v[2:3], v1
	v_mov_b32_e32 v1, s0
	s_add_i32 s0, 0, 0x23050
	ds_read_b64 v[4:5], v1
	v_mov_b32_e32 v1, s0
	ds_read_b64 v[6:7], v1
	s_movk_i32 s4, 0x2800
	s_waitcnt lgkmcnt(0)
	v_readfirstlane_b32 s9, v3
	v_readfirstlane_b32 s8, v2
	v_readfirstlane_b32 s1, v5
	v_readfirstlane_b32 s0, v4
	v_readfirstlane_b32 s7, v7
	v_readfirstlane_b32 s6, v6
	v_cmp_gt_i32_e32 vcc, s4, v74
	s_and_saveexec_b64 s[4:5], vcc
	s_cbranch_execz .LBB0_9
	s_nop 4
	v_lshlrev_b32_e32 v12, 2, v220
	v_add_u32_e32 v15, 0x1000, v12
	global_load_dword v184, v12, s[8:9]
	global_load_dword v185, v12, s[8:9] offset:2048
	global_load_dword v186, v15, s[8:9]
	global_load_dword v187, v15, s[8:9] offset:2048
	global_load_dword v188, v12, s[0:1]
	global_load_dword v189, v12, s[0:1] offset:2048
	s_add_u32 s0, s0, 0x1000
	s_addc_u32 s1, s1, 0
	global_load_dword v190, v12, s[0:1]
	global_load_dword v191, v12, s[0:1] offset:2048
	s_add_u32 s0, s0, 0x1000
	s_addc_u32 s1, s1, 0
	global_load_dword v192, v12, s[0:1]
	global_load_dword v193, v12, s[0:1] offset:2048
	s_add_u32 s0, s0, 0x1000
	s_addc_u32 s1, s1, 0
	global_load_dword v194, v12, s[0:1]
	global_load_dword v195, v12, s[0:1] offset:2048
	s_add_u32 s0, s0, 0x1000
	s_addc_u32 s1, s1, 0
	global_load_dword v196, v12, s[0:1]
	global_load_dword v197, v12, s[0:1] offset:2048
	s_add_u32 s0, s0, 0x1000
	s_addc_u32 s1, s1, 0
	global_load_dword v198, v12, s[0:1]
	global_load_dword v199, v12, s[0:1] offset:2048
	s_add_u32 s0, s0, 0x1000
	s_addc_u32 s1, s1, 0
	global_load_dword v200, v12, s[0:1]
	global_load_dword v201, v12, s[0:1] offset:2048
	s_add_u32 s0, s0, 0x1000
	s_addc_u32 s1, s1, 0
	global_load_dword v202, v12, s[0:1]
	global_load_dword v203, v12, s[0:1] offset:2048
	v_mov_b32_e32 v1, v12
	s_waitcnt vmcnt(0)
	v_mul_f32_e32 v5, 0xbfb8aa3b, v184
	v_exp_f32_e32 v5, v5
	s_nop 0
	v_add_f32_e32 v5, 1.0, v5
	v_div_scale_f32 v7, s[20:21], v5, v5, v184
	v_rcp_f32_e32 v8, v7
	s_nop 0
	v_fma_f32 v9, -v7, v8, 1.0
	v_fmac_f32_e32 v8, v9, v8
	v_div_scale_f32 v9, vcc, v184, v5, v184
	v_mul_f32_e32 v2, v9, v8
	v_fma_f32 v3, -v7, v2, v9
	v_fmac_f32_e32 v2, v3, v8
	v_fma_f32 v7, -v7, v2, v9
	v_div_fmas_f32 v7, v7, v8, v2
	v_div_fixup_f32 v4, v7, v5, v184
	ds_write_b32 v1, v4
	v_mul_f32_e32 v5, 0xbfb8aa3b, v185
	v_exp_f32_e32 v5, v5
	s_nop 0
	v_add_f32_e32 v5, 1.0, v5
	v_div_scale_f32 v7, s[20:21], v5, v5, v185
	v_rcp_f32_e32 v8, v7
	s_nop 0
	v_fma_f32 v9, -v7, v8, 1.0
	v_fmac_f32_e32 v8, v9, v8
	v_div_scale_f32 v9, vcc, v185, v5, v185
	v_mul_f32_e32 v2, v9, v8
	v_fma_f32 v3, -v7, v2, v9
	v_fmac_f32_e32 v2, v3, v8
	v_fma_f32 v7, -v7, v2, v9
	v_div_fmas_f32 v7, v7, v8, v2
	v_div_fixup_f32 v4, v7, v5, v185
	ds_write_b32 v1, v4 offset:2048
	v_mul_f32_e32 v5, 0xbfb8aa3b, v186
	v_exp_f32_e32 v5, v5
	s_nop 0
	v_add_f32_e32 v5, 1.0, v5
	v_div_scale_f32 v7, s[20:21], v5, v5, v186
	v_rcp_f32_e32 v8, v7
	s_nop 0
	v_fma_f32 v9, -v7, v8, 1.0
	v_fmac_f32_e32 v8, v9, v8
	v_div_scale_f32 v9, vcc, v186, v5, v186
	v_mul_f32_e32 v2, v9, v8
	v_fma_f32 v3, -v7, v2, v9
	v_fmac_f32_e32 v2, v3, v8
	v_fma_f32 v7, -v7, v2, v9
	v_div_fmas_f32 v7, v7, v8, v2
	v_div_fixup_f32 v4, v7, v5, v186
	ds_write_b32 v1, v4 offset:4096
	v_mul_f32_e32 v5, 0xbfb8aa3b, v187
	v_exp_f32_e32 v5, v5
	s_nop 0
	v_add_f32_e32 v5, 1.0, v5
	v_div_scale_f32 v7, s[20:21], v5, v5, v187
	v_rcp_f32_e32 v8, v7
	s_nop 0
	v_fma_f32 v9, -v7, v8, 1.0
	v_fmac_f32_e32 v8, v9, v8
	v_div_scale_f32 v9, vcc, v187, v5, v187
	v_mul_f32_e32 v2, v9, v8
	v_fma_f32 v3, -v7, v2, v9
	v_fmac_f32_e32 v2, v3, v8
	v_fma_f32 v7, -v7, v2, v9
	v_div_fmas_f32 v7, v7, v8, v2
	v_div_fixup_f32 v4, v7, v5, v187
	ds_write_b32 v1, v4 offset:6144
	v_mul_f32_e32 v5, 0xbfb8aa3b, v188
	v_exp_f32_e32 v5, v5
	s_nop 0
	v_add_f32_e32 v5, 1.0, v5
	v_div_scale_f32 v7, s[20:21], v5, v5, v188
	v_rcp_f32_e32 v8, v7
	s_nop 0
	v_fma_f32 v9, -v7, v8, 1.0
	v_fmac_f32_e32 v8, v9, v8
	v_div_scale_f32 v9, vcc, v188, v5, v188
	v_mul_f32_e32 v2, v9, v8
	v_fma_f32 v3, -v7, v2, v9
	v_fmac_f32_e32 v2, v3, v8
	v_fma_f32 v7, -v7, v2, v9
	v_div_fmas_f32 v7, v7, v8, v2
	v_div_fixup_f32 v4, v7, v5, v188
	ds_write_b32 v1, v4 offset:8192
	v_mul_f32_e32 v5, 0xbfb8aa3b, v189
	v_exp_f32_e32 v5, v5
	s_nop 0
	v_add_f32_e32 v5, 1.0, v5
	v_div_scale_f32 v7, s[20:21], v5, v5, v189
	v_rcp_f32_e32 v8, v7
	s_nop 0
	v_fma_f32 v9, -v7, v8, 1.0
	v_fmac_f32_e32 v8, v9, v8
	v_div_scale_f32 v9, vcc, v189, v5, v189
	v_mul_f32_e32 v2, v9, v8
	v_fma_f32 v3, -v7, v2, v9
	v_fmac_f32_e32 v2, v3, v8
	v_fma_f32 v7, -v7, v2, v9
	v_div_fmas_f32 v7, v7, v8, v2
	v_div_fixup_f32 v4, v7, v5, v189
	ds_write_b32 v1, v4 offset:10240
	v_mul_f32_e32 v5, 0xbfb8aa3b, v190
	v_exp_f32_e32 v5, v5
	s_nop 0
	v_add_f32_e32 v5, 1.0, v5
	v_div_scale_f32 v7, s[20:21], v5, v5, v190
	v_rcp_f32_e32 v8, v7
	s_nop 0
	v_fma_f32 v9, -v7, v8, 1.0
	v_fmac_f32_e32 v8, v9, v8
	v_div_scale_f32 v9, vcc, v190, v5, v190
	v_mul_f32_e32 v2, v9, v8
	v_fma_f32 v3, -v7, v2, v9
	v_fmac_f32_e32 v2, v3, v8
	v_fma_f32 v7, -v7, v2, v9
	v_div_fmas_f32 v7, v7, v8, v2
	v_div_fixup_f32 v4, v7, v5, v190
	ds_write_b32 v1, v4 offset:12288
	v_mul_f32_e32 v5, 0xbfb8aa3b, v191
	v_exp_f32_e32 v5, v5
	s_nop 0
	v_add_f32_e32 v5, 1.0, v5
	v_div_scale_f32 v7, s[20:21], v5, v5, v191
	v_rcp_f32_e32 v8, v7
	s_nop 0
	v_fma_f32 v9, -v7, v8, 1.0
	v_fmac_f32_e32 v8, v9, v8
	v_div_scale_f32 v9, vcc, v191, v5, v191
	v_mul_f32_e32 v2, v9, v8
	v_fma_f32 v3, -v7, v2, v9
	v_fmac_f32_e32 v2, v3, v8
	v_fma_f32 v7, -v7, v2, v9
	v_div_fmas_f32 v7, v7, v8, v2
	v_div_fixup_f32 v4, v7, v5, v191
	ds_write_b32 v1, v4 offset:14336
; DI void adaln_layer(const Frame& F, int l, int b_idx, int b_cnt) {
;     ...
;     for (int i = F.tid; i < NSEQ * DM; i += 512) { const int s = i >> 10, k = i & 1023; const float c = s < 2 ? cp[s * DM + k] : cs[(s - 2) * DM + k]; sc[i] = c / (1.f + __expf(-c)); }
	v_mul_f32_e32 v5, 0xbfb8aa3b, v192
	v_exp_f32_e32 v5, v5
	s_nop 0
	v_add_f32_e32 v5, 1.0, v5
	v_div_scale_f32 v7, s[20:21], v5, v5, v192
	v_rcp_f32_e32 v8, v7
	s_nop 0
	v_fma_f32 v9, -v7, v8, 1.0
	v_fmac_f32_e32 v8, v9, v8
	v_div_scale_f32 v9, vcc, v192, v5, v192
	v_mul_f32_e32 v2, v9, v8
	v_fma_f32 v3, -v7, v2, v9
	v_fmac_f32_e32 v2, v3, v8
	v_fma_f32 v7, -v7, v2, v9
	v_div_fmas_f32 v7, v7, v8, v2
	v_div_fixup_f32 v4, v7, v5, v192
	ds_write_b32 v1, v4 offset:16384
	v_mul_f32_e32 v5, 0xbfb8aa3b, v193
	v_exp_f32_e32 v5, v5
	s_nop 0
	v_add_f32_e32 v5, 1.0, v5
	v_div_scale_f32 v7, s[20:21], v5, v5, v193
	v_rcp_f32_e32 v8, v7
	s_nop 0
	v_fma_f32 v9, -v7, v8, 1.0
	v_fmac_f32_e32 v8, v9, v8
	v_div_scale_f32 v9, vcc, v193, v5, v193
	v_mul_f32_e32 v2, v9, v8
	v_fma_f32 v3, -v7, v2, v9
	v_fmac_f32_e32 v2, v3, v8
	v_fma_f32 v7, -v7, v2, v9
	v_div_fmas_f32 v7, v7, v8, v2
	v_div_fixup_f32 v4, v7, v5, v193
	ds_write_b32 v1, v4 offset:18432
	v_mul_f32_e32 v5, 0xbfb8aa3b, v194
	v_exp_f32_e32 v5, v5
	s_nop 0
	v_add_f32_e32 v5, 1.0, v5
	v_div_scale_f32 v7, s[20:21], v5, v5, v194
	v_rcp_f32_e32 v8, v7
	s_nop 0
	v_fma_f32 v9, -v7, v8, 1.0
	v_fmac_f32_e32 v8, v9, v8
	v_div_scale_f32 v9, vcc, v194, v5, v194
	v_mul_f32_e32 v2, v9, v8
	v_fma_f32 v3, -v7, v2, v9
	v_fmac_f32_e32 v2, v3, v8
	v_fma_f32 v7, -v7, v2, v9
	v_div_fmas_f32 v7, v7, v8, v2
	v_div_fixup_f32 v4, v7, v5, v194
	ds_write_b32 v1, v4 offset:20480
	v_mul_f32_e32 v5, 0xbfb8aa3b, v195
	v_exp_f32_e32 v5, v5
	s_nop 0
	v_add_f32_e32 v5, 1.0, v5
	v_div_scale_f32 v7, s[20:21], v5, v5, v195
	v_rcp_f32_e32 v8, v7
	s_nop 0
	v_fma_f32 v9, -v7, v8, 1.0
	v_fmac_f32_e32 v8, v9, v8
	v_div_scale_f32 v9, vcc, v195, v5, v195
	v_mul_f32_e32 v2, v9, v8
	v_fma_f32 v3, -v7, v2, v9
	v_fmac_f32_e32 v2, v3, v8
	v_fma_f32 v7, -v7, v2, v9
	v_div_fmas_f32 v7, v7, v8, v2
	v_div_fixup_f32 v4, v7, v5, v195
	ds_write_b32 v1, v4 offset:22528
	v_mul_f32_e32 v5, 0xbfb8aa3b, v196
	v_exp_f32_e32 v5, v5
	s_nop 0
	v_add_f32_e32 v5, 1.0, v5
	v_div_scale_f32 v7, s[20:21], v5, v5, v196
	v_rcp_f32_e32 v8, v7
	s_nop 0
	v_fma_f32 v9, -v7, v8, 1.0
	v_fmac_f32_e32 v8, v9, v8
	v_div_scale_f32 v9, vcc, v196, v5, v196
	v_mul_f32_e32 v2, v9, v8
	v_fma_f32 v3, -v7, v2, v9
	v_fmac_f32_e32 v2, v3, v8
	v_fma_f32 v7, -v7, v2, v9
	v_div_fmas_f32 v7, v7, v8, v2
	v_div_fixup_f32 v4, v7, v5, v196
	ds_write_b32 v1, v4 offset:24576
	v_mul_f32_e32 v5, 0xbfb8aa3b, v197
	v_exp_f32_e32 v5, v5
	s_nop 0
	v_add_f32_e32 v5, 1.0, v5
	v_div_scale_f32 v7, s[20:21], v5, v5, v197
	v_rcp_f32_e32 v8, v7
	s_nop 0
	v_fma_f32 v9, -v7, v8, 1.0
	v_fmac_f32_e32 v8, v9, v8
	v_div_scale_f32 v9, vcc, v197, v5, v197
	v_mul_f32_e32 v2, v9, v8
	v_fma_f32 v3, -v7, v2, v9
	v_fmac_f32_e32 v2, v3, v8
	v_fma_f32 v7, -v7, v2, v9
	v_div_fmas_f32 v7, v7, v8, v2
	v_div_fixup_f32 v4, v7, v5, v197
	ds_write_b32 v1, v4 offset:26624
	v_mul_f32_e32 v5, 0xbfb8aa3b, v198
	v_exp_f32_e32 v5, v5
	s_nop 0
	v_add_f32_e32 v5, 1.0, v5
	v_div_scale_f32 v7, s[20:21], v5, v5, v198
	v_rcp_f32_e32 v8, v7
	s_nop 0
	v_fma_f32 v9, -v7, v8, 1.0
	v_fmac_f32_e32 v8, v9, v8
	v_div_scale_f32 v9, vcc, v198, v5, v198
	v_mul_f32_e32 v2, v9, v8
	v_fma_f32 v3, -v7, v2, v9
	v_fmac_f32_e32 v2, v3, v8
	v_fma_f32 v7, -v7, v2, v9
	v_div_fmas_f32 v7, v7, v8, v2
	v_div_fixup_f32 v4, v7, v5, v198
	ds_write_b32 v1, v4 offset:28672
	v_mul_f32_e32 v5, 0xbfb8aa3b, v199
	v_exp_f32_e32 v5, v5
	s_nop 0
	v_add_f32_e32 v5, 1.0, v5
	v_div_scale_f32 v7, s[20:21], v5, v5, v199
	v_rcp_f32_e32 v8, v7
	s_nop 0
	v_fma_f32 v9, -v7, v8, 1.0
	v_fmac_f32_e32 v8, v9, v8
	v_div_scale_f32 v9, vcc, v199, v5, v199
	v_mul_f32_e32 v2, v9, v8
	v_fma_f32 v3, -v7, v2, v9
	v_fmac_f32_e32 v2, v3, v8
	v_fma_f32 v7, -v7, v2, v9
	v_div_fmas_f32 v7, v7, v8, v2
	v_div_fixup_f32 v4, v7, v5, v199
	ds_write_b32 v1, v4 offset:30720
	v_mul_f32_e32 v5, 0xbfb8aa3b, v200
	v_exp_f32_e32 v5, v5
	s_nop 0
	v_add_f32_e32 v5, 1.0, v5
	v_div_scale_f32 v7, s[20:21], v5, v5, v200
	v_rcp_f32_e32 v8, v7
	s_nop 0
	v_fma_f32 v9, -v7, v8, 1.0
	v_fmac_f32_e32 v8, v9, v8
	v_div_scale_f32 v9, vcc, v200, v5, v200
	v_mul_f32_e32 v2, v9, v8
	v_fma_f32 v3, -v7, v2, v9
	v_fmac_f32_e32 v2, v3, v8
	v_fma_f32 v7, -v7, v2, v9
	v_div_fmas_f32 v7, v7, v8, v2
	v_div_fixup_f32 v4, v7, v5, v200
	ds_write_b32 v1, v4 offset:32768
	v_mul_f32_e32 v5, 0xbfb8aa3b, v201
	v_exp_f32_e32 v5, v5
	s_nop 0
	v_add_f32_e32 v5, 1.0, v5
	v_div_scale_f32 v7, s[20:21], v5, v5, v201
	v_rcp_f32_e32 v8, v7
	s_nop 0
	v_fma_f32 v9, -v7, v8, 1.0
	v_fmac_f32_e32 v8, v9, v8
	v_div_scale_f32 v9, vcc, v201, v5, v201
	v_mul_f32_e32 v2, v9, v8
	v_fma_f32 v3, -v7, v2, v9
	v_fmac_f32_e32 v2, v3, v8
	v_fma_f32 v7, -v7, v2, v9
	v_div_fmas_f32 v7, v7, v8, v2
	v_div_fixup_f32 v4, v7, v5, v201
	ds_write_b32 v1, v4 offset:34816
	v_mul_f32_e32 v5, 0xbfb8aa3b, v202
	v_exp_f32_e32 v5, v5
	s_nop 0
	v_add_f32_e32 v5, 1.0, v5
	v_div_scale_f32 v7, s[20:21], v5, v5, v202
	v_rcp_f32_e32 v8, v7
	s_nop 0
	v_fma_f32 v9, -v7, v8, 1.0
	v_fmac_f32_e32 v8, v9, v8
	v_div_scale_f32 v9, vcc, v202, v5, v202
	v_mul_f32_e32 v2, v9, v8
	v_fma_f32 v3, -v7, v2, v9
	v_fmac_f32_e32 v2, v3, v8
	v_fma_f32 v7, -v7, v2, v9
	v_div_fmas_f32 v7, v7, v8, v2
	v_div_fixup_f32 v4, v7, v5, v202
	ds_write_b32 v1, v4 offset:36864
	v_mul_f32_e32 v5, 0xbfb8aa3b, v203
	v_exp_f32_e32 v5, v5
	s_nop 0
	v_add_f32_e32 v5, 1.0, v5
	v_div_scale_f32 v7, s[20:21], v5, v5, v203
	v_rcp_f32_e32 v8, v7
	s_nop 0
	v_fma_f32 v9, -v7, v8, 1.0
	v_fmac_f32_e32 v8, v9, v8
	v_div_scale_f32 v9, vcc, v203, v5, v203
	v_mul_f32_e32 v2, v9, v8
	v_fma_f32 v3, -v7, v2, v9
	v_fmac_f32_e32 v2, v3, v8
	v_fma_f32 v7, -v7, v2, v9
	v_div_fmas_f32 v7, v7, v8, v2
	v_div_fixup_f32 v4, v7, v5, v203
	ds_write_b32 v1, v4 offset:38912

; #define LAS __attribute__((address_space(3)))
; DI void adaln_layer(const Frame& F, int l, int b_idx, int b_cnt) {
;     ...
;         const int k0 = F.wave * 128;
;         const float* wp_ = W + (size_t)k0 * MODW;
; #pragma unroll 1
;         for (int kb = k0; kb < k0 + 128; kb += 16) {
;             float wv[16];
; #pragma unroll
;             for (int i = 0; i < 16; ++i) { wv[i] = __builtin_nontemporal_load(wp_); wp_ += MODW; }
; #pragma unroll
;             for (int i = 0; i < 16; i += 4) {
; #pragma unroll
;                 for (int s = 0; s < NSEQ; ++s) { const f32x4 c4 = *(const LAS f32x4*)(sc + s * DM + kb + i); acc[s] += (c4[0] * wv[i] + c4[1] * wv[i + 1]) + (c4[2] * wv[i + 2] + c4[3] * wv[i + 3]); } }
;         }
.LBB0_12:
	ds_read_b64 v[2:3], v75
	s_lshl_b32 s8, s19, 6
	s_ashr_i32 s9, s8, 31
	s_lshl_b64 s[8:9], s[8:9], 2
	v_mov_b32_e32 v92, 0
	s_waitcnt lgkmcnt(0)
	v_readfirstlane_b32 s10, v2
	v_readfirstlane_b32 s2, v3
	s_add_u32 s10, s10, s8
	s_addc_u32 s11, s2, s9
	v_lshl_add_u64 v[2:3], s[10:11], 0, v[78:79]
	v_lshl_add_u64 v[84:85], v[2:3], 0, s[0:1]
	s_mov_b32 s10, s17
	s_mov_b32 s11, s16
	v_mov_b32_e32 v93, v79
	v_mov_b32_e32 v90, 0
	v_mov_b32_e32 v91, v79
	v_mov_b32_e32 v88, 0
	v_mov_b32_e32 v89, v79
	v_mov_b32_e32 v86, 0
	v_mov_b32_e32 v87, v79
	v_mov_b32_e32 v96, 0
	v_mov_b32_e32 v97, v79
	v_readfirstlane_b32 s20, v84
	v_readfirstlane_b32 s21, v85
	v_and_b32_e32 v15, 63, v220
	v_lshlrev_b32_e32 v15, 2, v15
	v_mov_b32_e32 v12, s10
	s_nop 4
	global_load_dword v184, v15, s[20:21] nt
	s_add_u32 s20, s20, 0x9000
	s_addc_u32 s21, s21, 0
	global_load_dword v185, v15, s[20:21] nt
	s_add_u32 s20, s20, 0x9000
	s_addc_u32 s21, s21, 0
	global_load_dword v186, v15, s[20:21] nt
	s_add_u32 s20, s20, 0x9000
	s_addc_u32 s21, s21, 0
	global_load_dword v187, v15, s[20:21] nt
	s_add_u32 s20, s20, 0x9000
	s_addc_u32 s21, s21, 0
	global_load_dword v188, v15, s[20:21] nt
	s_add_u32 s20, s20, 0x9000
	s_addc_u32 s21, s21, 0
	global_load_dword v189, v15, s[20:21] nt
	s_add_u32 s20, s20, 0x9000
	s_addc_u32 s21, s21, 0
	global_load_dword v190, v15, s[20:21] nt
	s_add_u32 s20, s20, 0x9000
	s_addc_u32 s21, s21, 0
	global_load_dword v191, v15, s[20:21] nt
	s_add_u32 s20, s20, 0x9000
	s_addc_u32 s21, s21, 0
	global_load_dword v192, v15, s[20:21] nt
	s_add_u32 s20, s20, 0x9000
	s_addc_u32 s21, s21, 0
	global_load_dword v193, v15, s[20:21] nt
	s_add_u32 s20, s20, 0x9000
	s_addc_u32 s21, s21, 0
	global_load_dword v194, v15, s[20:21] nt
	s_add_u32 s20, s20, 0x9000
	s_addc_u32 s21, s21, 0
	global_load_dword v195, v15, s[20:21] nt
	s_add_u32 s20, s20, 0x9000
	s_addc_u32 s21, s21, 0
	global_load_dword v196, v15, s[20:21] nt
	s_add_u32 s20, s20, 0x9000
	s_addc_u32 s21, s21, 0
	global_load_dword v197, v15, s[20:21] nt
	s_add_u32 s20, s20, 0x9000
	s_addc_u32 s21, s21, 0
	global_load_dword v198, v15, s[20:21] nt
	s_add_u32 s20, s20, 0x9000
	s_addc_u32 s21, s21, 0
	global_load_dword v199, v15, s[20:21] nt
	s_add_u32 s20, s20, 0x9000
	s_addc_u32 s21, s21, 0
	global_load_dword v206, v15, s[20:21] nt
	s_add_u32 s20, s20, 0x9000
	s_addc_u32 s21, s21, 0
	global_load_dword v207, v15, s[20:21] nt
	s_add_u32 s20, s20, 0x9000
	s_addc_u32 s21, s21, 0
	global_load_dword v208, v15, s[20:21] nt
	s_add_u32 s20, s20, 0x9000
	s_addc_u32 s21, s21, 0
	global_load_dword v209, v15, s[20:21] nt
	s_add_u32 s20, s20, 0x9000
	s_addc_u32 s21, s21, 0
	global_load_dword v210, v15, s[20:21] nt
	s_add_u32 s20, s20, 0x9000
	s_addc_u32 s21, s21, 0
	global_load_dword v211, v15, s[20:21] nt
	s_add_u32 s20, s20, 0x9000
	s_addc_u32 s21, s21, 0
	global_load_dword v212, v15, s[20:21] nt
	s_add_u32 s20, s20, 0x9000
	s_addc_u32 s21, s21, 0
	global_load_dword v213, v15, s[20:21] nt
	s_add_u32 s20, s20, 0x9000
	s_addc_u32 s21, s21, 0
	global_load_dword v214, v15, s[20:21] nt
	s_add_u32 s20, s20, 0x9000
	s_addc_u32 s21, s21, 0
	global_load_dword v215, v15, s[20:21] nt
	s_add_u32 s20, s20, 0x9000
	s_addc_u32 s21, s21, 0
	global_load_dword v216, v15, s[20:21] nt
	s_add_u32 s20, s20, 0x9000
	s_addc_u32 s21, s21, 0
	global_load_dword v217, v15, s[20:21] nt
	s_add_u32 s20, s20, 0x9000
	s_addc_u32 s21, s21, 0
	global_load_dword v218, v15, s[20:21] nt
	s_add_u32 s20, s20, 0x9000
	s_addc_u32 s21, s21, 0
	global_load_dword v221, v15, s[20:21] nt
	s_add_u32 s20, s20, 0x9000
	s_addc_u32 s21, s21, 0
	global_load_dword v222, v15, s[20:21] nt
	s_add_u32 s20, s20, 0x9000
	s_addc_u32 s21, s21, 0
	global_load_dword v223, v15, s[20:21] nt
	s_add_u32 s20, s20, 0x9000
	s_addc_u32 s21, s21, 0
	global_load_dword v224, v15, s[20:21] nt
	s_add_u32 s20, s20, 0x9000
	s_addc_u32 s21, s21, 0
	global_load_dword v225, v15, s[20:21] nt
	s_add_u32 s20, s20, 0x9000
	s_addc_u32 s21, s21, 0
	global_load_dword v226, v15, s[20:21] nt
	s_add_u32 s20, s20, 0x9000
	s_addc_u32 s21, s21, 0
	global_load_dword v227, v15, s[20:21] nt
	s_add_u32 s20, s20, 0x9000
	s_addc_u32 s21, s21, 0
	global_load_dword v228, v15, s[20:21] nt
	s_add_u32 s20, s20, 0x9000
	s_addc_u32 s21, s21, 0
	global_load_dword v229, v15, s[20:21] nt
	s_add_u32 s20, s20, 0x9000
	s_addc_u32 s21, s21, 0
	global_load_dword v230, v15, s[20:21] nt
	s_add_u32 s20, s20, 0x9000
	s_addc_u32 s21, s21, 0
	global_load_dword v231, v15, s[20:21] nt
	s_add_u32 s20, s20, 0x9000
	s_addc_u32 s21, s21, 0
	global_load_dword v232, v15, s[20:21] nt
	s_add_u32 s20, s20, 0x9000
	s_addc_u32 s21, s21, 0
	global_load_dword v233, v15, s[20:21] nt
	s_add_u32 s20, s20, 0x9000
	s_addc_u32 s21, s21, 0
	global_load_dword v234, v15, s[20:21] nt
	s_add_u32 s20, s20, 0x9000
	s_addc_u32 s21, s21, 0
	global_load_dword v235, v15, s[20:21] nt
	s_add_u32 s20, s20, 0x9000
	s_addc_u32 s21, s21, 0
	global_load_dword v236, v15, s[20:21] nt
	s_add_u32 s20, s20, 0x9000
	s_addc_u32 s21, s21, 0
	global_load_dword v237, v15, s[20:21] nt
	s_add_u32 s20, s20, 0x9000
	s_addc_u32 s21, s21, 0
	global_load_dword v238, v15, s[20:21] nt
	s_add_u32 s20, s20, 0x9000
	s_addc_u32 s21, s21, 0
	global_load_dword v239, v15, s[20:21] nt
	s_add_u32 s20, s20, 0x9000
	s_addc_u32 s21, s21, 0
	s_waitcnt vmcnt(32)
	ds_read_b128 v[2:5], v12 offset:0
	ds_read_b128 v[6:9], v12 offset:4096
	ds_read_b128 v[22:25], v12 offset:8192
	ds_read_b128 v[30:33], v12 offset:12288
	ds_read_b128 v[34:37], v12 offset:16384
	ds_read_b128 v[38:41], v12 offset:20480
	ds_read_b128 v[42:45], v12 offset:24576
	ds_read_b128 v[46:49], v12 offset:28672
	ds_read_b128 v[50:53], v12 offset:32768
	ds_read_b128 v[60:63], v12 offset:36864
	s_waitcnt lgkmcnt(5)
; #define LAS __attribute__((address_space(3)))
; DI void adaln_layer(const Frame& F, int l, int b_idx, int b_cnt) {
;     ...
;         const int k0 = F.wave * 128;
;         const float* wp_ = W + (size_t)k0 * MODW;
; #pragma unroll 1
;         for (int kb = k0; kb < k0 + 128; kb += 16) {
;             float wv[16];
; #pragma unroll
;             for (int i = 0; i < 16; ++i) { wv[i] = __builtin_nontemporal_load(wp_); wp_ += MODW; }
; #pragma unroll
;             for (int i = 0; i < 16; i += 4) {
; #pragma unroll
;                 for (int s = 0; s < NSEQ; ++s) { const f32x4 c4 = *(const LAS f32x4*)(sc + s * DM + kb + i); acc[s] += (c4[0] * wv[i] + c4[1] * wv[i + 1]) + (c4[2] * wv[i + 2] + c4[3] * wv[i + 3]); } }
;         }
	v_fmac_f32_e32 v92, v2, v184
	v_fmac_f32_e32 v92, v3, v185
	v_fmac_f32_e32 v92, v4, v186
	v_fmac_f32_e32 v92, v5, v187
	v_fmac_f32_e32 v93, v6, v184
	v_fmac_f32_e32 v93, v7, v185
	v_fmac_f32_e32 v93, v8, v186
	v_fmac_f32_e32 v93, v9, v187
	v_fmac_f32_e32 v90, v22, v184
	v_fmac_f32_e32 v90, v23, v185
	v_fmac_f32_e32 v90, v24, v186
	v_fmac_f32_e32 v90, v25, v187
	v_fmac_f32_e32 v91, v30, v184
	v_fmac_f32_e32 v91, v31, v185
	v_fmac_f32_e32 v91, v32, v186
	v_fmac_f32_e32 v91, v33, v187
	v_fmac_f32_e32 v88, v34, v184
	v_fmac_f32_e32 v88, v35, v185
	v_fmac_f32_e32 v88, v36, v186
	v_fmac_f32_e32 v88, v37, v187
	ds_read_b128 v[2:5], v12 offset:16
	ds_read_b128 v[6:9], v12 offset:4112
	ds_read_b128 v[22:25], v12 offset:8208
	ds_read_b128 v[30:33], v12 offset:12304
	ds_read_b128 v[34:37], v12 offset:16400
	s_waitcnt lgkmcnt(5)
	v_fmac_f32_e32 v89, v38, v184
	v_fmac_f32_e32 v89, v39, v185
	v_fmac_f32_e32 v89, v40, v186
	v_fmac_f32_e32 v89, v41, v187
	v_fmac_f32_e32 v86, v42, v184
	v_fmac_f32_e32 v86, v43, v185
	v_fmac_f32_e32 v86, v44, v186
	v_fmac_f32_e32 v86, v45, v187
	v_fmac_f32_e32 v87, v46, v184
	v_fmac_f32_e32 v87, v47, v185
	v_fmac_f32_e32 v87, v48, v186
	v_fmac_f32_e32 v87, v49, v187
	v_fmac_f32_e32 v96, v50, v184
	v_fmac_f32_e32 v96, v51, v185
	v_fmac_f32_e32 v96, v52, v186
	v_fmac_f32_e32 v96, v53, v187
	v_fmac_f32_e32 v97, v60, v184
	v_fmac_f32_e32 v97, v61, v185
	v_fmac_f32_e32 v97, v62, v186
	v_fmac_f32_e32 v97, v63, v187
	ds_read_b128 v[38:41], v12 offset:20496
	ds_read_b128 v[42:45], v12 offset:24592
	ds_read_b128 v[46:49], v12 offset:28688
	ds_read_b128 v[50:53], v12 offset:32784
	ds_read_b128 v[60:63], v12 offset:36880
	s_waitcnt lgkmcnt(5)
	v_fmac_f32_e32 v92, v2, v188
	v_fmac_f32_e32 v92, v3, v189
	v_fmac_f32_e32 v92, v4, v190
	v_fmac_f32_e32 v92, v5, v191
	v_fmac_f32_e32 v93, v6, v188
	v_fmac_f32_e32 v93, v7, v189
	v_fmac_f32_e32 v93, v8, v190
	v_fmac_f32_e32 v93, v9, v191
	v_fmac_f32_e32 v90, v22, v188
	v_fmac_f32_e32 v90, v23, v189
	v_fmac_f32_e32 v90, v24, v190
	v_fmac_f32_e32 v90, v25, v191
	v_fmac_f32_e32 v91, v30, v188
	v_fmac_f32_e32 v91, v31, v189
	v_fmac_f32_e32 v91, v32, v190
	v_fmac_f32_e32 v91, v33, v191
	v_fmac_f32_e32 v88, v34, v188
	v_fmac_f32_e32 v88, v35, v189
	v_fmac_f32_e32 v88, v36, v190
	v_fmac_f32_e32 v88, v37, v191
	ds_read_b128 v[2:5], v12 offset:32
	ds_read_b128 v[6:9], v12 offset:4128
	ds_read_b128 v[22:25], v12 offset:8224
	ds_read_b128 v[30:33], v12 offset:12320
	ds_read_b128 v[34:37], v12 offset:16416
	s_waitcnt lgkmcnt(5)
	v_fmac_f32_e32 v89, v38, v188
	v_fmac_f32_e32 v89, v39, v189
	v_fmac_f32_e32 v89, v40, v190
	v_fmac_f32_e32 v89, v41, v191
	v_fmac_f32_e32 v86, v42, v188
	v_fmac_f32_e32 v86, v43, v189
	v_fmac_f32_e32 v86, v44, v190
	v_fmac_f32_e32 v86, v45, v191
	v_fmac_f32_e32 v87, v46, v188
	v_fmac_f32_e32 v87, v47, v189
	v_fmac_f32_e32 v87, v48, v190
	v_fmac_f32_e32 v87, v49, v191
	v_fmac_f32_e32 v96, v50, v188
	v_fmac_f32_e32 v96, v51, v189
	v_fmac_f32_e32 v96, v52, v190
	v_fmac_f32_e32 v96, v53, v191
	v_fmac_f32_e32 v97, v60, v188
	v_fmac_f32_e32 v97, v61, v189
	v_fmac_f32_e32 v97, v62, v190
	v_fmac_f32_e32 v97, v63, v191
	ds_read_b128 v[38:41], v12 offset:20512
	ds_read_b128 v[42:45], v12 offset:24608
	ds_read_b128 v[46:49], v12 offset:28704
	ds_read_b128 v[50:53], v12 offset:32800
	ds_read_b128 v[60:63], v12 offset:36896
	s_waitcnt lgkmcnt(5)
	v_fmac_f32_e32 v92, v2, v192
	v_fmac_f32_e32 v92, v3, v193
	v_fmac_f32_e32 v92, v4, v194
	v_fmac_f32_e32 v92, v5, v195
	v_fmac_f32_e32 v93, v6, v192
	v_fmac_f32_e32 v93, v7, v193
	v_fmac_f32_e32 v93, v8, v194
	v_fmac_f32_e32 v93, v9, v195
	v_fmac_f32_e32 v90, v22, v192
	v_fmac_f32_e32 v90, v23, v193
	v_fmac_f32_e32 v90, v24, v194
	v_fmac_f32_e32 v90, v25, v195
	v_fmac_f32_e32 v91, v30, v192
	v_fmac_f32_e32 v91, v31, v193
	v_fmac_f32_e32 v91, v32, v194
	v_fmac_f32_e32 v91, v33, v195
	v_fmac_f32_e32 v88, v34, v192
	v_fmac_f32_e32 v88, v35, v193
	v_fmac_f32_e32 v88, v36, v194
	v_fmac_f32_e32 v88, v37, v195
	ds_read_b128 v[2:5], v12 offset:48
	ds_read_b128 v[6:9], v12 offset:4144
	ds_read_b128 v[22:25], v12 offset:8240
	ds_read_b128 v[30:33], v12 offset:12336
	ds_read_b128 v[34:37], v12 offset:16432
	s_waitcnt lgkmcnt(5)
	v_fmac_f32_e32 v89, v38, v192
	v_fmac_f32_e32 v89, v39, v193
	v_fmac_f32_e32 v89, v40, v194
	v_fmac_f32_e32 v89, v41, v195
	v_fmac_f32_e32 v86, v42, v192
	v_fmac_f32_e32 v86, v43, v193
	v_fmac_f32_e32 v86, v44, v194
	v_fmac_f32_e32 v86, v45, v195
	v_fmac_f32_e32 v87, v46, v192
	v_fmac_f32_e32 v87, v47, v193
	v_fmac_f32_e32 v87, v48, v194
	v_fmac_f32_e32 v87, v49, v195
	v_fmac_f32_e32 v96, v50, v192
	v_fmac_f32_e32 v96, v51, v193
	v_fmac_f32_e32 v96, v52, v194
	v_fmac_f32_e32 v96, v53, v195
	v_fmac_f32_e32 v97, v60, v192
	v_fmac_f32_e32 v97, v61, v193
	v_fmac_f32_e32 v97, v62, v194
	v_fmac_f32_e32 v97, v63, v195
	ds_read_b128 v[38:41], v12 offset:20528
	ds_read_b128 v[42:45], v12 offset:24624
	ds_read_b128 v[46:49], v12 offset:28720
	ds_read_b128 v[50:53], v12 offset:32816
	ds_read_b128 v[60:63], v12 offset:36912
	s_waitcnt lgkmcnt(5)
	v_fmac_f32_e32 v92, v2, v196
	v_fmac_f32_e32 v92, v3, v197
	v_fmac_f32_e32 v92, v4, v198
	v_fmac_f32_e32 v92, v5, v199
	v_fmac_f32_e32 v93, v6, v196
	v_fmac_f32_e32 v93, v7, v197
	v_fmac_f32_e32 v93, v8, v198
	v_fmac_f32_e32 v93, v9, v199
	v_fmac_f32_e32 v90, v22, v196
	v_fmac_f32_e32 v90, v23, v197
	v_fmac_f32_e32 v90, v24, v198
	v_fmac_f32_e32 v90, v25, v199
	v_fmac_f32_e32 v91, v30, v196
	v_fmac_f32_e32 v91, v31, v197
	v_fmac_f32_e32 v91, v32, v198
	v_fmac_f32_e32 v91, v33, v199
	v_fmac_f32_e32 v88, v34, v196
	v_fmac_f32_e32 v88, v35, v197
	v_fmac_f32_e32 v88, v36, v198
	v_fmac_f32_e32 v88, v37, v199
	s_waitcnt lgkmcnt(0)
; #define LAS __attribute__((address_space(3)))
; DI void adaln_layer(const Frame& F, int l, int b_idx, int b_cnt) {
;     ...
;         const int k0 = F.wave * 128;
;         const float* wp_ = W + (size_t)k0 * MODW;
; #pragma unroll 1
;         for (int kb = k0; kb < k0 + 128; kb += 16) {
;             float wv[16];
; #pragma unroll
;             for (int i = 0; i < 16; ++i) { wv[i] = __builtin_nontemporal_load(wp_); wp_ += MODW; }
; #pragma unroll
;             for (int i = 0; i < 16; i += 4) {
; #pragma unroll
;                 for (int s = 0; s < NSEQ; ++s) { const f32x4 c4 = *(const LAS f32x4*)(sc + s * DM + kb + i); acc[s] += (c4[0] * wv[i] + c4[1] * wv[i + 1]) + (c4[2] * wv[i + 2] + c4[3] * wv[i + 3]); } }
;         }
	v_fmac_f32_e32 v89, v38, v196
	v_fmac_f32_e32 v89, v39, v197
	v_fmac_f32_e32 v89, v40, v198
	v_fmac_f32_e32 v89, v41, v199
	v_fmac_f32_e32 v86, v42, v196
	v_fmac_f32_e32 v86, v43, v197
	v_fmac_f32_e32 v86, v44, v198
	v_fmac_f32_e32 v86, v45, v199
	v_fmac_f32_e32 v87, v46, v196
	v_fmac_f32_e32 v87, v47, v197
	v_fmac_f32_e32 v87, v48, v198
	v_fmac_f32_e32 v87, v49, v199
	v_fmac_f32_e32 v96, v50, v196
	v_fmac_f32_e32 v96, v51, v197
	v_fmac_f32_e32 v96, v52, v198
	v_fmac_f32_e32 v96, v53, v199
	v_fmac_f32_e32 v97, v60, v196
	v_fmac_f32_e32 v97, v61, v197
	v_fmac_f32_e32 v97, v62, v198
	v_fmac_f32_e32 v97, v63, v199
	global_load_dword v184, v15, s[20:21] nt
	s_add_u32 s20, s20, 0x9000
	s_addc_u32 s21, s21, 0
	global_load_dword v185, v15, s[20:21] nt
	s_add_u32 s20, s20, 0x9000
	s_addc_u32 s21, s21, 0
	global_load_dword v186, v15, s[20:21] nt
	s_add_u32 s20, s20, 0x9000
	s_addc_u32 s21, s21, 0
	global_load_dword v187, v15, s[20:21] nt
	s_add_u32 s20, s20, 0x9000
	s_addc_u32 s21, s21, 0
	global_load_dword v188, v15, s[20:21] nt
	s_add_u32 s20, s20, 0x9000
	s_addc_u32 s21, s21, 0
	global_load_dword v189, v15, s[20:21] nt
	s_add_u32 s20, s20, 0x9000
	s_addc_u32 s21, s21, 0
	global_load_dword v190, v15, s[20:21] nt
	s_add_u32 s20, s20, 0x9000
	s_addc_u32 s21, s21, 0
	global_load_dword v191, v15, s[20:21] nt
	s_add_u32 s20, s20, 0x9000
	s_addc_u32 s21, s21, 0
	global_load_dword v192, v15, s[20:21] nt
	s_add_u32 s20, s20, 0x9000
	s_addc_u32 s21, s21, 0
	global_load_dword v193, v15, s[20:21] nt
	s_add_u32 s20, s20, 0x9000
	s_addc_u32 s21, s21, 0
	global_load_dword v194, v15, s[20:21] nt
	s_add_u32 s20, s20, 0x9000
	s_addc_u32 s21, s21, 0
	global_load_dword v195, v15, s[20:21] nt
	s_add_u32 s20, s20, 0x9000
	s_addc_u32 s21, s21, 0
	global_load_dword v196, v15, s[20:21] nt
	s_add_u32 s20, s20, 0x9000
	s_addc_u32 s21, s21, 0
	global_load_dword v197, v15, s[20:21] nt
	s_add_u32 s20, s20, 0x9000
	s_addc_u32 s21, s21, 0
	global_load_dword v198, v15, s[20:21] nt
	s_add_u32 s20, s20, 0x9000
	s_addc_u32 s21, s21, 0
	global_load_dword v199, v15, s[20:21] nt
	s_add_u32 s20, s20, 0x9000
	s_addc_u32 s21, s21, 0
	s_waitcnt vmcnt(32)
	ds_read_b128 v[2:5], v12 offset:64
	ds_read_b128 v[6:9], v12 offset:4160
	ds_read_b128 v[22:25], v12 offset:8256
	ds_read_b128 v[30:33], v12 offset:12352
	ds_read_b128 v[34:37], v12 offset:16448
	ds_read_b128 v[38:41], v12 offset:20544
	ds_read_b128 v[42:45], v12 offset:24640
	ds_read_b128 v[46:49], v12 offset:28736
	ds_read_b128 v[50:53], v12 offset:32832
	ds_read_b128 v[60:63], v12 offset:36928
	s_waitcnt lgkmcnt(5)
	v_fmac_f32_e32 v92, v2, v206
	v_fmac_f32_e32 v92, v3, v207
	v_fmac_f32_e32 v92, v4, v208
	v_fmac_f32_e32 v92, v5, v209
	v_fmac_f32_e32 v93, v6, v206
	v_fmac_f32_e32 v93, v7, v207
	v_fmac_f32_e32 v93, v8, v208
	v_fmac_f32_e32 v93, v9, v209
	v_fmac_f32_e32 v90, v22, v206
	v_fmac_f32_e32 v90, v23, v207
	v_fmac_f32_e32 v90, v24, v208
	v_fmac_f32_e32 v90, v25, v209
	v_fmac_f32_e32 v91, v30, v206
	v_fmac_f32_e32 v91, v31, v207
	v_fmac_f32_e32 v91, v32, v208
	v_fmac_f32_e32 v91, v33, v209
	v_fmac_f32_e32 v88, v34, v206
	v_fmac_f32_e32 v88, v35, v207
	v_fmac_f32_e32 v88, v36, v208
	v_fmac_f32_e32 v88, v37, v209
	ds_read_b128 v[2:5], v12 offset:80
	ds_read_b128 v[6:9], v12 offset:4176
	ds_read_b128 v[22:25], v12 offset:8272
	ds_read_b128 v[30:33], v12 offset:12368
	ds_read_b128 v[34:37], v12 offset:16464
	s_waitcnt lgkmcnt(5)
	v_fmac_f32_e32 v89, v38, v206
	v_fmac_f32_e32 v89, v39, v207
	v_fmac_f32_e32 v89, v40, v208
	v_fmac_f32_e32 v89, v41, v209
	v_fmac_f32_e32 v86, v42, v206
	v_fmac_f32_e32 v86, v43, v207
	v_fmac_f32_e32 v86, v44, v208
	v_fmac_f32_e32 v86, v45, v209
	v_fmac_f32_e32 v87, v46, v206
	v_fmac_f32_e32 v87, v47, v207
	v_fmac_f32_e32 v87, v48, v208
	v_fmac_f32_e32 v87, v49, v209
	v_fmac_f32_e32 v96, v50, v206
	v_fmac_f32_e32 v96, v51, v207
	v_fmac_f32_e32 v96, v52, v208
	v_fmac_f32_e32 v96, v53, v209
	v_fmac_f32_e32 v97, v60, v206
	v_fmac_f32_e32 v97, v61, v207
	v_fmac_f32_e32 v97, v62, v208
	v_fmac_f32_e32 v97, v63, v209
	ds_read_b128 v[38:41], v12 offset:20560
	ds_read_b128 v[42:45], v12 offset:24656
	ds_read_b128 v[46:49], v12 offset:28752
	ds_read_b128 v[50:53], v12 offset:32848
	ds_read_b128 v[60:63], v12 offset:36944
	s_waitcnt lgkmcnt(5)
	v_fmac_f32_e32 v92, v2, v210
	v_fmac_f32_e32 v92, v3, v211
	v_fmac_f32_e32 v92, v4, v212
	v_fmac_f32_e32 v92, v5, v213
	v_fmac_f32_e32 v93, v6, v210
	v_fmac_f32_e32 v93, v7, v211
	v_fmac_f32_e32 v93, v8, v212
	v_fmac_f32_e32 v93, v9, v213
	v_fmac_f32_e32 v90, v22, v210
	v_fmac_f32_e32 v90, v23, v211
	v_fmac_f32_e32 v90, v24, v212
	v_fmac_f32_e32 v90, v25, v213
	v_fmac_f32_e32 v91, v30, v210
	v_fmac_f32_e32 v91, v31, v211
	v_fmac_f32_e32 v91, v32, v212
	v_fmac_f32_e32 v91, v33, v213
	v_fmac_f32_e32 v88, v34, v210
	v_fmac_f32_e32 v88, v35, v211
	v_fmac_f32_e32 v88, v36, v212
	v_fmac_f32_e32 v88, v37, v213
	ds_read_b128 v[2:5], v12 offset:96
	ds_read_b128 v[6:9], v12 offset:4192
	ds_read_b128 v[22:25], v12 offset:8288
	ds_read_b128 v[30:33], v12 offset:12384
	ds_read_b128 v[34:37], v12 offset:16480
	s_waitcnt lgkmcnt(5)
	v_fmac_f32_e32 v89, v38, v210
	v_fmac_f32_e32 v89, v39, v211
	v_fmac_f32_e32 v89, v40, v212
	v_fmac_f32_e32 v89, v41, v213
	v_fmac_f32_e32 v86, v42, v210
	v_fmac_f32_e32 v86, v43, v211
	v_fmac_f32_e32 v86, v44, v212
	v_fmac_f32_e32 v86, v45, v213
	v_fmac_f32_e32 v87, v46, v210
	v_fmac_f32_e32 v87, v47, v211
	v_fmac_f32_e32 v87, v48, v212
	v_fmac_f32_e32 v87, v49, v213
	v_fmac_f32_e32 v96, v50, v210
	v_fmac_f32_e32 v96, v51, v211
	v_fmac_f32_e32 v96, v52, v212
	v_fmac_f32_e32 v96, v53, v213
	v_fmac_f32_e32 v97, v60, v210
	v_fmac_f32_e32 v97, v61, v211
	v_fmac_f32_e32 v97, v62, v212
	v_fmac_f32_e32 v97, v63, v213
	ds_read_b128 v[38:41], v12 offset:20576
	ds_read_b128 v[42:45], v12 offset:24672
	ds_read_b128 v[46:49], v12 offset:28768
	ds_read_b128 v[50:53], v12 offset:32864
	ds_read_b128 v[60:63], v12 offset:36960
	s_waitcnt lgkmcnt(5)
; #define LAS __attribute__((address_space(3)))
; DI void adaln_layer(const Frame& F, int l, int b_idx, int b_cnt) {
;     ...
; #pragma unroll 1
;         for (int kb = k0; kb < k0 + 128; kb += 16) {
;             float wv[16];
; #pragma unroll
;             for (int i = 0; i < 16; ++i) { wv[i] = __builtin_nontemporal_load(wp_); wp_ += MODW; }
; #pragma unroll
;             for (int i = 0; i < 16; i += 4) {
; #pragma unroll
;                 for (int s = 0; s < NSEQ; ++s) { const f32x4 c4 = *(const LAS f32x4*)(sc + s * DM + kb + i); acc[s] += (c4[0] * wv[i] + c4[1] * wv[i + 1]) + (c4[2] * wv[i + 2] + c4[3] * wv[i + 3]); } }
	v_fmac_f32_e32 v92, v2, v214
	v_fmac_f32_e32 v92, v3, v215
	v_fmac_f32_e32 v92, v4, v216
	v_fmac_f32_e32 v92, v5, v217
	v_fmac_f32_e32 v93, v6, v214
	v_fmac_f32_e32 v93, v7, v215
	v_fmac_f32_e32 v93, v8, v216
	v_fmac_f32_e32 v93, v9, v217
	v_fmac_f32_e32 v90, v22, v214
	v_fmac_f32_e32 v90, v23, v215
	v_fmac_f32_e32 v90, v24, v216
	v_fmac_f32_e32 v90, v25, v217
	v_fmac_f32_e32 v91, v30, v214
	v_fmac_f32_e32 v91, v31, v215
	v_fmac_f32_e32 v91, v32, v216
	v_fmac_f32_e32 v91, v33, v217
	v_fmac_f32_e32 v88, v34, v214
	v_fmac_f32_e32 v88, v35, v215
	v_fmac_f32_e32 v88, v36, v216
	v_fmac_f32_e32 v88, v37, v217
	ds_read_b128 v[2:5], v12 offset:112
	ds_read_b128 v[6:9], v12 offset:4208
	ds_read_b128 v[22:25], v12 offset:8304
	ds_read_b128 v[30:33], v12 offset:12400
	ds_read_b128 v[34:37], v12 offset:16496
	s_waitcnt lgkmcnt(5)
	v_fmac_f32_e32 v89, v38, v214
	v_fmac_f32_e32 v89, v39, v215
	v_fmac_f32_e32 v89, v40, v216
	v_fmac_f32_e32 v89, v41, v217
	v_fmac_f32_e32 v86, v42, v214
	v_fmac_f32_e32 v86, v43, v215
	v_fmac_f32_e32 v86, v44, v216
	v_fmac_f32_e32 v86, v45, v217
	v_fmac_f32_e32 v87, v46, v214
	v_fmac_f32_e32 v87, v47, v215
	v_fmac_f32_e32 v87, v48, v216
	v_fmac_f32_e32 v87, v49, v217
	v_fmac_f32_e32 v96, v50, v214
	v_fmac_f32_e32 v96, v51, v215
	v_fmac_f32_e32 v96, v52, v216
	v_fmac_f32_e32 v96, v53, v217
	v_fmac_f32_e32 v97, v60, v214
	v_fmac_f32_e32 v97, v61, v215
	v_fmac_f32_e32 v97, v62, v216
	v_fmac_f32_e32 v97, v63, v217
	ds_read_b128 v[38:41], v12 offset:20592
	ds_read_b128 v[42:45], v12 offset:24688
	ds_read_b128 v[46:49], v12 offset:28784
	ds_read_b128 v[50:53], v12 offset:32880
	ds_read_b128 v[60:63], v12 offset:36976
	s_waitcnt lgkmcnt(5)
	v_fmac_f32_e32 v92, v2, v218
	v_fmac_f32_e32 v92, v3, v221
	v_fmac_f32_e32 v92, v4, v222
	v_fmac_f32_e32 v92, v5, v223
	v_fmac_f32_e32 v93, v6, v218
	v_fmac_f32_e32 v93, v7, v221
	v_fmac_f32_e32 v93, v8, v222
	v_fmac_f32_e32 v93, v9, v223
	v_fmac_f32_e32 v90, v22, v218
	v_fmac_f32_e32 v90, v23, v221
	v_fmac_f32_e32 v90, v24, v222
	v_fmac_f32_e32 v90, v25, v223
	v_fmac_f32_e32 v91, v30, v218
	v_fmac_f32_e32 v91, v31, v221
	v_fmac_f32_e32 v91, v32, v222
	v_fmac_f32_e32 v91, v33, v223
	v_fmac_f32_e32 v88, v34, v218
	v_fmac_f32_e32 v88, v35, v221
	v_fmac_f32_e32 v88, v36, v222
	v_fmac_f32_e32 v88, v37, v223
	s_waitcnt lgkmcnt(0)
	v_fmac_f32_e32 v89, v38, v218
	v_fmac_f32_e32 v89, v39, v221
	v_fmac_f32_e32 v89, v40, v222
	v_fmac_f32_e32 v89, v41, v223
	v_fmac_f32_e32 v86, v42, v218
	v_fmac_f32_e32 v86, v43, v221
	v_fmac_f32_e32 v86, v44, v222
	v_fmac_f32_e32 v86, v45, v223
	v_fmac_f32_e32 v87, v46, v218
	v_fmac_f32_e32 v87, v47, v221
	v_fmac_f32_e32 v87, v48, v222
	v_fmac_f32_e32 v87, v49, v223
	v_fmac_f32_e32 v96, v50, v218
	v_fmac_f32_e32 v96, v51, v221
	v_fmac_f32_e32 v96, v52, v222
	v_fmac_f32_e32 v96, v53, v223
	v_fmac_f32_e32 v97, v60, v218
	v_fmac_f32_e32 v97, v61, v221
	v_fmac_f32_e32 v97, v62, v222
	v_fmac_f32_e32 v97, v63, v223
	global_load_dword v206, v15, s[20:21] nt
	s_add_u32 s20, s20, 0x9000
	s_addc_u32 s21, s21, 0
	global_load_dword v207, v15, s[20:21] nt
	s_add_u32 s20, s20, 0x9000
	s_addc_u32 s21, s21, 0
	global_load_dword v208, v15, s[20:21] nt
	s_add_u32 s20, s20, 0x9000
	s_addc_u32 s21, s21, 0
	global_load_dword v209, v15, s[20:21] nt
	s_add_u32 s20, s20, 0x9000
	s_addc_u32 s21, s21, 0
	global_load_dword v210, v15, s[20:21] nt
	s_add_u32 s20, s20, 0x9000
	s_addc_u32 s21, s21, 0
	global_load_dword v211, v15, s[20:21] nt
	s_add_u32 s20, s20, 0x9000
	s_addc_u32 s21, s21, 0
	global_load_dword v212, v15, s[20:21] nt
	s_add_u32 s20, s20, 0x9000
	s_addc_u32 s21, s21, 0
	global_load_dword v213, v15, s[20:21] nt
	s_add_u32 s20, s20, 0x9000
	s_addc_u32 s21, s21, 0
	global_load_dword v214, v15, s[20:21] nt
	s_add_u32 s20, s20, 0x9000
	s_addc_u32 s21, s21, 0
	global_load_dword v215, v15, s[20:21] nt
	s_add_u32 s20, s20, 0x9000
	s_addc_u32 s21, s21, 0
	global_load_dword v216, v15, s[20:21] nt
	s_add_u32 s20, s20, 0x9000
	s_addc_u32 s21, s21, 0
	global_load_dword v217, v15, s[20:21] nt
	s_add_u32 s20, s20, 0x9000
	s_addc_u32 s21, s21, 0
	global_load_dword v218, v15, s[20:21] nt
	s_add_u32 s20, s20, 0x9000
	s_addc_u32 s21, s21, 0
	global_load_dword v221, v15, s[20:21] nt
	s_add_u32 s20, s20, 0x9000
	s_addc_u32 s21, s21, 0
	global_load_dword v222, v15, s[20:21] nt
	s_add_u32 s20, s20, 0x9000
	s_addc_u32 s21, s21, 0
	global_load_dword v223, v15, s[20:21] nt
	s_add_u32 s20, s20, 0x9000
	s_addc_u32 s21, s21, 0
	s_waitcnt vmcnt(32)
	ds_read_b128 v[2:5], v12 offset:128
	ds_read_b128 v[6:9], v12 offset:4224
	ds_read_b128 v[22:25], v12 offset:8320
	ds_read_b128 v[30:33], v12 offset:12416
	ds_read_b128 v[34:37], v12 offset:16512
	ds_read_b128 v[38:41], v12 offset:20608
	ds_read_b128 v[42:45], v12 offset:24704
	ds_read_b128 v[46:49], v12 offset:28800
	ds_read_b128 v[50:53], v12 offset:32896
	ds_read_b128 v[60:63], v12 offset:36992
	s_waitcnt lgkmcnt(5)
	v_fmac_f32_e32 v92, v2, v224
	v_fmac_f32_e32 v92, v3, v225
	v_fmac_f32_e32 v92, v4, v226
	v_fmac_f32_e32 v92, v5, v227
	v_fmac_f32_e32 v93, v6, v224
	v_fmac_f32_e32 v93, v7, v225
	v_fmac_f32_e32 v93, v8, v226
	v_fmac_f32_e32 v93, v9, v227
	v_fmac_f32_e32 v90, v22, v224
	v_fmac_f32_e32 v90, v23, v225
	v_fmac_f32_e32 v90, v24, v226
	v_fmac_f32_e32 v90, v25, v227
	v_fmac_f32_e32 v91, v30, v224
	v_fmac_f32_e32 v91, v31, v225
	v_fmac_f32_e32 v91, v32, v226
	v_fmac_f32_e32 v91, v33, v227
	v_fmac_f32_e32 v88, v34, v224
	v_fmac_f32_e32 v88, v35, v225
	v_fmac_f32_e32 v88, v36, v226
	v_fmac_f32_e32 v88, v37, v227
	ds_read_b128 v[2:5], v12 offset:144
	ds_read_b128 v[6:9], v12 offset:4240
	ds_read_b128 v[22:25], v12 offset:8336
	ds_read_b128 v[30:33], v12 offset:12432
	ds_read_b128 v[34:37], v12 offset:16528
	s_waitcnt lgkmcnt(5)
; #define LAS __attribute__((address_space(3)))
; DI void adaln_layer(const Frame& F, int l, int b_idx, int b_cnt) {
;     ...
; #pragma unroll 1
;         for (int kb = k0; kb < k0 + 128; kb += 16) {
;             float wv[16];
; #pragma unroll
;             for (int i = 0; i < 16; ++i) { wv[i] = __builtin_nontemporal_load(wp_); wp_ += MODW; }
; #pragma unroll
;             for (int i = 0; i < 16; i += 4) {
; #pragma unroll
;                 for (int s = 0; s < NSEQ; ++s) { const f32x4 c4 = *(const LAS f32x4*)(sc + s * DM + kb + i); acc[s] += (c4[0] * wv[i] + c4[1] * wv[i + 1]) + (c4[2] * wv[i + 2] + c4[3] * wv[i + 3]); } }
	v_fmac_f32_e32 v89, v38, v224
	v_fmac_f32_e32 v89, v39, v225
	v_fmac_f32_e32 v89, v40, v226
	v_fmac_f32_e32 v89, v41, v227
	v_fmac_f32_e32 v86, v42, v224
	v_fmac_f32_e32 v86, v43, v225
	v_fmac_f32_e32 v86, v44, v226
	v_fmac_f32_e32 v86, v45, v227
	v_fmac_f32_e32 v87, v46, v224
	v_fmac_f32_e32 v87, v47, v225
	v_fmac_f32_e32 v87, v48, v226
	v_fmac_f32_e32 v87, v49, v227
	v_fmac_f32_e32 v96, v50, v224
	v_fmac_f32_e32 v96, v51, v225
	v_fmac_f32_e32 v96, v52, v226
	v_fmac_f32_e32 v96, v53, v227
	v_fmac_f32_e32 v97, v60, v224
	v_fmac_f32_e32 v97, v61, v225
	v_fmac_f32_e32 v97, v62, v226
	v_fmac_f32_e32 v97, v63, v227
	ds_read_b128 v[38:41], v12 offset:20624
	ds_read_b128 v[42:45], v12 offset:24720
	ds_read_b128 v[46:49], v12 offset:28816
	ds_read_b128 v[50:53], v12 offset:32912
	ds_read_b128 v[60:63], v12 offset:37008
	s_waitcnt lgkmcnt(5)
	v_fmac_f32_e32 v92, v2, v228
	v_fmac_f32_e32 v92, v3, v229
	v_fmac_f32_e32 v92, v4, v230
	v_fmac_f32_e32 v92, v5, v231
	v_fmac_f32_e32 v93, v6, v228
	v_fmac_f32_e32 v93, v7, v229
	v_fmac_f32_e32 v93, v8, v230
	v_fmac_f32_e32 v93, v9, v231
	v_fmac_f32_e32 v90, v22, v228
	v_fmac_f32_e32 v90, v23, v229
	v_fmac_f32_e32 v90, v24, v230
	v_fmac_f32_e32 v90, v25, v231
	v_fmac_f32_e32 v91, v30, v228
	v_fmac_f32_e32 v91, v31, v229
	v_fmac_f32_e32 v91, v32, v230
	v_fmac_f32_e32 v91, v33, v231
	v_fmac_f32_e32 v88, v34, v228
	v_fmac_f32_e32 v88, v35, v229
	v_fmac_f32_e32 v88, v36, v230
	v_fmac_f32_e32 v88, v37, v231
	ds_read_b128 v[2:5], v12 offset:160
	ds_read_b128 v[6:9], v12 offset:4256
	ds_read_b128 v[22:25], v12 offset:8352
	ds_read_b128 v[30:33], v12 offset:12448
	ds_read_b128 v[34:37], v12 offset:16544
	s_waitcnt lgkmcnt(5)
	v_fmac_f32_e32 v89, v38, v228
	v_fmac_f32_e32 v89, v39, v229
	v_fmac_f32_e32 v89, v40, v230
	v_fmac_f32_e32 v89, v41, v231
	v_fmac_f32_e32 v86, v42, v228
	v_fmac_f32_e32 v86, v43, v229
	v_fmac_f32_e32 v86, v44, v230
	v_fmac_f32_e32 v86, v45, v231
	v_fmac_f32_e32 v87, v46, v228
	v_fmac_f32_e32 v87, v47, v229
	v_fmac_f32_e32 v87, v48, v230
	v_fmac_f32_e32 v87, v49, v231
	v_fmac_f32_e32 v96, v50, v228
	v_fmac_f32_e32 v96, v51, v229
	v_fmac_f32_e32 v96, v52, v230
	v_fmac_f32_e32 v96, v53, v231
	v_fmac_f32_e32 v97, v60, v228
	v_fmac_f32_e32 v97, v61, v229
	v_fmac_f32_e32 v97, v62, v230
	v_fmac_f32_e32 v97, v63, v231
	ds_read_b128 v[38:41], v12 offset:20640
	ds_read_b128 v[42:45], v12 offset:24736
	ds_read_b128 v[46:49], v12 offset:28832
	ds_read_b128 v[50:53], v12 offset:32928
	ds_read_b128 v[60:63], v12 offset:37024
	s_waitcnt lgkmcnt(5)
	v_fmac_f32_e32 v92, v2, v232
	v_fmac_f32_e32 v92, v3, v233
	v_fmac_f32_e32 v92, v4, v234
	v_fmac_f32_e32 v92, v5, v235
	v_fmac_f32_e32 v93, v6, v232
	v_fmac_f32_e32 v93, v7, v233
	v_fmac_f32_e32 v93, v8, v234
	v_fmac_f32_e32 v93, v9, v235
	v_fmac_f32_e32 v90, v22, v232
	v_fmac_f32_e32 v90, v23, v233
	v_fmac_f32_e32 v90, v24, v234
	v_fmac_f32_e32 v90, v25, v235
	v_fmac_f32_e32 v91, v30, v232
	v_fmac_f32_e32 v91, v31, v233
	v_fmac_f32_e32 v91, v32, v234
	v_fmac_f32_e32 v91, v33, v235
	v_fmac_f32_e32 v88, v34, v232
	v_fmac_f32_e32 v88, v35, v233
	v_fmac_f32_e32 v88, v36, v234
	v_fmac_f32_e32 v88, v37, v235
	ds_read_b128 v[2:5], v12 offset:176
	ds_read_b128 v[6:9], v12 offset:4272
	ds_read_b128 v[22:25], v12 offset:8368
	ds_read_b128 v[30:33], v12 offset:12464
	ds_read_b128 v[34:37], v12 offset:16560
	s_waitcnt lgkmcnt(5)
	v_fmac_f32_e32 v89, v38, v232
	v_fmac_f32_e32 v89, v39, v233
	v_fmac_f32_e32 v89, v40, v234
	v_fmac_f32_e32 v89, v41, v235
	v_fmac_f32_e32 v86, v42, v232
	v_fmac_f32_e32 v86, v43, v233
	v_fmac_f32_e32 v86, v44, v234
	v_fmac_f32_e32 v86, v45, v235
	v_fmac_f32_e32 v87, v46, v232
	v_fmac_f32_e32 v87, v47, v233
	v_fmac_f32_e32 v87, v48, v234
	v_fmac_f32_e32 v87, v49, v235
	v_fmac_f32_e32 v96, v50, v232
	v_fmac_f32_e32 v96, v51, v233
	v_fmac_f32_e32 v96, v52, v234
	v_fmac_f32_e32 v96, v53, v235
	v_fmac_f32_e32 v97, v60, v232
	v_fmac_f32_e32 v97, v61, v233
	v_fmac_f32_e32 v97, v62, v234
	v_fmac_f32_e32 v97, v63, v235
	ds_read_b128 v[38:41], v12 offset:20656
	ds_read_b128 v[42:45], v12 offset:24752
	ds_read_b128 v[46:49], v12 offset:28848
	ds_read_b128 v[50:53], v12 offset:32944
	ds_read_b128 v[60:63], v12 offset:37040
	s_waitcnt lgkmcnt(5)
	v_fmac_f32_e32 v92, v2, v236
	v_fmac_f32_e32 v92, v3, v237
	v_fmac_f32_e32 v92, v4, v238
	v_fmac_f32_e32 v92, v5, v239
	v_fmac_f32_e32 v93, v6, v236
	v_fmac_f32_e32 v93, v7, v237
	v_fmac_f32_e32 v93, v8, v238
	v_fmac_f32_e32 v93, v9, v239
	v_fmac_f32_e32 v90, v22, v236
	v_fmac_f32_e32 v90, v23, v237
	v_fmac_f32_e32 v90, v24, v238
	v_fmac_f32_e32 v90, v25, v239
	v_fmac_f32_e32 v91, v30, v236
	v_fmac_f32_e32 v91, v31, v237
	v_fmac_f32_e32 v91, v32, v238
	v_fmac_f32_e32 v91, v33, v239
	v_fmac_f32_e32 v88, v34, v236
	v_fmac_f32_e32 v88, v35, v237
	v_fmac_f32_e32 v88, v36, v238
	v_fmac_f32_e32 v88, v37, v239
	s_waitcnt lgkmcnt(0)
; #define LAS __attribute__((address_space(3)))
; DI void adaln_layer(const Frame& F, int l, int b_idx, int b_cnt) {
;     ...
; #pragma unroll 1
;         for (int kb = k0; kb < k0 + 128; kb += 16) {
;             float wv[16];
; #pragma unroll
;             for (int i = 0; i < 16; ++i) { wv[i] = __builtin_nontemporal_load(wp_); wp_ += MODW; }
; #pragma unroll
;             for (int i = 0; i < 16; i += 4) {
; #pragma unroll
;                 for (int s = 0; s < NSEQ; ++s) { const f32x4 c4 = *(const LAS f32x4*)(sc + s * DM + kb + i); acc[s] += (c4[0] * wv[i] + c4[1] * wv[i + 1]) + (c4[2] * wv[i + 2] + c4[3] * wv[i + 3]); } }
	v_fmac_f32_e32 v89, v38, v236
	v_fmac_f32_e32 v89, v39, v237
	v_fmac_f32_e32 v89, v40, v238
	v_fmac_f32_e32 v89, v41, v239
	v_fmac_f32_e32 v86, v42, v236
	v_fmac_f32_e32 v86, v43, v237
	v_fmac_f32_e32 v86, v44, v238
	v_fmac_f32_e32 v86, v45, v239
	v_fmac_f32_e32 v87, v46, v236
	v_fmac_f32_e32 v87, v47, v237
	v_fmac_f32_e32 v87, v48, v238
	v_fmac_f32_e32 v87, v49, v239
	v_fmac_f32_e32 v96, v50, v236
	v_fmac_f32_e32 v96, v51, v237
	v_fmac_f32_e32 v96, v52, v238
	v_fmac_f32_e32 v96, v53, v239
	v_fmac_f32_e32 v97, v60, v236
	v_fmac_f32_e32 v97, v61, v237
	v_fmac_f32_e32 v97, v62, v238
	v_fmac_f32_e32 v97, v63, v239
	global_load_dword v224, v15, s[20:21] nt
	s_add_u32 s20, s20, 0x9000
	s_addc_u32 s21, s21, 0
	global_load_dword v225, v15, s[20:21] nt
	s_add_u32 s20, s20, 0x9000
	s_addc_u32 s21, s21, 0
	global_load_dword v226, v15, s[20:21] nt
	s_add_u32 s20, s20, 0x9000
	s_addc_u32 s21, s21, 0
	global_load_dword v227, v15, s[20:21] nt
	s_add_u32 s20, s20, 0x9000
	s_addc_u32 s21, s21, 0
	global_load_dword v228, v15, s[20:21] nt
	s_add_u32 s20, s20, 0x9000
	s_addc_u32 s21, s21, 0
	global_load_dword v229, v15, s[20:21] nt
	s_add_u32 s20, s20, 0x9000
	s_addc_u32 s21, s21, 0
	global_load_dword v230, v15, s[20:21] nt
	s_add_u32 s20, s20, 0x9000
	s_addc_u32 s21, s21, 0
	global_load_dword v231, v15, s[20:21] nt
	s_add_u32 s20, s20, 0x9000
	s_addc_u32 s21, s21, 0
	global_load_dword v232, v15, s[20:21] nt
	s_add_u32 s20, s20, 0x9000
	s_addc_u32 s21, s21, 0
	global_load_dword v233, v15, s[20:21] nt
	s_add_u32 s20, s20, 0x9000
	s_addc_u32 s21, s21, 0
	global_load_dword v234, v15, s[20:21] nt
	s_add_u32 s20, s20, 0x9000
	s_addc_u32 s21, s21, 0
	global_load_dword v235, v15, s[20:21] nt
	s_add_u32 s20, s20, 0x9000
	s_addc_u32 s21, s21, 0
	global_load_dword v236, v15, s[20:21] nt
	s_add_u32 s20, s20, 0x9000
	s_addc_u32 s21, s21, 0
	global_load_dword v237, v15, s[20:21] nt
	s_add_u32 s20, s20, 0x9000
	s_addc_u32 s21, s21, 0
	global_load_dword v238, v15, s[20:21] nt
	s_add_u32 s20, s20, 0x9000
	s_addc_u32 s21, s21, 0
	global_load_dword v239, v15, s[20:21] nt
	s_add_u32 s20, s20, 0x9000
	s_addc_u32 s21, s21, 0
	s_waitcnt vmcnt(32)
	ds_read_b128 v[2:5], v12 offset:192
	ds_read_b128 v[6:9], v12 offset:4288
	ds_read_b128 v[22:25], v12 offset:8384
	ds_read_b128 v[30:33], v12 offset:12480
	ds_read_b128 v[34:37], v12 offset:16576
	ds_read_b128 v[38:41], v12 offset:20672
	ds_read_b128 v[42:45], v12 offset:24768
	ds_read_b128 v[46:49], v12 offset:28864
	ds_read_b128 v[50:53], v12 offset:32960
	ds_read_b128 v[60:63], v12 offset:37056
	s_waitcnt lgkmcnt(5)
	v_fmac_f32_e32 v92, v2, v184
	v_fmac_f32_e32 v92, v3, v185
	v_fmac_f32_e32 v92, v4, v186
	v_fmac_f32_e32 v92, v5, v187
	v_fmac_f32_e32 v93, v6, v184
	v_fmac_f32_e32 v93, v7, v185
	v_fmac_f32_e32 v93, v8, v186
	v_fmac_f32_e32 v93, v9, v187
	v_fmac_f32_e32 v90, v22, v184
	v_fmac_f32_e32 v90, v23, v185
	v_fmac_f32_e32 v90, v24, v186
	v_fmac_f32_e32 v90, v25, v187
	v_fmac_f32_e32 v91, v30, v184
	v_fmac_f32_e32 v91, v31, v185
	v_fmac_f32_e32 v91, v32, v186
	v_fmac_f32_e32 v91, v33, v187
	v_fmac_f32_e32 v88, v34, v184
	v_fmac_f32_e32 v88, v35, v185
	v_fmac_f32_e32 v88, v36, v186
	v_fmac_f32_e32 v88, v37, v187
	ds_read_b128 v[2:5], v12 offset:208
	ds_read_b128 v[6:9], v12 offset:4304
	ds_read_b128 v[22:25], v12 offset:8400
	ds_read_b128 v[30:33], v12 offset:12496
	ds_read_b128 v[34:37], v12 offset:16592
	s_waitcnt lgkmcnt(5)
	v_fmac_f32_e32 v89, v38, v184
	v_fmac_f32_e32 v89, v39, v185
	v_fmac_f32_e32 v89, v40, v186
	v_fmac_f32_e32 v89, v41, v187
	v_fmac_f32_e32 v86, v42, v184
	v_fmac_f32_e32 v86, v43, v185
	v_fmac_f32_e32 v86, v44, v186
	v_fmac_f32_e32 v86, v45, v187
	v_fmac_f32_e32 v87, v46, v184
	v_fmac_f32_e32 v87, v47, v185
	v_fmac_f32_e32 v87, v48, v186
	v_fmac_f32_e32 v87, v49, v187
	v_fmac_f32_e32 v96, v50, v184
	v_fmac_f32_e32 v96, v51, v185
	v_fmac_f32_e32 v96, v52, v186
	v_fmac_f32_e32 v96, v53, v187
	v_fmac_f32_e32 v97, v60, v184
	v_fmac_f32_e32 v97, v61, v185
	v_fmac_f32_e32 v97, v62, v186
	v_fmac_f32_e32 v97, v63, v187
	ds_read_b128 v[38:41], v12 offset:20688
	ds_read_b128 v[42:45], v12 offset:24784
	ds_read_b128 v[46:49], v12 offset:28880
	ds_read_b128 v[50:53], v12 offset:32976
	ds_read_b128 v[60:63], v12 offset:37072
	s_waitcnt lgkmcnt(5)
	v_fmac_f32_e32 v92, v2, v188
	v_fmac_f32_e32 v92, v3, v189
	v_fmac_f32_e32 v92, v4, v190
	v_fmac_f32_e32 v92, v5, v191
	v_fmac_f32_e32 v93, v6, v188
	v_fmac_f32_e32 v93, v7, v189
	v_fmac_f32_e32 v93, v8, v190
	v_fmac_f32_e32 v93, v9, v191
	v_fmac_f32_e32 v90, v22, v188
	v_fmac_f32_e32 v90, v23, v189
	v_fmac_f32_e32 v90, v24, v190
	v_fmac_f32_e32 v90, v25, v191
	v_fmac_f32_e32 v91, v30, v188
	v_fmac_f32_e32 v91, v31, v189
	v_fmac_f32_e32 v91, v32, v190
	v_fmac_f32_e32 v91, v33, v191
	v_fmac_f32_e32 v88, v34, v188
	v_fmac_f32_e32 v88, v35, v189
	v_fmac_f32_e32 v88, v36, v190
	v_fmac_f32_e32 v88, v37, v191
	ds_read_b128 v[2:5], v12 offset:224
	ds_read_b128 v[6:9], v12 offset:4320
	ds_read_b128 v[22:25], v12 offset:8416
	ds_read_b128 v[30:33], v12 offset:12512
	ds_read_b128 v[34:37], v12 offset:16608
	s_waitcnt lgkmcnt(5)
	v_fmac_f32_e32 v89, v38, v188
	v_fmac_f32_e32 v89, v39, v189
	v_fmac_f32_e32 v89, v40, v190
	v_fmac_f32_e32 v89, v41, v191
	v_fmac_f32_e32 v86, v42, v188
	v_fmac_f32_e32 v86, v43, v189
	v_fmac_f32_e32 v86, v44, v190
	v_fmac_f32_e32 v86, v45, v191
	v_fmac_f32_e32 v87, v46, v188
	v_fmac_f32_e32 v87, v47, v189
	v_fmac_f32_e32 v87, v48, v190
	v_fmac_f32_e32 v87, v49, v191
	v_fmac_f32_e32 v96, v50, v188
	v_fmac_f32_e32 v96, v51, v189
	v_fmac_f32_e32 v96, v52, v190
	v_fmac_f32_e32 v96, v53, v191
	v_fmac_f32_e32 v97, v60, v188
	v_fmac_f32_e32 v97, v61, v189
	v_fmac_f32_e32 v97, v62, v190
	v_fmac_f32_e32 v97, v63, v191
	ds_read_b128 v[38:41], v12 offset:20704
	ds_read_b128 v[42:45], v12 offset:24800
	ds_read_b128 v[46:49], v12 offset:28896
	ds_read_b128 v[50:53], v12 offset:32992
	ds_read_b128 v[60:63], v12 offset:37088
	s_waitcnt lgkmcnt(5)
; #define LAS __attribute__((address_space(3)))
; DI void adaln_layer(const Frame& F, int l, int b_idx, int b_cnt) {
;     ...
; #pragma unroll 1
;         for (int kb = k0; kb < k0 + 128; kb += 16) {
;             float wv[16];
; #pragma unroll
;             for (int i = 0; i < 16; ++i) { wv[i] = __builtin_nontemporal_load(wp_); wp_ += MODW; }
; #pragma unroll
;             for (int i = 0; i < 16; i += 4) {
; #pragma unroll
;                 for (int s = 0; s < NSEQ; ++s) { const f32x4 c4 = *(const LAS f32x4*)(sc + s * DM + kb + i); acc[s] += (c4[0] * wv[i] + c4[1] * wv[i + 1]) + (c4[2] * wv[i + 2] + c4[3] * wv[i + 3]); } }
	v_fmac_f32_e32 v92, v2, v192
	v_fmac_f32_e32 v92, v3, v193
	v_fmac_f32_e32 v92, v4, v194
	v_fmac_f32_e32 v92, v5, v195
	v_fmac_f32_e32 v93, v6, v192
	v_fmac_f32_e32 v93, v7, v193
	v_fmac_f32_e32 v93, v8, v194
	v_fmac_f32_e32 v93, v9, v195
	v_fmac_f32_e32 v90, v22, v192
	v_fmac_f32_e32 v90, v23, v193
	v_fmac_f32_e32 v90, v24, v194
	v_fmac_f32_e32 v90, v25, v195
	v_fmac_f32_e32 v91, v30, v192
	v_fmac_f32_e32 v91, v31, v193
	v_fmac_f32_e32 v91, v32, v194
	v_fmac_f32_e32 v91, v33, v195
	v_fmac_f32_e32 v88, v34, v192
	v_fmac_f32_e32 v88, v35, v193
	v_fmac_f32_e32 v88, v36, v194
	v_fmac_f32_e32 v88, v37, v195
	ds_read_b128 v[2:5], v12 offset:240
	ds_read_b128 v[6:9], v12 offset:4336
	ds_read_b128 v[22:25], v12 offset:8432
	ds_read_b128 v[30:33], v12 offset:12528
	ds_read_b128 v[34:37], v12 offset:16624
	s_waitcnt lgkmcnt(5)
	v_fmac_f32_e32 v89, v38, v192
	v_fmac_f32_e32 v89, v39, v193
	v_fmac_f32_e32 v89, v40, v194
	v_fmac_f32_e32 v89, v41, v195
	v_fmac_f32_e32 v86, v42, v192
	v_fmac_f32_e32 v86, v43, v193
	v_fmac_f32_e32 v86, v44, v194
	v_fmac_f32_e32 v86, v45, v195
	v_fmac_f32_e32 v87, v46, v192
	v_fmac_f32_e32 v87, v47, v193
	v_fmac_f32_e32 v87, v48, v194
	v_fmac_f32_e32 v87, v49, v195
	v_fmac_f32_e32 v96, v50, v192
	v_fmac_f32_e32 v96, v51, v193
	v_fmac_f32_e32 v96, v52, v194
	v_fmac_f32_e32 v96, v53, v195
	v_fmac_f32_e32 v97, v60, v192
	v_fmac_f32_e32 v97, v61, v193
	v_fmac_f32_e32 v97, v62, v194
	v_fmac_f32_e32 v97, v63, v195
	ds_read_b128 v[38:41], v12 offset:20720
	ds_read_b128 v[42:45], v12 offset:24816
	ds_read_b128 v[46:49], v12 offset:28912
	ds_read_b128 v[50:53], v12 offset:33008
	ds_read_b128 v[60:63], v12 offset:37104
	s_waitcnt lgkmcnt(5)
	v_fmac_f32_e32 v92, v2, v196
	v_fmac_f32_e32 v92, v3, v197
	v_fmac_f32_e32 v92, v4, v198
	v_fmac_f32_e32 v92, v5, v199
	v_fmac_f32_e32 v93, v6, v196
	v_fmac_f32_e32 v93, v7, v197
	v_fmac_f32_e32 v93, v8, v198
	v_fmac_f32_e32 v93, v9, v199
	v_fmac_f32_e32 v90, v22, v196
	v_fmac_f32_e32 v90, v23, v197
	v_fmac_f32_e32 v90, v24, v198
	v_fmac_f32_e32 v90, v25, v199
	v_fmac_f32_e32 v91, v30, v196
	v_fmac_f32_e32 v91, v31, v197
	v_fmac_f32_e32 v91, v32, v198
	v_fmac_f32_e32 v91, v33, v199
	v_fmac_f32_e32 v88, v34, v196
	v_fmac_f32_e32 v88, v35, v197
	v_fmac_f32_e32 v88, v36, v198
	v_fmac_f32_e32 v88, v37, v199
	s_waitcnt lgkmcnt(0)
	v_fmac_f32_e32 v89, v38, v196
	v_fmac_f32_e32 v89, v39, v197
	v_fmac_f32_e32 v89, v40, v198
	v_fmac_f32_e32 v89, v41, v199
	v_fmac_f32_e32 v86, v42, v196
	v_fmac_f32_e32 v86, v43, v197
	v_fmac_f32_e32 v86, v44, v198
	v_fmac_f32_e32 v86, v45, v199
	v_fmac_f32_e32 v87, v46, v196
	v_fmac_f32_e32 v87, v47, v197
	v_fmac_f32_e32 v87, v48, v198
	v_fmac_f32_e32 v87, v49, v199
	v_fmac_f32_e32 v96, v50, v196
	v_fmac_f32_e32 v96, v51, v197
	v_fmac_f32_e32 v96, v52, v198
	v_fmac_f32_e32 v96, v53, v199
	v_fmac_f32_e32 v97, v60, v196
	v_fmac_f32_e32 v97, v61, v197
	v_fmac_f32_e32 v97, v62, v198
	v_fmac_f32_e32 v97, v63, v199
	global_load_dword v184, v15, s[20:21] nt
	s_add_u32 s20, s20, 0x9000
	s_addc_u32 s21, s21, 0
	global_load_dword v185, v15, s[20:21] nt
	s_add_u32 s20, s20, 0x9000
	s_addc_u32 s21, s21, 0
	global_load_dword v186, v15, s[20:21] nt
	s_add_u32 s20, s20, 0x9000
	s_addc_u32 s21, s21, 0
	global_load_dword v187, v15, s[20:21] nt
	s_add_u32 s20, s20, 0x9000
	s_addc_u32 s21, s21, 0
	global_load_dword v188, v15, s[20:21] nt
	s_add_u32 s20, s20, 0x9000
	s_addc_u32 s21, s21, 0
	global_load_dword v189, v15, s[20:21] nt
	s_add_u32 s20, s20, 0x9000
	s_addc_u32 s21, s21, 0
	global_load_dword v190, v15, s[20:21] nt
	s_add_u32 s20, s20, 0x9000
	s_addc_u32 s21, s21, 0
	global_load_dword v191, v15, s[20:21] nt
	s_add_u32 s20, s20, 0x9000
	s_addc_u32 s21, s21, 0
	global_load_dword v192, v15, s[20:21] nt
	s_add_u32 s20, s20, 0x9000
	s_addc_u32 s21, s21, 0
	global_load_dword v193, v15, s[20:21] nt
	s_add_u32 s20, s20, 0x9000
	s_addc_u32 s21, s21, 0
	global_load_dword v194, v15, s[20:21] nt
	s_add_u32 s20, s20, 0x9000
	s_addc_u32 s21, s21, 0
	global_load_dword v195, v15, s[20:21] nt
	s_add_u32 s20, s20, 0x9000
	s_addc_u32 s21, s21, 0
	global_load_dword v196, v15, s[20:21] nt
	s_add_u32 s20, s20, 0x9000
	s_addc_u32 s21, s21, 0
	global_load_dword v197, v15, s[20:21] nt
	s_add_u32 s20, s20, 0x9000
	s_addc_u32 s21, s21, 0
	global_load_dword v198, v15, s[20:21] nt
	s_add_u32 s20, s20, 0x9000
	s_addc_u32 s21, s21, 0
	global_load_dword v199, v15, s[20:21] nt
	s_add_u32 s20, s20, 0x9000
	s_addc_u32 s21, s21, 0
	s_waitcnt vmcnt(32)
	ds_read_b128 v[2:5], v12 offset:256
	ds_read_b128 v[6:9], v12 offset:4352
	ds_read_b128 v[22:25], v12 offset:8448
	ds_read_b128 v[30:33], v12 offset:12544
	ds_read_b128 v[34:37], v12 offset:16640
	ds_read_b128 v[38:41], v12 offset:20736
	ds_read_b128 v[42:45], v12 offset:24832
	ds_read_b128 v[46:49], v12 offset:28928
	ds_read_b128 v[50:53], v12 offset:33024
	ds_read_b128 v[60:63], v12 offset:37120
	s_waitcnt lgkmcnt(5)
	v_fmac_f32_e32 v92, v2, v206
	v_fmac_f32_e32 v92, v3, v207
	v_fmac_f32_e32 v92, v4, v208
	v_fmac_f32_e32 v92, v5, v209
	v_fmac_f32_e32 v93, v6, v206
	v_fmac_f32_e32 v93, v7, v207
	v_fmac_f32_e32 v93, v8, v208
	v_fmac_f32_e32 v93, v9, v209
	v_fmac_f32_e32 v90, v22, v206
	v_fmac_f32_e32 v90, v23, v207
	v_fmac_f32_e32 v90, v24, v208
	v_fmac_f32_e32 v90, v25, v209
	v_fmac_f32_e32 v91, v30, v206
	v_fmac_f32_e32 v91, v31, v207
	v_fmac_f32_e32 v91, v32, v208
	v_fmac_f32_e32 v91, v33, v209
	v_fmac_f32_e32 v88, v34, v206
	v_fmac_f32_e32 v88, v35, v207
	v_fmac_f32_e32 v88, v36, v208
	v_fmac_f32_e32 v88, v37, v209
	ds_read_b128 v[2:5], v12 offset:272
	ds_read_b128 v[6:9], v12 offset:4368
	ds_read_b128 v[22:25], v12 offset:8464
	ds_read_b128 v[30:33], v12 offset:12560
	ds_read_b128 v[34:37], v12 offset:16656
	s_waitcnt lgkmcnt(5)
; #define LAS __attribute__((address_space(3)))
; DI void adaln_layer(const Frame& F, int l, int b_idx, int b_cnt) {
;     ...
; #pragma unroll 1
;         for (int kb = k0; kb < k0 + 128; kb += 16) {
;             float wv[16];
; #pragma unroll
;             for (int i = 0; i < 16; ++i) { wv[i] = __builtin_nontemporal_load(wp_); wp_ += MODW; }
; #pragma unroll
;             for (int i = 0; i < 16; i += 4) {
; #pragma unroll
;                 for (int s = 0; s < NSEQ; ++s) { const f32x4 c4 = *(const LAS f32x4*)(sc + s * DM + kb + i); acc[s] += (c4[0] * wv[i] + c4[1] * wv[i + 1]) + (c4[2] * wv[i + 2] + c4[3] * wv[i + 3]); } }
	v_fmac_f32_e32 v89, v38, v206
	v_fmac_f32_e32 v89, v39, v207
	v_fmac_f32_e32 v89, v40, v208
	v_fmac_f32_e32 v89, v41, v209
	v_fmac_f32_e32 v86, v42, v206
	v_fmac_f32_e32 v86, v43, v207
	v_fmac_f32_e32 v86, v44, v208
	v_fmac_f32_e32 v86, v45, v209
	v_fmac_f32_e32 v87, v46, v206
	v_fmac_f32_e32 v87, v47, v207
	v_fmac_f32_e32 v87, v48, v208
	v_fmac_f32_e32 v87, v49, v209
	v_fmac_f32_e32 v96, v50, v206
	v_fmac_f32_e32 v96, v51, v207
	v_fmac_f32_e32 v96, v52, v208
	v_fmac_f32_e32 v96, v53, v209
	v_fmac_f32_e32 v97, v60, v206
	v_fmac_f32_e32 v97, v61, v207
	v_fmac_f32_e32 v97, v62, v208
	v_fmac_f32_e32 v97, v63, v209
	ds_read_b128 v[38:41], v12 offset:20752
	ds_read_b128 v[42:45], v12 offset:24848
	ds_read_b128 v[46:49], v12 offset:28944
	ds_read_b128 v[50:53], v12 offset:33040
	ds_read_b128 v[60:63], v12 offset:37136
	s_waitcnt lgkmcnt(5)
	v_fmac_f32_e32 v92, v2, v210
	v_fmac_f32_e32 v92, v3, v211
	v_fmac_f32_e32 v92, v4, v212
	v_fmac_f32_e32 v92, v5, v213
	v_fmac_f32_e32 v93, v6, v210
	v_fmac_f32_e32 v93, v7, v211
	v_fmac_f32_e32 v93, v8, v212
	v_fmac_f32_e32 v93, v9, v213
	v_fmac_f32_e32 v90, v22, v210
	v_fmac_f32_e32 v90, v23, v211
	v_fmac_f32_e32 v90, v24, v212
	v_fmac_f32_e32 v90, v25, v213
	v_fmac_f32_e32 v91, v30, v210
	v_fmac_f32_e32 v91, v31, v211
	v_fmac_f32_e32 v91, v32, v212
	v_fmac_f32_e32 v91, v33, v213
	v_fmac_f32_e32 v88, v34, v210
	v_fmac_f32_e32 v88, v35, v211
	v_fmac_f32_e32 v88, v36, v212
	v_fmac_f32_e32 v88, v37, v213
	ds_read_b128 v[2:5], v12 offset:288
	ds_read_b128 v[6:9], v12 offset:4384
	ds_read_b128 v[22:25], v12 offset:8480
	ds_read_b128 v[30:33], v12 offset:12576
	ds_read_b128 v[34:37], v12 offset:16672
	s_waitcnt lgkmcnt(5)
	v_fmac_f32_e32 v89, v38, v210
	v_fmac_f32_e32 v89, v39, v211
	v_fmac_f32_e32 v89, v40, v212
	v_fmac_f32_e32 v89, v41, v213
	v_fmac_f32_e32 v86, v42, v210
	v_fmac_f32_e32 v86, v43, v211
	v_fmac_f32_e32 v86, v44, v212
	v_fmac_f32_e32 v86, v45, v213
	v_fmac_f32_e32 v87, v46, v210
	v_fmac_f32_e32 v87, v47, v211
	v_fmac_f32_e32 v87, v48, v212
	v_fmac_f32_e32 v87, v49, v213
	v_fmac_f32_e32 v96, v50, v210
	v_fmac_f32_e32 v96, v51, v211
	v_fmac_f32_e32 v96, v52, v212
	v_fmac_f32_e32 v96, v53, v213
	v_fmac_f32_e32 v97, v60, v210
	v_fmac_f32_e32 v97, v61, v211
	v_fmac_f32_e32 v97, v62, v212
	v_fmac_f32_e32 v97, v63, v213
	ds_read_b128 v[38:41], v12 offset:20768
	ds_read_b128 v[42:45], v12 offset:24864
	ds_read_b128 v[46:49], v12 offset:28960
	ds_read_b128 v[50:53], v12 offset:33056
	ds_read_b128 v[60:63], v12 offset:37152
	s_waitcnt lgkmcnt(5)
	v_fmac_f32_e32 v92, v2, v214
	v_fmac_f32_e32 v92, v3, v215
	v_fmac_f32_e32 v92, v4, v216
	v_fmac_f32_e32 v92, v5, v217
	v_fmac_f32_e32 v93, v6, v214
	v_fmac_f32_e32 v93, v7, v215
	v_fmac_f32_e32 v93, v8, v216
	v_fmac_f32_e32 v93, v9, v217
	v_fmac_f32_e32 v90, v22, v214
	v_fmac_f32_e32 v90, v23, v215
	v_fmac_f32_e32 v90, v24, v216
	v_fmac_f32_e32 v90, v25, v217
	v_fmac_f32_e32 v91, v30, v214
	v_fmac_f32_e32 v91, v31, v215
	v_fmac_f32_e32 v91, v32, v216
	v_fmac_f32_e32 v91, v33, v217
	v_fmac_f32_e32 v88, v34, v214
	v_fmac_f32_e32 v88, v35, v215
	v_fmac_f32_e32 v88, v36, v216
	v_fmac_f32_e32 v88, v37, v217
	ds_read_b128 v[2:5], v12 offset:304
	ds_read_b128 v[6:9], v12 offset:4400
	ds_read_b128 v[22:25], v12 offset:8496
	ds_read_b128 v[30:33], v12 offset:12592
	ds_read_b128 v[34:37], v12 offset:16688
	s_waitcnt lgkmcnt(5)
	v_fmac_f32_e32 v89, v38, v214
	v_fmac_f32_e32 v89, v39, v215
	v_fmac_f32_e32 v89, v40, v216
	v_fmac_f32_e32 v89, v41, v217
	v_fmac_f32_e32 v86, v42, v214
	v_fmac_f32_e32 v86, v43, v215
	v_fmac_f32_e32 v86, v44, v216
	v_fmac_f32_e32 v86, v45, v217
	v_fmac_f32_e32 v87, v46, v214
	v_fmac_f32_e32 v87, v47, v215
	v_fmac_f32_e32 v87, v48, v216
	v_fmac_f32_e32 v87, v49, v217
	v_fmac_f32_e32 v96, v50, v214
	v_fmac_f32_e32 v96, v51, v215
	v_fmac_f32_e32 v96, v52, v216
	v_fmac_f32_e32 v96, v53, v217
	v_fmac_f32_e32 v97, v60, v214
	v_fmac_f32_e32 v97, v61, v215
	v_fmac_f32_e32 v97, v62, v216
	v_fmac_f32_e32 v97, v63, v217
	ds_read_b128 v[38:41], v12 offset:20784
	ds_read_b128 v[42:45], v12 offset:24880
	ds_read_b128 v[46:49], v12 offset:28976
	ds_read_b128 v[50:53], v12 offset:33072
	ds_read_b128 v[60:63], v12 offset:37168
	s_waitcnt lgkmcnt(5)
	v_fmac_f32_e32 v92, v2, v218
	v_fmac_f32_e32 v92, v3, v221
	v_fmac_f32_e32 v92, v4, v222
	v_fmac_f32_e32 v92, v5, v223
	v_fmac_f32_e32 v93, v6, v218
	v_fmac_f32_e32 v93, v7, v221
	v_fmac_f32_e32 v93, v8, v222
	v_fmac_f32_e32 v93, v9, v223
	v_fmac_f32_e32 v90, v22, v218
	v_fmac_f32_e32 v90, v23, v221
	v_fmac_f32_e32 v90, v24, v222
	v_fmac_f32_e32 v90, v25, v223
	v_fmac_f32_e32 v91, v30, v218
	v_fmac_f32_e32 v91, v31, v221
	v_fmac_f32_e32 v91, v32, v222
	v_fmac_f32_e32 v91, v33, v223
	v_fmac_f32_e32 v88, v34, v218
	v_fmac_f32_e32 v88, v35, v221
	v_fmac_f32_e32 v88, v36, v222
	v_fmac_f32_e32 v88, v37, v223
	s_waitcnt lgkmcnt(0)
; #define LAS __attribute__((address_space(3)))
; DI void adaln_layer(const Frame& F, int l, int b_idx, int b_cnt) {
;     ...
; #pragma unroll 1
;         for (int kb = k0; kb < k0 + 128; kb += 16) {
;             float wv[16];
; #pragma unroll
;             for (int i = 0; i < 16; ++i) { wv[i] = __builtin_nontemporal_load(wp_); wp_ += MODW; }
; #pragma unroll
;             for (int i = 0; i < 16; i += 4) {
; #pragma unroll
;                 for (int s = 0; s < NSEQ; ++s) { const f32x4 c4 = *(const LAS f32x4*)(sc + s * DM + kb + i); acc[s] += (c4[0] * wv[i] + c4[1] * wv[i + 1]) + (c4[2] * wv[i + 2] + c4[3] * wv[i + 3]); } }
	v_fmac_f32_e32 v89, v38, v218
	v_fmac_f32_e32 v89, v39, v221
	v_fmac_f32_e32 v89, v40, v222
	v_fmac_f32_e32 v89, v41, v223
	v_fmac_f32_e32 v86, v42, v218
	v_fmac_f32_e32 v86, v43, v221
	v_fmac_f32_e32 v86, v44, v222
	v_fmac_f32_e32 v86, v45, v223
	v_fmac_f32_e32 v87, v46, v218
	v_fmac_f32_e32 v87, v47, v221
	v_fmac_f32_e32 v87, v48, v222
	v_fmac_f32_e32 v87, v49, v223
	v_fmac_f32_e32 v96, v50, v218
	v_fmac_f32_e32 v96, v51, v221
	v_fmac_f32_e32 v96, v52, v222
	v_fmac_f32_e32 v96, v53, v223
	v_fmac_f32_e32 v97, v60, v218
	v_fmac_f32_e32 v97, v61, v221
	v_fmac_f32_e32 v97, v62, v222
	v_fmac_f32_e32 v97, v63, v223
	global_load_dword v206, v15, s[20:21] nt
	s_add_u32 s20, s20, 0x9000
	s_addc_u32 s21, s21, 0
	global_load_dword v207, v15, s[20:21] nt
	s_add_u32 s20, s20, 0x9000
	s_addc_u32 s21, s21, 0
	global_load_dword v208, v15, s[20:21] nt
	s_add_u32 s20, s20, 0x9000
	s_addc_u32 s21, s21, 0
	global_load_dword v209, v15, s[20:21] nt
	s_add_u32 s20, s20, 0x9000
	s_addc_u32 s21, s21, 0
	global_load_dword v210, v15, s[20:21] nt
	s_add_u32 s20, s20, 0x9000
	s_addc_u32 s21, s21, 0
	global_load_dword v211, v15, s[20:21] nt
	s_add_u32 s20, s20, 0x9000
	s_addc_u32 s21, s21, 0
	global_load_dword v212, v15, s[20:21] nt
	s_add_u32 s20, s20, 0x9000
	s_addc_u32 s21, s21, 0
	global_load_dword v213, v15, s[20:21] nt
	s_add_u32 s20, s20, 0x9000
	s_addc_u32 s21, s21, 0
	global_load_dword v214, v15, s[20:21] nt
	s_add_u32 s20, s20, 0x9000
	s_addc_u32 s21, s21, 0
	global_load_dword v215, v15, s[20:21] nt
	s_add_u32 s20, s20, 0x9000
	s_addc_u32 s21, s21, 0
	global_load_dword v216, v15, s[20:21] nt
	s_add_u32 s20, s20, 0x9000
	s_addc_u32 s21, s21, 0
	global_load_dword v217, v15, s[20:21] nt
	s_add_u32 s20, s20, 0x9000
	s_addc_u32 s21, s21, 0
	global_load_dword v218, v15, s[20:21] nt
	s_add_u32 s20, s20, 0x9000
	s_addc_u32 s21, s21, 0
	global_load_dword v221, v15, s[20:21] nt
	s_add_u32 s20, s20, 0x9000
	s_addc_u32 s21, s21, 0
	global_load_dword v222, v15, s[20:21] nt
	s_add_u32 s20, s20, 0x9000
	s_addc_u32 s21, s21, 0
	global_load_dword v223, v15, s[20:21] nt
	s_add_u32 s20, s20, 0x9000
	s_addc_u32 s21, s21, 0
	s_waitcnt vmcnt(32)
	ds_read_b128 v[2:5], v12 offset:320
	ds_read_b128 v[6:9], v12 offset:4416
	ds_read_b128 v[22:25], v12 offset:8512
	ds_read_b128 v[30:33], v12 offset:12608
	ds_read_b128 v[34:37], v12 offset:16704
	ds_read_b128 v[38:41], v12 offset:20800
	ds_read_b128 v[42:45], v12 offset:24896
	ds_read_b128 v[46:49], v12 offset:28992
	ds_read_b128 v[50:53], v12 offset:33088
	ds_read_b128 v[60:63], v12 offset:37184
	s_waitcnt lgkmcnt(5)
	v_fmac_f32_e32 v92, v2, v224
	v_fmac_f32_e32 v92, v3, v225
	v_fmac_f32_e32 v92, v4, v226
	v_fmac_f32_e32 v92, v5, v227
	v_fmac_f32_e32 v93, v6, v224
	v_fmac_f32_e32 v93, v7, v225
	v_fmac_f32_e32 v93, v8, v226
	v_fmac_f32_e32 v93, v9, v227
	v_fmac_f32_e32 v90, v22, v224
	v_fmac_f32_e32 v90, v23, v225
	v_fmac_f32_e32 v90, v24, v226
	v_fmac_f32_e32 v90, v25, v227
	v_fmac_f32_e32 v91, v30, v224
	v_fmac_f32_e32 v91, v31, v225
	v_fmac_f32_e32 v91, v32, v226
	v_fmac_f32_e32 v91, v33, v227
	v_fmac_f32_e32 v88, v34, v224
	v_fmac_f32_e32 v88, v35, v225
	v_fmac_f32_e32 v88, v36, v226
	v_fmac_f32_e32 v88, v37, v227
	ds_read_b128 v[2:5], v12 offset:336
	ds_read_b128 v[6:9], v12 offset:4432
	ds_read_b128 v[22:25], v12 offset:8528
	ds_read_b128 v[30:33], v12 offset:12624
	ds_read_b128 v[34:37], v12 offset:16720
	s_waitcnt lgkmcnt(5)
	v_fmac_f32_e32 v89, v38, v224
	v_fmac_f32_e32 v89, v39, v225
	v_fmac_f32_e32 v89, v40, v226
	v_fmac_f32_e32 v89, v41, v227
	v_fmac_f32_e32 v86, v42, v224
	v_fmac_f32_e32 v86, v43, v225
	v_fmac_f32_e32 v86, v44, v226
	v_fmac_f32_e32 v86, v45, v227
	v_fmac_f32_e32 v87, v46, v224
	v_fmac_f32_e32 v87, v47, v225
	v_fmac_f32_e32 v87, v48, v226
	v_fmac_f32_e32 v87, v49, v227
	v_fmac_f32_e32 v96, v50, v224
	v_fmac_f32_e32 v96, v51, v225
	v_fmac_f32_e32 v96, v52, v226
	v_fmac_f32_e32 v96, v53, v227
	v_fmac_f32_e32 v97, v60, v224
	v_fmac_f32_e32 v97, v61, v225
	v_fmac_f32_e32 v97, v62, v226
	v_fmac_f32_e32 v97, v63, v227
	ds_read_b128 v[38:41], v12 offset:20816
	ds_read_b128 v[42:45], v12 offset:24912
	ds_read_b128 v[46:49], v12 offset:29008
	ds_read_b128 v[50:53], v12 offset:33104
	ds_read_b128 v[60:63], v12 offset:37200
	s_waitcnt lgkmcnt(5)
	v_fmac_f32_e32 v92, v2, v228
	v_fmac_f32_e32 v92, v3, v229
	v_fmac_f32_e32 v92, v4, v230
	v_fmac_f32_e32 v92, v5, v231
	v_fmac_f32_e32 v93, v6, v228
	v_fmac_f32_e32 v93, v7, v229
	v_fmac_f32_e32 v93, v8, v230
	v_fmac_f32_e32 v93, v9, v231
	v_fmac_f32_e32 v90, v22, v228
	v_fmac_f32_e32 v90, v23, v229
	v_fmac_f32_e32 v90, v24, v230
	v_fmac_f32_e32 v90, v25, v231
	v_fmac_f32_e32 v91, v30, v228
	v_fmac_f32_e32 v91, v31, v229
	v_fmac_f32_e32 v91, v32, v230
	v_fmac_f32_e32 v91, v33, v231
	v_fmac_f32_e32 v88, v34, v228
	v_fmac_f32_e32 v88, v35, v229
	v_fmac_f32_e32 v88, v36, v230
	v_fmac_f32_e32 v88, v37, v231
	ds_read_b128 v[2:5], v12 offset:352
	ds_read_b128 v[6:9], v12 offset:4448
	ds_read_b128 v[22:25], v12 offset:8544
	ds_read_b128 v[30:33], v12 offset:12640
	ds_read_b128 v[34:37], v12 offset:16736
	s_waitcnt lgkmcnt(5)
	v_fmac_f32_e32 v89, v38, v228
	v_fmac_f32_e32 v89, v39, v229
	v_fmac_f32_e32 v89, v40, v230
	v_fmac_f32_e32 v89, v41, v231
	v_fmac_f32_e32 v86, v42, v228
	v_fmac_f32_e32 v86, v43, v229
	v_fmac_f32_e32 v86, v44, v230
	v_fmac_f32_e32 v86, v45, v231
	v_fmac_f32_e32 v87, v46, v228
	v_fmac_f32_e32 v87, v47, v229
	v_fmac_f32_e32 v87, v48, v230
	v_fmac_f32_e32 v87, v49, v231
	v_fmac_f32_e32 v96, v50, v228
	v_fmac_f32_e32 v96, v51, v229
	v_fmac_f32_e32 v96, v52, v230
	v_fmac_f32_e32 v96, v53, v231
	v_fmac_f32_e32 v97, v60, v228
	v_fmac_f32_e32 v97, v61, v229
	v_fmac_f32_e32 v97, v62, v230
	v_fmac_f32_e32 v97, v63, v231
	ds_read_b128 v[38:41], v12 offset:20832
	ds_read_b128 v[42:45], v12 offset:24928
	ds_read_b128 v[46:49], v12 offset:29024
	ds_read_b128 v[50:53], v12 offset:33120
	ds_read_b128 v[60:63], v12 offset:37216
	s_waitcnt lgkmcnt(5)
; #define LAS __attribute__((address_space(3)))
; DI void adaln_layer(const Frame& F, int l, int b_idx, int b_cnt) {
;     ...
; #pragma unroll 1
;         for (int kb = k0; kb < k0 + 128; kb += 16) {
;             float wv[16];
; #pragma unroll
;             for (int i = 0; i < 16; ++i) { wv[i] = __builtin_nontemporal_load(wp_); wp_ += MODW; }
; #pragma unroll
;             for (int i = 0; i < 16; i += 4) {
; #pragma unroll
;                 for (int s = 0; s < NSEQ; ++s) { const f32x4 c4 = *(const LAS f32x4*)(sc + s * DM + kb + i); acc[s] += (c4[0] * wv[i] + c4[1] * wv[i + 1]) + (c4[2] * wv[i + 2] + c4[3] * wv[i + 3]); } }
	v_fmac_f32_e32 v92, v2, v232
	v_fmac_f32_e32 v92, v3, v233
	v_fmac_f32_e32 v92, v4, v234
	v_fmac_f32_e32 v92, v5, v235
	v_fmac_f32_e32 v93, v6, v232
	v_fmac_f32_e32 v93, v7, v233
	v_fmac_f32_e32 v93, v8, v234
	v_fmac_f32_e32 v93, v9, v235
	v_fmac_f32_e32 v90, v22, v232
	v_fmac_f32_e32 v90, v23, v233
	v_fmac_f32_e32 v90, v24, v234
	v_fmac_f32_e32 v90, v25, v235
	v_fmac_f32_e32 v91, v30, v232
	v_fmac_f32_e32 v91, v31, v233
	v_fmac_f32_e32 v91, v32, v234
	v_fmac_f32_e32 v91, v33, v235
	v_fmac_f32_e32 v88, v34, v232
	v_fmac_f32_e32 v88, v35, v233
	v_fmac_f32_e32 v88, v36, v234
	v_fmac_f32_e32 v88, v37, v235
	ds_read_b128 v[2:5], v12 offset:368
	ds_read_b128 v[6:9], v12 offset:4464
	ds_read_b128 v[22:25], v12 offset:8560
	ds_read_b128 v[30:33], v12 offset:12656
	ds_read_b128 v[34:37], v12 offset:16752
	s_waitcnt lgkmcnt(5)
	v_fmac_f32_e32 v89, v38, v232
	v_fmac_f32_e32 v89, v39, v233
	v_fmac_f32_e32 v89, v40, v234
	v_fmac_f32_e32 v89, v41, v235
	v_fmac_f32_e32 v86, v42, v232
	v_fmac_f32_e32 v86, v43, v233
	v_fmac_f32_e32 v86, v44, v234
	v_fmac_f32_e32 v86, v45, v235
	v_fmac_f32_e32 v87, v46, v232
	v_fmac_f32_e32 v87, v47, v233
	v_fmac_f32_e32 v87, v48, v234
	v_fmac_f32_e32 v87, v49, v235
	v_fmac_f32_e32 v96, v50, v232
	v_fmac_f32_e32 v96, v51, v233
	v_fmac_f32_e32 v96, v52, v234
	v_fmac_f32_e32 v96, v53, v235
	v_fmac_f32_e32 v97, v60, v232
	v_fmac_f32_e32 v97, v61, v233
	v_fmac_f32_e32 v97, v62, v234
	v_fmac_f32_e32 v97, v63, v235
	ds_read_b128 v[38:41], v12 offset:20848
	ds_read_b128 v[42:45], v12 offset:24944
	ds_read_b128 v[46:49], v12 offset:29040
	ds_read_b128 v[50:53], v12 offset:33136
	ds_read_b128 v[60:63], v12 offset:37232
	s_waitcnt lgkmcnt(5)
	v_fmac_f32_e32 v92, v2, v236
	v_fmac_f32_e32 v92, v3, v237
	v_fmac_f32_e32 v92, v4, v238
	v_fmac_f32_e32 v92, v5, v239
	v_fmac_f32_e32 v93, v6, v236
	v_fmac_f32_e32 v93, v7, v237
	v_fmac_f32_e32 v93, v8, v238
	v_fmac_f32_e32 v93, v9, v239
	v_fmac_f32_e32 v90, v22, v236
	v_fmac_f32_e32 v90, v23, v237
	v_fmac_f32_e32 v90, v24, v238
	v_fmac_f32_e32 v90, v25, v239
	v_fmac_f32_e32 v91, v30, v236
	v_fmac_f32_e32 v91, v31, v237
	v_fmac_f32_e32 v91, v32, v238
	v_fmac_f32_e32 v91, v33, v239
	v_fmac_f32_e32 v88, v34, v236
	v_fmac_f32_e32 v88, v35, v237
	v_fmac_f32_e32 v88, v36, v238
	v_fmac_f32_e32 v88, v37, v239
	s_waitcnt lgkmcnt(0)
	v_fmac_f32_e32 v89, v38, v236
	v_fmac_f32_e32 v89, v39, v237
	v_fmac_f32_e32 v89, v40, v238
	v_fmac_f32_e32 v89, v41, v239
	v_fmac_f32_e32 v86, v42, v236
	v_fmac_f32_e32 v86, v43, v237
	v_fmac_f32_e32 v86, v44, v238
	v_fmac_f32_e32 v86, v45, v239
	v_fmac_f32_e32 v87, v46, v236
	v_fmac_f32_e32 v87, v47, v237
	v_fmac_f32_e32 v87, v48, v238
	v_fmac_f32_e32 v87, v49, v239
	v_fmac_f32_e32 v96, v50, v236
	v_fmac_f32_e32 v96, v51, v237
	v_fmac_f32_e32 v96, v52, v238
	v_fmac_f32_e32 v96, v53, v239
	v_fmac_f32_e32 v97, v60, v236
	v_fmac_f32_e32 v97, v61, v237
	v_fmac_f32_e32 v97, v62, v238
	v_fmac_f32_e32 v97, v63, v239
	s_waitcnt vmcnt(16)
	ds_read_b128 v[2:5], v12 offset:384
	ds_read_b128 v[6:9], v12 offset:4480
	ds_read_b128 v[22:25], v12 offset:8576
	ds_read_b128 v[30:33], v12 offset:12672
	ds_read_b128 v[34:37], v12 offset:16768
	ds_read_b128 v[38:41], v12 offset:20864
	ds_read_b128 v[42:45], v12 offset:24960
	ds_read_b128 v[46:49], v12 offset:29056
	ds_read_b128 v[50:53], v12 offset:33152
	ds_read_b128 v[60:63], v12 offset:37248
	s_waitcnt lgkmcnt(5)
	v_fmac_f32_e32 v92, v2, v184
	v_fmac_f32_e32 v92, v3, v185
	v_fmac_f32_e32 v92, v4, v186
	v_fmac_f32_e32 v92, v5, v187
	v_fmac_f32_e32 v93, v6, v184
	v_fmac_f32_e32 v93, v7, v185
	v_fmac_f32_e32 v93, v8, v186
	v_fmac_f32_e32 v93, v9, v187
	v_fmac_f32_e32 v90, v22, v184
	v_fmac_f32_e32 v90, v23, v185
	v_fmac_f32_e32 v90, v24, v186
	v_fmac_f32_e32 v90, v25, v187
	v_fmac_f32_e32 v91, v30, v184
	v_fmac_f32_e32 v91, v31, v185
	v_fmac_f32_e32 v91, v32, v186
	v_fmac_f32_e32 v91, v33, v187
	v_fmac_f32_e32 v88, v34, v184
	v_fmac_f32_e32 v88, v35, v185
	v_fmac_f32_e32 v88, v36, v186
	v_fmac_f32_e32 v88, v37, v187
	ds_read_b128 v[2:5], v12 offset:400
	ds_read_b128 v[6:9], v12 offset:4496
	ds_read_b128 v[22:25], v12 offset:8592
	ds_read_b128 v[30:33], v12 offset:12688
	ds_read_b128 v[34:37], v12 offset:16784
	s_waitcnt lgkmcnt(5)
	v_fmac_f32_e32 v89, v38, v184
	v_fmac_f32_e32 v89, v39, v185
	v_fmac_f32_e32 v89, v40, v186
	v_fmac_f32_e32 v89, v41, v187
	v_fmac_f32_e32 v86, v42, v184
	v_fmac_f32_e32 v86, v43, v185
	v_fmac_f32_e32 v86, v44, v186
	v_fmac_f32_e32 v86, v45, v187
	v_fmac_f32_e32 v87, v46, v184
	v_fmac_f32_e32 v87, v47, v185
	v_fmac_f32_e32 v87, v48, v186
	v_fmac_f32_e32 v87, v49, v187
	v_fmac_f32_e32 v96, v50, v184
	v_fmac_f32_e32 v96, v51, v185
	v_fmac_f32_e32 v96, v52, v186
	v_fmac_f32_e32 v96, v53, v187
	v_fmac_f32_e32 v97, v60, v184
	v_fmac_f32_e32 v97, v61, v185
	v_fmac_f32_e32 v97, v62, v186
	v_fmac_f32_e32 v97, v63, v187
	ds_read_b128 v[38:41], v12 offset:20880
	ds_read_b128 v[42:45], v12 offset:24976
	ds_read_b128 v[46:49], v12 offset:29072
	ds_read_b128 v[50:53], v12 offset:33168
	ds_read_b128 v[60:63], v12 offset:37264
	s_waitcnt lgkmcnt(5)
	v_fmac_f32_e32 v92, v2, v188
	v_fmac_f32_e32 v92, v3, v189
	v_fmac_f32_e32 v92, v4, v190
	v_fmac_f32_e32 v92, v5, v191
	v_fmac_f32_e32 v93, v6, v188
	v_fmac_f32_e32 v93, v7, v189
	v_fmac_f32_e32 v93, v8, v190
	v_fmac_f32_e32 v93, v9, v191
	v_fmac_f32_e32 v90, v22, v188
	v_fmac_f32_e32 v90, v23, v189
	v_fmac_f32_e32 v90, v24, v190
	v_fmac_f32_e32 v90, v25, v191
	v_fmac_f32_e32 v91, v30, v188
	v_fmac_f32_e32 v91, v31, v189
	v_fmac_f32_e32 v91, v32, v190
	v_fmac_f32_e32 v91, v33, v191
	v_fmac_f32_e32 v88, v34, v188
	v_fmac_f32_e32 v88, v35, v189
	v_fmac_f32_e32 v88, v36, v190
	v_fmac_f32_e32 v88, v37, v191
	ds_read_b128 v[2:5], v12 offset:416
	ds_read_b128 v[6:9], v12 offset:4512
	ds_read_b128 v[22:25], v12 offset:8608
	ds_read_b128 v[30:33], v12 offset:12704
	ds_read_b128 v[34:37], v12 offset:16800
	s_waitcnt lgkmcnt(5)
; #define LAS __attribute__((address_space(3)))
; DI void adaln_layer(const Frame& F, int l, int b_idx, int b_cnt) {
;     ...
; #pragma unroll 1
;         for (int kb = k0; kb < k0 + 128; kb += 16) {
;             float wv[16];
; #pragma unroll
;             for (int i = 0; i < 16; ++i) { wv[i] = __builtin_nontemporal_load(wp_); wp_ += MODW; }
; #pragma unroll
;             for (int i = 0; i < 16; i += 4) {
; #pragma unroll
;                 for (int s = 0; s < NSEQ; ++s) { const f32x4 c4 = *(const LAS f32x4*)(sc + s * DM + kb + i); acc[s] += (c4[0] * wv[i] + c4[1] * wv[i + 1]) + (c4[2] * wv[i + 2] + c4[3] * wv[i + 3]); } }
	v_fmac_f32_e32 v89, v38, v188
	v_fmac_f32_e32 v89, v39, v189
	v_fmac_f32_e32 v89, v40, v190
	v_fmac_f32_e32 v89, v41, v191
	v_fmac_f32_e32 v86, v42, v188
	v_fmac_f32_e32 v86, v43, v189
	v_fmac_f32_e32 v86, v44, v190
	v_fmac_f32_e32 v86, v45, v191
	v_fmac_f32_e32 v87, v46, v188
	v_fmac_f32_e32 v87, v47, v189
	v_fmac_f32_e32 v87, v48, v190
	v_fmac_f32_e32 v87, v49, v191
	v_fmac_f32_e32 v96, v50, v188
	v_fmac_f32_e32 v96, v51, v189
	v_fmac_f32_e32 v96, v52, v190
	v_fmac_f32_e32 v96, v53, v191
	v_fmac_f32_e32 v97, v60, v188
	v_fmac_f32_e32 v97, v61, v189
	v_fmac_f32_e32 v97, v62, v190
	v_fmac_f32_e32 v97, v63, v191
	ds_read_b128 v[38:41], v12 offset:20896
	ds_read_b128 v[42:45], v12 offset:24992
	ds_read_b128 v[46:49], v12 offset:29088
	ds_read_b128 v[50:53], v12 offset:33184
	ds_read_b128 v[60:63], v12 offset:37280
	s_waitcnt lgkmcnt(5)
	v_fmac_f32_e32 v92, v2, v192
	v_fmac_f32_e32 v92, v3, v193
	v_fmac_f32_e32 v92, v4, v194
	v_fmac_f32_e32 v92, v5, v195
	v_fmac_f32_e32 v93, v6, v192
	v_fmac_f32_e32 v93, v7, v193
	v_fmac_f32_e32 v93, v8, v194
	v_fmac_f32_e32 v93, v9, v195
	v_fmac_f32_e32 v90, v22, v192
	v_fmac_f32_e32 v90, v23, v193
	v_fmac_f32_e32 v90, v24, v194
	v_fmac_f32_e32 v90, v25, v195
	v_fmac_f32_e32 v91, v30, v192
	v_fmac_f32_e32 v91, v31, v193
	v_fmac_f32_e32 v91, v32, v194
	v_fmac_f32_e32 v91, v33, v195
	v_fmac_f32_e32 v88, v34, v192
	v_fmac_f32_e32 v88, v35, v193
	v_fmac_f32_e32 v88, v36, v194
	v_fmac_f32_e32 v88, v37, v195
	ds_read_b128 v[2:5], v12 offset:432
	ds_read_b128 v[6:9], v12 offset:4528
	ds_read_b128 v[22:25], v12 offset:8624
	ds_read_b128 v[30:33], v12 offset:12720
	ds_read_b128 v[34:37], v12 offset:16816
	s_waitcnt lgkmcnt(5)
	v_fmac_f32_e32 v89, v38, v192
	v_fmac_f32_e32 v89, v39, v193
	v_fmac_f32_e32 v89, v40, v194
	v_fmac_f32_e32 v89, v41, v195
	v_fmac_f32_e32 v86, v42, v192
	v_fmac_f32_e32 v86, v43, v193
	v_fmac_f32_e32 v86, v44, v194
	v_fmac_f32_e32 v86, v45, v195
	v_fmac_f32_e32 v87, v46, v192
	v_fmac_f32_e32 v87, v47, v193
	v_fmac_f32_e32 v87, v48, v194
	v_fmac_f32_e32 v87, v49, v195
	v_fmac_f32_e32 v96, v50, v192
	v_fmac_f32_e32 v96, v51, v193
	v_fmac_f32_e32 v96, v52, v194
	v_fmac_f32_e32 v96, v53, v195
	v_fmac_f32_e32 v97, v60, v192
	v_fmac_f32_e32 v97, v61, v193
	v_fmac_f32_e32 v97, v62, v194
	v_fmac_f32_e32 v97, v63, v195
	ds_read_b128 v[38:41], v12 offset:20912
	ds_read_b128 v[42:45], v12 offset:25008
	ds_read_b128 v[46:49], v12 offset:29104
	ds_read_b128 v[50:53], v12 offset:33200
	ds_read_b128 v[60:63], v12 offset:37296
	s_waitcnt lgkmcnt(5)
	v_fmac_f32_e32 v92, v2, v196
	v_fmac_f32_e32 v92, v3, v197
	v_fmac_f32_e32 v92, v4, v198
	v_fmac_f32_e32 v92, v5, v199
	v_fmac_f32_e32 v93, v6, v196
	v_fmac_f32_e32 v93, v7, v197
	v_fmac_f32_e32 v93, v8, v198
	v_fmac_f32_e32 v93, v9, v199
	v_fmac_f32_e32 v90, v22, v196
	v_fmac_f32_e32 v90, v23, v197
	v_fmac_f32_e32 v90, v24, v198
	v_fmac_f32_e32 v90, v25, v199
	v_fmac_f32_e32 v91, v30, v196
	v_fmac_f32_e32 v91, v31, v197
	v_fmac_f32_e32 v91, v32, v198
	v_fmac_f32_e32 v91, v33, v199
	v_fmac_f32_e32 v88, v34, v196
	v_fmac_f32_e32 v88, v35, v197
	v_fmac_f32_e32 v88, v36, v198
	v_fmac_f32_e32 v88, v37, v199
	s_waitcnt lgkmcnt(0)
	v_fmac_f32_e32 v89, v38, v196
	v_fmac_f32_e32 v89, v39, v197
	v_fmac_f32_e32 v89, v40, v198
	v_fmac_f32_e32 v89, v41, v199
	v_fmac_f32_e32 v86, v42, v196
	v_fmac_f32_e32 v86, v43, v197
	v_fmac_f32_e32 v86, v44, v198
	v_fmac_f32_e32 v86, v45, v199
	v_fmac_f32_e32 v87, v46, v196
	v_fmac_f32_e32 v87, v47, v197
	v_fmac_f32_e32 v87, v48, v198
	v_fmac_f32_e32 v87, v49, v199
	v_fmac_f32_e32 v96, v50, v196
	v_fmac_f32_e32 v96, v51, v197
	v_fmac_f32_e32 v96, v52, v198
	v_fmac_f32_e32 v96, v53, v199
	v_fmac_f32_e32 v97, v60, v196
	v_fmac_f32_e32 v97, v61, v197
	v_fmac_f32_e32 v97, v62, v198
	v_fmac_f32_e32 v97, v63, v199
	s_waitcnt vmcnt(0)
	ds_read_b128 v[2:5], v12 offset:448
	ds_read_b128 v[6:9], v12 offset:4544
	ds_read_b128 v[22:25], v12 offset:8640
	ds_read_b128 v[30:33], v12 offset:12736
	ds_read_b128 v[34:37], v12 offset:16832
	ds_read_b128 v[38:41], v12 offset:20928
	ds_read_b128 v[42:45], v12 offset:25024
	ds_read_b128 v[46:49], v12 offset:29120
	ds_read_b128 v[50:53], v12 offset:33216
	ds_read_b128 v[60:63], v12 offset:37312
	s_waitcnt lgkmcnt(5)
	v_fmac_f32_e32 v92, v2, v206
	v_fmac_f32_e32 v92, v3, v207
	v_fmac_f32_e32 v92, v4, v208
	v_fmac_f32_e32 v92, v5, v209
	v_fmac_f32_e32 v93, v6, v206
	v_fmac_f32_e32 v93, v7, v207
	v_fmac_f32_e32 v93, v8, v208
	v_fmac_f32_e32 v93, v9, v209
	v_fmac_f32_e32 v90, v22, v206
	v_fmac_f32_e32 v90, v23, v207
	v_fmac_f32_e32 v90, v24, v208
	v_fmac_f32_e32 v90, v25, v209
	v_fmac_f32_e32 v91, v30, v206
	v_fmac_f32_e32 v91, v31, v207
	v_fmac_f32_e32 v91, v32, v208
	v_fmac_f32_e32 v91, v33, v209
	v_fmac_f32_e32 v88, v34, v206
	v_fmac_f32_e32 v88, v35, v207
	v_fmac_f32_e32 v88, v36, v208
	v_fmac_f32_e32 v88, v37, v209
	ds_read_b128 v[2:5], v12 offset:464
	ds_read_b128 v[6:9], v12 offset:4560
	ds_read_b128 v[22:25], v12 offset:8656
	ds_read_b128 v[30:33], v12 offset:12752
	ds_read_b128 v[34:37], v12 offset:16848
	s_waitcnt lgkmcnt(5)
	v_fmac_f32_e32 v89, v38, v206
	v_fmac_f32_e32 v89, v39, v207
	v_fmac_f32_e32 v89, v40, v208
	v_fmac_f32_e32 v89, v41, v209
	v_fmac_f32_e32 v86, v42, v206
	v_fmac_f32_e32 v86, v43, v207
	v_fmac_f32_e32 v86, v44, v208
	v_fmac_f32_e32 v86, v45, v209
	v_fmac_f32_e32 v87, v46, v206
	v_fmac_f32_e32 v87, v47, v207
	v_fmac_f32_e32 v87, v48, v208
	v_fmac_f32_e32 v87, v49, v209
	v_fmac_f32_e32 v96, v50, v206
	v_fmac_f32_e32 v96, v51, v207
	v_fmac_f32_e32 v96, v52, v208
	v_fmac_f32_e32 v96, v53, v209
	v_fmac_f32_e32 v97, v60, v206
	v_fmac_f32_e32 v97, v61, v207
	v_fmac_f32_e32 v97, v62, v208
	v_fmac_f32_e32 v97, v63, v209
	ds_read_b128 v[38:41], v12 offset:20944
	ds_read_b128 v[42:45], v12 offset:25040
	ds_read_b128 v[46:49], v12 offset:29136
	ds_read_b128 v[50:53], v12 offset:33232
	ds_read_b128 v[60:63], v12 offset:37328
	s_waitcnt lgkmcnt(5)
; #define LAS __attribute__((address_space(3)))
; DI void adaln_layer(const Frame& F, int l, int b_idx, int b_cnt) {
;     ...
;             for (int i = 0; i < 16; i += 4) {
; #pragma unroll
;                 for (int s = 0; s < NSEQ; ++s) { const f32x4 c4 = *(const LAS f32x4*)(sc + s * DM + kb + i); acc[s] += (c4[0] * wv[i] + c4[1] * wv[i + 1]) + (c4[2] * wv[i + 2] + c4[3] * wv[i + 3]); } }
;         }
; #pragma unroll
;         for (int s = 0; s < NSEQ; ++s) part[(F.wave * NSEQ + s) * 64 + F.lane] = acc[s];
;         __syncthreads();
;         for (int o = F.tid; o < NSEQ * 64; o += 512) { const int s = o >> 6, ln = o & 63; float sum = 0.f;
	v_fmac_f32_e32 v92, v2, v210
	v_fmac_f32_e32 v92, v3, v211
	v_fmac_f32_e32 v92, v4, v212
	v_fmac_f32_e32 v92, v5, v213
	v_fmac_f32_e32 v93, v6, v210
	v_fmac_f32_e32 v93, v7, v211
	v_fmac_f32_e32 v93, v8, v212
	v_fmac_f32_e32 v93, v9, v213
	v_fmac_f32_e32 v90, v22, v210
	v_fmac_f32_e32 v90, v23, v211
	v_fmac_f32_e32 v90, v24, v212
	v_fmac_f32_e32 v90, v25, v213
	v_fmac_f32_e32 v91, v30, v210
	v_fmac_f32_e32 v91, v31, v211
	v_fmac_f32_e32 v91, v32, v212
	v_fmac_f32_e32 v91, v33, v213
	v_fmac_f32_e32 v88, v34, v210
	v_fmac_f32_e32 v88, v35, v211
	v_fmac_f32_e32 v88, v36, v212
	v_fmac_f32_e32 v88, v37, v213
	ds_read_b128 v[2:5], v12 offset:480
	ds_read_b128 v[6:9], v12 offset:4576
	ds_read_b128 v[22:25], v12 offset:8672
	ds_read_b128 v[30:33], v12 offset:12768
	ds_read_b128 v[34:37], v12 offset:16864
	s_waitcnt lgkmcnt(5)
	v_fmac_f32_e32 v89, v38, v210
	v_fmac_f32_e32 v89, v39, v211
	v_fmac_f32_e32 v89, v40, v212
	v_fmac_f32_e32 v89, v41, v213
	v_fmac_f32_e32 v86, v42, v210
	v_fmac_f32_e32 v86, v43, v211
	v_fmac_f32_e32 v86, v44, v212
	v_fmac_f32_e32 v86, v45, v213
	v_fmac_f32_e32 v87, v46, v210
	v_fmac_f32_e32 v87, v47, v211
	v_fmac_f32_e32 v87, v48, v212
	v_fmac_f32_e32 v87, v49, v213
	v_fmac_f32_e32 v96, v50, v210
	v_fmac_f32_e32 v96, v51, v211
	v_fmac_f32_e32 v96, v52, v212
	v_fmac_f32_e32 v96, v53, v213
	v_fmac_f32_e32 v97, v60, v210
	v_fmac_f32_e32 v97, v61, v211
	v_fmac_f32_e32 v97, v62, v212
	v_fmac_f32_e32 v97, v63, v213
	ds_read_b128 v[38:41], v12 offset:20960
	ds_read_b128 v[42:45], v12 offset:25056
	ds_read_b128 v[46:49], v12 offset:29152
	ds_read_b128 v[50:53], v12 offset:33248
	ds_read_b128 v[60:63], v12 offset:37344
	s_waitcnt lgkmcnt(5)
	v_fmac_f32_e32 v92, v2, v214
	v_fmac_f32_e32 v92, v3, v215
	v_fmac_f32_e32 v92, v4, v216
	v_fmac_f32_e32 v92, v5, v217
	v_fmac_f32_e32 v93, v6, v214
	v_fmac_f32_e32 v93, v7, v215
	v_fmac_f32_e32 v93, v8, v216
	v_fmac_f32_e32 v93, v9, v217
	v_fmac_f32_e32 v90, v22, v214
	v_fmac_f32_e32 v90, v23, v215
	v_fmac_f32_e32 v90, v24, v216
	v_fmac_f32_e32 v90, v25, v217
	v_fmac_f32_e32 v91, v30, v214
	v_fmac_f32_e32 v91, v31, v215
	v_fmac_f32_e32 v91, v32, v216
	v_fmac_f32_e32 v91, v33, v217
	v_fmac_f32_e32 v88, v34, v214
	v_fmac_f32_e32 v88, v35, v215
	v_fmac_f32_e32 v88, v36, v216
	v_fmac_f32_e32 v88, v37, v217
	ds_read_b128 v[2:5], v12 offset:496
	ds_read_b128 v[6:9], v12 offset:4592
	ds_read_b128 v[22:25], v12 offset:8688
	ds_read_b128 v[30:33], v12 offset:12784
	ds_read_b128 v[34:37], v12 offset:16880
	s_waitcnt lgkmcnt(5)
	v_fmac_f32_e32 v89, v38, v214
	v_fmac_f32_e32 v89, v39, v215
	v_fmac_f32_e32 v89, v40, v216
	v_fmac_f32_e32 v89, v41, v217
	v_fmac_f32_e32 v86, v42, v214
	v_fmac_f32_e32 v86, v43, v215
	v_fmac_f32_e32 v86, v44, v216
	v_fmac_f32_e32 v86, v45, v217
	v_fmac_f32_e32 v87, v46, v214
	v_fmac_f32_e32 v87, v47, v215
	v_fmac_f32_e32 v87, v48, v216
	v_fmac_f32_e32 v87, v49, v217
	v_fmac_f32_e32 v96, v50, v214
	v_fmac_f32_e32 v96, v51, v215
	v_fmac_f32_e32 v96, v52, v216
	v_fmac_f32_e32 v96, v53, v217
	v_fmac_f32_e32 v97, v60, v214
	v_fmac_f32_e32 v97, v61, v215
	v_fmac_f32_e32 v97, v62, v216
	v_fmac_f32_e32 v97, v63, v217
	ds_read_b128 v[38:41], v12 offset:20976
	ds_read_b128 v[42:45], v12 offset:25072
	ds_read_b128 v[46:49], v12 offset:29168
	ds_read_b128 v[50:53], v12 offset:33264
	ds_read_b128 v[60:63], v12 offset:37360
	s_waitcnt lgkmcnt(5)
	v_fmac_f32_e32 v92, v2, v218
	v_fmac_f32_e32 v92, v3, v221
	v_fmac_f32_e32 v92, v4, v222
	v_fmac_f32_e32 v92, v5, v223
	v_fmac_f32_e32 v93, v6, v218
	v_fmac_f32_e32 v93, v7, v221
	v_fmac_f32_e32 v93, v8, v222
	v_fmac_f32_e32 v93, v9, v223
	v_fmac_f32_e32 v90, v22, v218
	v_fmac_f32_e32 v90, v23, v221
	v_fmac_f32_e32 v90, v24, v222
	v_fmac_f32_e32 v90, v25, v223
	v_fmac_f32_e32 v91, v30, v218
	v_fmac_f32_e32 v91, v31, v221
	v_fmac_f32_e32 v91, v32, v222
	v_fmac_f32_e32 v91, v33, v223
	v_fmac_f32_e32 v88, v34, v218
	v_fmac_f32_e32 v88, v35, v221
	v_fmac_f32_e32 v88, v36, v222
	v_fmac_f32_e32 v88, v37, v223
	s_waitcnt lgkmcnt(0)
	v_fmac_f32_e32 v89, v38, v218
	v_fmac_f32_e32 v89, v39, v221
	v_fmac_f32_e32 v89, v40, v222
	v_fmac_f32_e32 v89, v41, v223
	v_fmac_f32_e32 v86, v42, v218
	v_fmac_f32_e32 v86, v43, v221
	v_fmac_f32_e32 v86, v44, v222
	v_fmac_f32_e32 v86, v45, v223
	v_fmac_f32_e32 v87, v46, v218
	v_fmac_f32_e32 v87, v47, v221
	v_fmac_f32_e32 v87, v48, v222
	v_fmac_f32_e32 v87, v49, v223
	v_fmac_f32_e32 v96, v50, v218
	v_fmac_f32_e32 v96, v51, v221
	v_fmac_f32_e32 v96, v52, v222
	v_fmac_f32_e32 v96, v53, v223
	v_fmac_f32_e32 v97, v60, v218
	v_fmac_f32_e32 v97, v61, v221
	v_fmac_f32_e32 v97, v62, v222
	v_fmac_f32_e32 v97, v63, v223
	v_add_u32_e32 v2, s15, v1
	ds_write2st64_b32 v2, v92, v93 offset0:160 offset1:161
	ds_write2st64_b32 v2, v90, v91 offset0:162 offset1:163
	ds_write2st64_b32 v2, v88, v89 offset0:164 offset1:165
	ds_write2st64_b32 v2, v86, v87 offset0:166 offset1:167
	ds_write2st64_b32 v2, v96, v97 offset0:168 offset1:169
	s_waitcnt lgkmcnt(0)
	s_barrier
	s_and_saveexec_b64 s[10:11], s[4:5]
	s_cbranch_execz .LBB0_11
	v_lshl_add_u64 v[2:3], v[80:81], 0, s[8:9]
	v_lshl_add_u64 v[4:5], v[82:83], 0, s[8:9]
	s_mov_b64 s[8:9], 0
	v_mov_b32_e32 v6, v74

; DI void adaln_layer(const Frame& F, int l, int b_idx, int b_cnt) {
;     ...
;     const float* cp = F.in[2]; const float* cs = F.in[3]; const float* adab = F.in[10];
;     for (int i = F.tid; i < NSEQ * DM; i += 512) { const int s = i >> 10, k = i & 1023; const float c = s < 2 ? cp[s * DM + k] : cs[(s - 2) * DM + k]; sc[i] = c / (1.f + __expf(-c)); }
.LBB0_142:
	s_cmp_eq_u32 s41, 3
	s_cselect_b64 s[18:19], -1, 0
	s_cmp_lg_u32 s41, 3
	s_cselect_b64 s[0:1], -1, 0
	v_writelane_b32 v255, s0, 30
	s_nop 1
	v_writelane_b32 v255, s1, 31
	v_readlane_b32 s0, v254, 23
	v_readlane_b32 s1, v254, 24
	v_writelane_b32 v255, s18, 32
	s_or_b64 s[0:1], s[18:19], s[0:1]
	s_nop 0
	v_writelane_b32 v255, s19, 33
	v_writelane_b32 v255, s0, 34
	s_and_b64 vcc, exec, s[0:1]
	s_nop 0
	v_writelane_b32 v255, s1, 35
	s_cbranch_vccnz .LBB0_191
	v_readlane_b32 s0, v254, 49
	s_movk_i32 s2, 0x2800
	v_cmp_gt_i32_e32 vcc, s2, v130
	v_mov_b32_e32 v1, s0
	ds_read_b64 v[2:3], v1
	v_readlane_b32 s0, v254, 50
	s_waitcnt lgkmcnt(0)
	v_readfirstlane_b32 s23, v3
	v_mov_b32_e32 v1, s0
	v_readfirstlane_b32 s22, v2
	ds_read_b64 v[2:3], v1
	v_readlane_b32 s0, v254, 51
	s_waitcnt lgkmcnt(0)
	v_readfirstlane_b32 s19, v3
	v_mov_b32_e32 v1, s0
	v_readfirstlane_b32 s18, v2
	ds_read_b64 v[2:3], v1
	s_waitcnt lgkmcnt(0)
	v_readfirstlane_b32 s0, v3
	v_readfirstlane_b32 s1, v2
	s_and_saveexec_b64 s[26:27], vcc
	s_cbranch_execz .LBB0_148
	s_nop 4
	v_lshlrev_b32_e32 v12, 2, v220
	v_add_u32_e32 v15, 0x1000, v12
	global_load_dword v184, v12, s[22:23]
	global_load_dword v185, v12, s[22:23] offset:2048
	global_load_dword v186, v15, s[22:23]
	global_load_dword v187, v15, s[22:23] offset:2048
	global_load_dword v188, v12, s[18:19]
	global_load_dword v189, v12, s[18:19] offset:2048
	s_add_u32 s18, s18, 0x1000
	s_addc_u32 s19, s19, 0
	global_load_dword v190, v12, s[18:19]
	global_load_dword v191, v12, s[18:19] offset:2048
	s_add_u32 s18, s18, 0x1000
	s_addc_u32 s19, s19, 0
	global_load_dword v192, v12, s[18:19]
	global_load_dword v193, v12, s[18:19] offset:2048
	s_add_u32 s18, s18, 0x1000
	s_addc_u32 s19, s19, 0
	global_load_dword v194, v12, s[18:19]
	global_load_dword v195, v12, s[18:19] offset:2048
	s_add_u32 s18, s18, 0x1000
	s_addc_u32 s19, s19, 0
	global_load_dword v196, v12, s[18:19]
	global_load_dword v197, v12, s[18:19] offset:2048
	s_add_u32 s18, s18, 0x1000
	s_addc_u32 s19, s19, 0
	global_load_dword v198, v12, s[18:19]
	global_load_dword v199, v12, s[18:19] offset:2048
	s_add_u32 s18, s18, 0x1000
	s_addc_u32 s19, s19, 0
	global_load_dword v200, v12, s[18:19]
	global_load_dword v201, v12, s[18:19] offset:2048
	s_add_u32 s18, s18, 0x1000
	s_addc_u32 s19, s19, 0
	global_load_dword v202, v12, s[18:19]
	global_load_dword v203, v12, s[18:19] offset:2048
	v_mov_b32_e32 v1, v12
	s_waitcnt vmcnt(0)
	v_mul_f32_e32 v5, 0xbfb8aa3b, v184
	v_exp_f32_e32 v5, v5
	s_nop 0
	v_add_f32_e32 v5, 1.0, v5
	v_div_scale_f32 v7, s[20:21], v5, v5, v184
	v_rcp_f32_e32 v8, v7
	s_nop 0
	v_fma_f32 v9, -v7, v8, 1.0
	v_fmac_f32_e32 v8, v9, v8
	v_div_scale_f32 v9, vcc, v184, v5, v184
	v_mul_f32_e32 v2, v9, v8
	v_fma_f32 v3, -v7, v2, v9
	v_fmac_f32_e32 v2, v3, v8
	v_fma_f32 v7, -v7, v2, v9
	v_div_fmas_f32 v7, v7, v8, v2
	v_div_fixup_f32 v4, v7, v5, v184
	ds_write_b32 v1, v4
	v_mul_f32_e32 v5, 0xbfb8aa3b, v185
	v_exp_f32_e32 v5, v5
	s_nop 0
	v_add_f32_e32 v5, 1.0, v5
	v_div_scale_f32 v7, s[20:21], v5, v5, v185
	v_rcp_f32_e32 v8, v7
	s_nop 0
	v_fma_f32 v9, -v7, v8, 1.0
	v_fmac_f32_e32 v8, v9, v8
	v_div_scale_f32 v9, vcc, v185, v5, v185
	v_mul_f32_e32 v2, v9, v8
	v_fma_f32 v3, -v7, v2, v9
	v_fmac_f32_e32 v2, v3, v8
	v_fma_f32 v7, -v7, v2, v9
	v_div_fmas_f32 v7, v7, v8, v2
	v_div_fixup_f32 v4, v7, v5, v185
	ds_write_b32 v1, v4 offset:2048
	v_mul_f32_e32 v5, 0xbfb8aa3b, v186
	v_exp_f32_e32 v5, v5
	s_nop 0
	v_add_f32_e32 v5, 1.0, v5
	v_div_scale_f32 v7, s[20:21], v5, v5, v186
	v_rcp_f32_e32 v8, v7
	s_nop 0
	v_fma_f32 v9, -v7, v8, 1.0
	v_fmac_f32_e32 v8, v9, v8
	v_div_scale_f32 v9, vcc, v186, v5, v186
	v_mul_f32_e32 v2, v9, v8
	v_fma_f32 v3, -v7, v2, v9
	v_fmac_f32_e32 v2, v3, v8
	v_fma_f32 v7, -v7, v2, v9
	v_div_fmas_f32 v7, v7, v8, v2
	v_div_fixup_f32 v4, v7, v5, v186
	ds_write_b32 v1, v4 offset:4096
	v_mul_f32_e32 v5, 0xbfb8aa3b, v187
	v_exp_f32_e32 v5, v5
	s_nop 0
	v_add_f32_e32 v5, 1.0, v5
	v_div_scale_f32 v7, s[20:21], v5, v5, v187
	v_rcp_f32_e32 v8, v7
	s_nop 0
	v_fma_f32 v9, -v7, v8, 1.0
	v_fmac_f32_e32 v8, v9, v8
	v_div_scale_f32 v9, vcc, v187, v5, v187
	v_mul_f32_e32 v2, v9, v8
	v_fma_f32 v3, -v7, v2, v9
	v_fmac_f32_e32 v2, v3, v8
	v_fma_f32 v7, -v7, v2, v9
	v_div_fmas_f32 v7, v7, v8, v2
	v_div_fixup_f32 v4, v7, v5, v187
	ds_write_b32 v1, v4 offset:6144
	v_mul_f32_e32 v5, 0xbfb8aa3b, v188
	v_exp_f32_e32 v5, v5
	s_nop 0
	v_add_f32_e32 v5, 1.0, v5
	v_div_scale_f32 v7, s[20:21], v5, v5, v188
	v_rcp_f32_e32 v8, v7
	s_nop 0
	v_fma_f32 v9, -v7, v8, 1.0
	v_fmac_f32_e32 v8, v9, v8
	v_div_scale_f32 v9, vcc, v188, v5, v188
	v_mul_f32_e32 v2, v9, v8
	v_fma_f32 v3, -v7, v2, v9
	v_fmac_f32_e32 v2, v3, v8
	v_fma_f32 v7, -v7, v2, v9
	v_div_fmas_f32 v7, v7, v8, v2
	v_div_fixup_f32 v4, v7, v5, v188
	ds_write_b32 v1, v4 offset:8192
	v_mul_f32_e32 v5, 0xbfb8aa3b, v189
	v_exp_f32_e32 v5, v5
	s_nop 0
	v_add_f32_e32 v5, 1.0, v5
	v_div_scale_f32 v7, s[20:21], v5, v5, v189
	v_rcp_f32_e32 v8, v7
	s_nop 0
	v_fma_f32 v9, -v7, v8, 1.0
	v_fmac_f32_e32 v8, v9, v8
	v_div_scale_f32 v9, vcc, v189, v5, v189
	v_mul_f32_e32 v2, v9, v8
	v_fma_f32 v3, -v7, v2, v9
	v_fmac_f32_e32 v2, v3, v8
	v_fma_f32 v7, -v7, v2, v9
	v_div_fmas_f32 v7, v7, v8, v2
	v_div_fixup_f32 v4, v7, v5, v189
	ds_write_b32 v1, v4 offset:10240
	v_mul_f32_e32 v5, 0xbfb8aa3b, v190
	v_exp_f32_e32 v5, v5
	s_nop 0
	v_add_f32_e32 v5, 1.0, v5
	v_div_scale_f32 v7, s[20:21], v5, v5, v190
	v_rcp_f32_e32 v8, v7
	s_nop 0
	v_fma_f32 v9, -v7, v8, 1.0
	v_fmac_f32_e32 v8, v9, v8
	v_div_scale_f32 v9, vcc, v190, v5, v190
	v_mul_f32_e32 v2, v9, v8
	v_fma_f32 v3, -v7, v2, v9
	v_fmac_f32_e32 v2, v3, v8
	v_fma_f32 v7, -v7, v2, v9
	v_div_fmas_f32 v7, v7, v8, v2
; DI void adaln_layer(const Frame& F, int l, int b_idx, int b_cnt) {
;     ...
;     for (int i = F.tid; i < NSEQ * DM; i += 512) { const int s = i >> 10, k = i & 1023; const float c = s < 2 ? cp[s * DM + k] : cs[(s - 2) * DM + k]; sc[i] = c / (1.f + __expf(-c)); }
	v_div_fixup_f32 v4, v7, v5, v190
	ds_write_b32 v1, v4 offset:12288
	v_mul_f32_e32 v5, 0xbfb8aa3b, v191
	v_exp_f32_e32 v5, v5
	s_nop 0
	v_add_f32_e32 v5, 1.0, v5
	v_div_scale_f32 v7, s[20:21], v5, v5, v191
	v_rcp_f32_e32 v8, v7
	s_nop 0
	v_fma_f32 v9, -v7, v8, 1.0
	v_fmac_f32_e32 v8, v9, v8
	v_div_scale_f32 v9, vcc, v191, v5, v191
	v_mul_f32_e32 v2, v9, v8
	v_fma_f32 v3, -v7, v2, v9
	v_fmac_f32_e32 v2, v3, v8
	v_fma_f32 v7, -v7, v2, v9
	v_div_fmas_f32 v7, v7, v8, v2
	v_div_fixup_f32 v4, v7, v5, v191
	ds_write_b32 v1, v4 offset:14336
	v_mul_f32_e32 v5, 0xbfb8aa3b, v192
	v_exp_f32_e32 v5, v5
	s_nop 0
	v_add_f32_e32 v5, 1.0, v5
	v_div_scale_f32 v7, s[20:21], v5, v5, v192
	v_rcp_f32_e32 v8, v7
	s_nop 0
	v_fma_f32 v9, -v7, v8, 1.0
	v_fmac_f32_e32 v8, v9, v8
	v_div_scale_f32 v9, vcc, v192, v5, v192
	v_mul_f32_e32 v2, v9, v8
	v_fma_f32 v3, -v7, v2, v9
	v_fmac_f32_e32 v2, v3, v8
	v_fma_f32 v7, -v7, v2, v9
	v_div_fmas_f32 v7, v7, v8, v2
	v_div_fixup_f32 v4, v7, v5, v192
	ds_write_b32 v1, v4 offset:16384
	v_mul_f32_e32 v5, 0xbfb8aa3b, v193
	v_exp_f32_e32 v5, v5
	s_nop 0
	v_add_f32_e32 v5, 1.0, v5
	v_div_scale_f32 v7, s[20:21], v5, v5, v193
	v_rcp_f32_e32 v8, v7
	s_nop 0
	v_fma_f32 v9, -v7, v8, 1.0
	v_fmac_f32_e32 v8, v9, v8
	v_div_scale_f32 v9, vcc, v193, v5, v193
	v_mul_f32_e32 v2, v9, v8
	v_fma_f32 v3, -v7, v2, v9
	v_fmac_f32_e32 v2, v3, v8
	v_fma_f32 v7, -v7, v2, v9
	v_div_fmas_f32 v7, v7, v8, v2
	v_div_fixup_f32 v4, v7, v5, v193
	ds_write_b32 v1, v4 offset:18432
	v_mul_f32_e32 v5, 0xbfb8aa3b, v194
	v_exp_f32_e32 v5, v5
	s_nop 0
	v_add_f32_e32 v5, 1.0, v5
	v_div_scale_f32 v7, s[20:21], v5, v5, v194
	v_rcp_f32_e32 v8, v7
	s_nop 0
	v_fma_f32 v9, -v7, v8, 1.0
	v_fmac_f32_e32 v8, v9, v8
	v_div_scale_f32 v9, vcc, v194, v5, v194
	v_mul_f32_e32 v2, v9, v8
	v_fma_f32 v3, -v7, v2, v9
	v_fmac_f32_e32 v2, v3, v8
	v_fma_f32 v7, -v7, v2, v9
	v_div_fmas_f32 v7, v7, v8, v2
	v_div_fixup_f32 v4, v7, v5, v194
	ds_write_b32 v1, v4 offset:20480
	v_mul_f32_e32 v5, 0xbfb8aa3b, v195
	v_exp_f32_e32 v5, v5
	s_nop 0
	v_add_f32_e32 v5, 1.0, v5
	v_div_scale_f32 v7, s[20:21], v5, v5, v195
	v_rcp_f32_e32 v8, v7
	s_nop 0
	v_fma_f32 v9, -v7, v8, 1.0
	v_fmac_f32_e32 v8, v9, v8
	v_div_scale_f32 v9, vcc, v195, v5, v195
	v_mul_f32_e32 v2, v9, v8
	v_fma_f32 v3, -v7, v2, v9
	v_fmac_f32_e32 v2, v3, v8
	v_fma_f32 v7, -v7, v2, v9
	v_div_fmas_f32 v7, v7, v8, v2
	v_div_fixup_f32 v4, v7, v5, v195
	ds_write_b32 v1, v4 offset:22528
	v_mul_f32_e32 v5, 0xbfb8aa3b, v196
	v_exp_f32_e32 v5, v5
	s_nop 0
	v_add_f32_e32 v5, 1.0, v5
	v_div_scale_f32 v7, s[20:21], v5, v5, v196
	v_rcp_f32_e32 v8, v7
	s_nop 0
	v_fma_f32 v9, -v7, v8, 1.0
	v_fmac_f32_e32 v8, v9, v8
	v_div_scale_f32 v9, vcc, v196, v5, v196
	v_mul_f32_e32 v2, v9, v8
	v_fma_f32 v3, -v7, v2, v9
	v_fmac_f32_e32 v2, v3, v8
	v_fma_f32 v7, -v7, v2, v9
	v_div_fmas_f32 v7, v7, v8, v2
	v_div_fixup_f32 v4, v7, v5, v196
	ds_write_b32 v1, v4 offset:24576
	v_mul_f32_e32 v5, 0xbfb8aa3b, v197
	v_exp_f32_e32 v5, v5
	s_nop 0
	v_add_f32_e32 v5, 1.0, v5
	v_div_scale_f32 v7, s[20:21], v5, v5, v197
	v_rcp_f32_e32 v8, v7
	s_nop 0
	v_fma_f32 v9, -v7, v8, 1.0
	v_fmac_f32_e32 v8, v9, v8
	v_div_scale_f32 v9, vcc, v197, v5, v197
	v_mul_f32_e32 v2, v9, v8
	v_fma_f32 v3, -v7, v2, v9
	v_fmac_f32_e32 v2, v3, v8
	v_fma_f32 v7, -v7, v2, v9
	v_div_fmas_f32 v7, v7, v8, v2
	v_div_fixup_f32 v4, v7, v5, v197
	ds_write_b32 v1, v4 offset:26624
	v_mul_f32_e32 v5, 0xbfb8aa3b, v198
	v_exp_f32_e32 v5, v5
	s_nop 0
	v_add_f32_e32 v5, 1.0, v5
	v_div_scale_f32 v7, s[20:21], v5, v5, v198
	v_rcp_f32_e32 v8, v7
	s_nop 0
	v_fma_f32 v9, -v7, v8, 1.0
	v_fmac_f32_e32 v8, v9, v8
	v_div_scale_f32 v9, vcc, v198, v5, v198
	v_mul_f32_e32 v2, v9, v8
	v_fma_f32 v3, -v7, v2, v9
	v_fmac_f32_e32 v2, v3, v8
	v_fma_f32 v7, -v7, v2, v9
	v_div_fmas_f32 v7, v7, v8, v2
	v_div_fixup_f32 v4, v7, v5, v198
	ds_write_b32 v1, v4 offset:28672
	v_mul_f32_e32 v5, 0xbfb8aa3b, v199
	v_exp_f32_e32 v5, v5
	s_nop 0
	v_add_f32_e32 v5, 1.0, v5
	v_div_scale_f32 v7, s[20:21], v5, v5, v199
	v_rcp_f32_e32 v8, v7
	s_nop 0
	v_fma_f32 v9, -v7, v8, 1.0
	v_fmac_f32_e32 v8, v9, v8
	v_div_scale_f32 v9, vcc, v199, v5, v199
	v_mul_f32_e32 v2, v9, v8
	v_fma_f32 v3, -v7, v2, v9
	v_fmac_f32_e32 v2, v3, v8
	v_fma_f32 v7, -v7, v2, v9
	v_div_fmas_f32 v7, v7, v8, v2
	v_div_fixup_f32 v4, v7, v5, v199
	ds_write_b32 v1, v4 offset:30720
	v_mul_f32_e32 v5, 0xbfb8aa3b, v200
	v_exp_f32_e32 v5, v5
	s_nop 0
	v_add_f32_e32 v5, 1.0, v5
	v_div_scale_f32 v7, s[20:21], v5, v5, v200
	v_rcp_f32_e32 v8, v7
	s_nop 0
	v_fma_f32 v9, -v7, v8, 1.0
	v_fmac_f32_e32 v8, v9, v8
	v_div_scale_f32 v9, vcc, v200, v5, v200
	v_mul_f32_e32 v2, v9, v8
	v_fma_f32 v3, -v7, v2, v9
	v_fmac_f32_e32 v2, v3, v8
	v_fma_f32 v7, -v7, v2, v9
	v_div_fmas_f32 v7, v7, v8, v2
	v_div_fixup_f32 v4, v7, v5, v200
	ds_write_b32 v1, v4 offset:32768
	v_mul_f32_e32 v5, 0xbfb8aa3b, v201
	v_exp_f32_e32 v5, v5
	s_nop 0
	v_add_f32_e32 v5, 1.0, v5
	v_div_scale_f32 v7, s[20:21], v5, v5, v201
	v_rcp_f32_e32 v8, v7
	s_nop 0
	v_fma_f32 v9, -v7, v8, 1.0
	v_fmac_f32_e32 v8, v9, v8
	v_div_scale_f32 v9, vcc, v201, v5, v201
	v_mul_f32_e32 v2, v9, v8
	v_fma_f32 v3, -v7, v2, v9
	v_fmac_f32_e32 v2, v3, v8
	v_fma_f32 v7, -v7, v2, v9
	v_div_fmas_f32 v7, v7, v8, v2
	v_div_fixup_f32 v4, v7, v5, v201
	ds_write_b32 v1, v4 offset:34816
	v_mul_f32_e32 v5, 0xbfb8aa3b, v202
	v_exp_f32_e32 v5, v5
	s_nop 0
	v_add_f32_e32 v5, 1.0, v5
	v_div_scale_f32 v7, s[20:21], v5, v5, v202
	v_rcp_f32_e32 v8, v7
	s_nop 0
	v_fma_f32 v9, -v7, v8, 1.0
	v_fmac_f32_e32 v8, v9, v8
	v_div_scale_f32 v9, vcc, v202, v5, v202
	v_mul_f32_e32 v2, v9, v8
	v_fma_f32 v3, -v7, v2, v9
	v_fmac_f32_e32 v2, v3, v8
	v_fma_f32 v7, -v7, v2, v9
	v_div_fmas_f32 v7, v7, v8, v2
	v_div_fixup_f32 v4, v7, v5, v202
	ds_write_b32 v1, v4 offset:36864
	v_mul_f32_e32 v5, 0xbfb8aa3b, v203
	v_exp_f32_e32 v5, v5
	s_nop 0
	v_add_f32_e32 v5, 1.0, v5
	v_div_scale_f32 v7, s[20:21], v5, v5, v203
	v_rcp_f32_e32 v8, v7
	s_nop 0
	v_fma_f32 v9, -v7, v8, 1.0
	v_fmac_f32_e32 v8, v9, v8
	v_div_scale_f32 v9, vcc, v203, v5, v203
	v_mul_f32_e32 v2, v9, v8
	v_fma_f32 v3, -v7, v2, v9
	v_fmac_f32_e32 v2, v3, v8
	v_fma_f32 v7, -v7, v2, v9
	v_div_fmas_f32 v7, v7, v8, v2
	v_div_fixup_f32 v4, v7, v5, v203
	ds_write_b32 v1, v4 offset:38912

; DI void adaln_layer(const Frame& F, int l, int b_idx, int b_cnt) {
;     ...
;     for (int task = b_idx; task < 144; task += b_cnt) {
;         const int n0 = task * 64;
;         const float* W = F.in[9] + (size_t)l * DM * MODW + n0 + F.lane;
;         float acc[NSEQ];
; #pragma unroll
;         for (int s = 0; s < NSEQ; ++s) acc[s] = 0.f;
;         const int k0 = F.wave * 128;
;         const float* wp_ = W + (size_t)k0 * MODW;
; #pragma unroll 1
;         for (int kb = k0; kb < k0 + 128; kb += 16) {
;             float wv[16];
; #pragma unroll
;             for (int i = 0; i < 16; ++i) { wv[i] = __builtin_nontemporal_load(wp_); wp_ += MODW; }
.LBB0_151:
	v_readlane_b32 s0, v254, 52
	s_mul_i32 s18, s22, 0x2400000
	v_mov_b32_e32 v109, v0
	v_mov_b32_e32 v2, s0
	ds_read_b64 v[2:3], v2
	s_lshl_b32 s0, s36, 6
	s_ashr_i32 s1, s0, 31
	v_mov_b32_e32 v114, 0
	s_mov_b32 s37, s35
	s_waitcnt lgkmcnt(0)
	v_readfirstlane_b32 s15, v2
	v_readfirstlane_b32 s2, v3
	s_add_u32 s15, s15, s18
	s_mul_hi_u32 s18, s22, 0x2400000
	s_addc_u32 s2, s2, s18
	s_lshl_b64 s[30:31], s[0:1], 2
	s_add_u32 s0, s15, s30
	s_addc_u32 s1, s2, s31
	v_lshl_add_u64 v[2:3], s[0:1], 0, v[108:109]
	v_lshl_add_u64 v[110:111], v[2:3], 0, s[28:29]
	s_mov_b32 s44, s34
	v_mov_b32_e32 v115, v114
	v_mov_b32_e32 v116, v114
	v_mov_b32_e32 v117, v114
	v_mov_b32_e32 v118, v114
	v_mov_b32_e32 v119, v114
	v_mov_b32_e32 v120, v114
	v_mov_b32_e32 v121, v114
	v_mov_b32_e32 v112, v114
	v_mov_b32_e32 v113, v114
	v_readfirstlane_b32 s18, v110
	v_readfirstlane_b32 s19, v111
	v_and_b32_e32 v11, 63, v220
	v_lshlrev_b32_e32 v11, 2, v11
	v_mov_b32_e32 v10, s37
	s_nop 4
	global_load_dword v184, v11, s[18:19] nt
	s_add_u32 s18, s18, 0x9000
	s_addc_u32 s19, s19, 0
	global_load_dword v185, v11, s[18:19] nt
	s_add_u32 s18, s18, 0x9000
	s_addc_u32 s19, s19, 0
	global_load_dword v186, v11, s[18:19] nt
	s_add_u32 s18, s18, 0x9000
	s_addc_u32 s19, s19, 0
	global_load_dword v187, v11, s[18:19] nt
	s_add_u32 s18, s18, 0x9000
	s_addc_u32 s19, s19, 0
	global_load_dword v188, v11, s[18:19] nt
	s_add_u32 s18, s18, 0x9000
	s_addc_u32 s19, s19, 0
	global_load_dword v189, v11, s[18:19] nt
	s_add_u32 s18, s18, 0x9000
	s_addc_u32 s19, s19, 0
	global_load_dword v190, v11, s[18:19] nt
	s_add_u32 s18, s18, 0x9000
	s_addc_u32 s19, s19, 0
	global_load_dword v191, v11, s[18:19] nt
	s_add_u32 s18, s18, 0x9000
	s_addc_u32 s19, s19, 0
	global_load_dword v192, v11, s[18:19] nt
	s_add_u32 s18, s18, 0x9000
	s_addc_u32 s19, s19, 0
	global_load_dword v193, v11, s[18:19] nt
	s_add_u32 s18, s18, 0x9000
	s_addc_u32 s19, s19, 0
	global_load_dword v194, v11, s[18:19] nt
	s_add_u32 s18, s18, 0x9000
	s_addc_u32 s19, s19, 0
	global_load_dword v195, v11, s[18:19] nt
	s_add_u32 s18, s18, 0x9000
	s_addc_u32 s19, s19, 0
	global_load_dword v196, v11, s[18:19] nt
	s_add_u32 s18, s18, 0x9000
	s_addc_u32 s19, s19, 0
	global_load_dword v197, v11, s[18:19] nt
	s_add_u32 s18, s18, 0x9000
	s_addc_u32 s19, s19, 0
	global_load_dword v198, v11, s[18:19] nt
	s_add_u32 s18, s18, 0x9000
	s_addc_u32 s19, s19, 0
	global_load_dword v199, v11, s[18:19] nt
	s_add_u32 s18, s18, 0x9000
	s_addc_u32 s19, s19, 0
	global_load_dword v200, v11, s[18:19] nt
	s_add_u32 s18, s18, 0x9000
	s_addc_u32 s19, s19, 0
	global_load_dword v201, v11, s[18:19] nt
	s_add_u32 s18, s18, 0x9000
	s_addc_u32 s19, s19, 0
	global_load_dword v202, v11, s[18:19] nt
	s_add_u32 s18, s18, 0x9000
	s_addc_u32 s19, s19, 0
	global_load_dword v203, v11, s[18:19] nt
	s_add_u32 s18, s18, 0x9000
	s_addc_u32 s19, s19, 0
	global_load_dword v204, v11, s[18:19] nt
	s_add_u32 s18, s18, 0x9000
	s_addc_u32 s19, s19, 0
	global_load_dword v205, v11, s[18:19] nt
	s_add_u32 s18, s18, 0x9000
	s_addc_u32 s19, s19, 0
	global_load_dword v206, v11, s[18:19] nt
	s_add_u32 s18, s18, 0x9000
	s_addc_u32 s19, s19, 0
	global_load_dword v207, v11, s[18:19] nt
	s_add_u32 s18, s18, 0x9000
	s_addc_u32 s19, s19, 0
	global_load_dword v208, v11, s[18:19] nt
	s_add_u32 s18, s18, 0x9000
	s_addc_u32 s19, s19, 0
	global_load_dword v209, v11, s[18:19] nt
	s_add_u32 s18, s18, 0x9000
	s_addc_u32 s19, s19, 0
	global_load_dword v210, v11, s[18:19] nt
	s_add_u32 s18, s18, 0x9000
	s_addc_u32 s19, s19, 0
	global_load_dword v211, v11, s[18:19] nt
	s_add_u32 s18, s18, 0x9000
	s_addc_u32 s19, s19, 0
	global_load_dword v212, v11, s[18:19] nt
	s_add_u32 s18, s18, 0x9000
	s_addc_u32 s19, s19, 0
	global_load_dword v213, v11, s[18:19] nt
	s_add_u32 s18, s18, 0x9000
	s_addc_u32 s19, s19, 0
	global_load_dword v214, v11, s[18:19] nt
	s_add_u32 s18, s18, 0x9000
	s_addc_u32 s19, s19, 0
	global_load_dword v215, v11, s[18:19] nt
	s_add_u32 s18, s18, 0x9000
	s_addc_u32 s19, s19, 0
	global_load_dword v216, v11, s[18:19] nt
	s_add_u32 s18, s18, 0x9000
	s_addc_u32 s19, s19, 0
	global_load_dword v217, v11, s[18:19] nt
	s_add_u32 s18, s18, 0x9000
	s_addc_u32 s19, s19, 0
	global_load_dword v218, v11, s[18:19] nt
	s_add_u32 s18, s18, 0x9000
	s_addc_u32 s19, s19, 0
	global_load_dword v236, v11, s[18:19] nt
	s_add_u32 s18, s18, 0x9000
	s_addc_u32 s19, s19, 0
	global_load_dword v237, v11, s[18:19] nt
	s_add_u32 s18, s18, 0x9000
	s_addc_u32 s19, s19, 0
	global_load_dword v238, v11, s[18:19] nt
	s_add_u32 s18, s18, 0x9000
	s_addc_u32 s19, s19, 0
	global_load_dword v239, v11, s[18:19] nt
	s_add_u32 s18, s18, 0x9000
	s_addc_u32 s19, s19, 0
	global_load_dword v240, v11, s[18:19] nt
	s_add_u32 s18, s18, 0x9000
	s_addc_u32 s19, s19, 0
	global_load_dword v241, v11, s[18:19] nt
	s_add_u32 s18, s18, 0x9000
	s_addc_u32 s19, s19, 0
	global_load_dword v242, v11, s[18:19] nt
	s_add_u32 s18, s18, 0x9000
	s_addc_u32 s19, s19, 0
	global_load_dword v243, v11, s[18:19] nt
	s_add_u32 s18, s18, 0x9000
	s_addc_u32 s19, s19, 0
	global_load_dword v244, v11, s[18:19] nt
	s_add_u32 s18, s18, 0x9000
	s_addc_u32 s19, s19, 0
	global_load_dword v245, v11, s[18:19] nt
	s_add_u32 s18, s18, 0x9000
	s_addc_u32 s19, s19, 0
	global_load_dword v248, v11, s[18:19] nt
	s_add_u32 s18, s18, 0x9000
	s_addc_u32 s19, s19, 0
	global_load_dword v249, v11, s[18:19] nt
	s_add_u32 s18, s18, 0x9000
	s_addc_u32 s19, s19, 0
	global_load_dword v250, v11, s[18:19] nt
	s_add_u32 s18, s18, 0x9000
	s_addc_u32 s19, s19, 0
	s_waitcnt vmcnt(32)
; #define LAS __attribute__((address_space(3)))
; DI void adaln_layer(const Frame& F, int l, int b_idx, int b_cnt) {
;     ...
;         for (int kb = k0; kb < k0 + 128; kb += 16) {
;             float wv[16];
; #pragma unroll
;             for (int i = 0; i < 16; ++i) { wv[i] = __builtin_nontemporal_load(wp_); wp_ += MODW; }
; #pragma unroll
;             for (int i = 0; i < 16; i += 4) {
; #pragma unroll
;                 for (int s = 0; s < NSEQ; ++s) { const f32x4 c4 = *(const LAS f32x4*)(sc + s * DM + kb + i); acc[s] += (c4[0] * wv[i] + c4[1] * wv[i + 1]) + (c4[2] * wv[i + 2] + c4[3] * wv[i + 3]); } }
	ds_read_b128 v[2:5], v10 offset:0
	ds_read_b128 v[6:9], v10 offset:4096
	ds_read_b128 v[22:25], v10 offset:8192
	ds_read_b128 v[30:33], v10 offset:12288
	ds_read_b128 v[34:37], v10 offset:16384
	ds_read_b128 v[38:41], v10 offset:20480
	ds_read_b128 v[42:45], v10 offset:24576
	ds_read_b128 v[46:49], v10 offset:28672
	ds_read_b128 v[50:53], v10 offset:32768
	ds_read_b128 v[60:63], v10 offset:36864
	s_waitcnt lgkmcnt(5)
	v_fmac_f32_e32 v114, v2, v184
	v_fmac_f32_e32 v114, v3, v185
	v_fmac_f32_e32 v114, v4, v186
	v_fmac_f32_e32 v114, v5, v187
	v_fmac_f32_e32 v115, v6, v184
	v_fmac_f32_e32 v115, v7, v185
	v_fmac_f32_e32 v115, v8, v186
	v_fmac_f32_e32 v115, v9, v187
	v_fmac_f32_e32 v116, v22, v184
	v_fmac_f32_e32 v116, v23, v185
	v_fmac_f32_e32 v116, v24, v186
	v_fmac_f32_e32 v116, v25, v187
	v_fmac_f32_e32 v117, v30, v184
	v_fmac_f32_e32 v117, v31, v185
	v_fmac_f32_e32 v117, v32, v186
	v_fmac_f32_e32 v117, v33, v187
	v_fmac_f32_e32 v118, v34, v184
	v_fmac_f32_e32 v118, v35, v185
	v_fmac_f32_e32 v118, v36, v186
	v_fmac_f32_e32 v118, v37, v187
	ds_read_b128 v[2:5], v10 offset:16
	ds_read_b128 v[6:9], v10 offset:4112
	ds_read_b128 v[22:25], v10 offset:8208
	ds_read_b128 v[30:33], v10 offset:12304
	ds_read_b128 v[34:37], v10 offset:16400
	s_waitcnt lgkmcnt(5)
	v_fmac_f32_e32 v119, v38, v184
	v_fmac_f32_e32 v119, v39, v185
	v_fmac_f32_e32 v119, v40, v186
	v_fmac_f32_e32 v119, v41, v187
	v_fmac_f32_e32 v120, v42, v184
	v_fmac_f32_e32 v120, v43, v185
	v_fmac_f32_e32 v120, v44, v186
	v_fmac_f32_e32 v120, v45, v187
	v_fmac_f32_e32 v121, v46, v184
	v_fmac_f32_e32 v121, v47, v185
	v_fmac_f32_e32 v121, v48, v186
	v_fmac_f32_e32 v121, v49, v187
	v_fmac_f32_e32 v112, v50, v184
	v_fmac_f32_e32 v112, v51, v185
	v_fmac_f32_e32 v112, v52, v186
	v_fmac_f32_e32 v112, v53, v187
	v_fmac_f32_e32 v113, v60, v184
	v_fmac_f32_e32 v113, v61, v185
	v_fmac_f32_e32 v113, v62, v186
	v_fmac_f32_e32 v113, v63, v187
	ds_read_b128 v[38:41], v10 offset:20496
	ds_read_b128 v[42:45], v10 offset:24592
	ds_read_b128 v[46:49], v10 offset:28688
	ds_read_b128 v[50:53], v10 offset:32784
	ds_read_b128 v[60:63], v10 offset:36880
	s_waitcnt lgkmcnt(5)
	v_fmac_f32_e32 v114, v2, v188
	v_fmac_f32_e32 v114, v3, v189
	v_fmac_f32_e32 v114, v4, v190
	v_fmac_f32_e32 v114, v5, v191
	v_fmac_f32_e32 v115, v6, v188
	v_fmac_f32_e32 v115, v7, v189
	v_fmac_f32_e32 v115, v8, v190
	v_fmac_f32_e32 v115, v9, v191
	v_fmac_f32_e32 v116, v22, v188
	v_fmac_f32_e32 v116, v23, v189
	v_fmac_f32_e32 v116, v24, v190
	v_fmac_f32_e32 v116, v25, v191
	v_fmac_f32_e32 v117, v30, v188
	v_fmac_f32_e32 v117, v31, v189
	v_fmac_f32_e32 v117, v32, v190
	v_fmac_f32_e32 v117, v33, v191
	v_fmac_f32_e32 v118, v34, v188
	v_fmac_f32_e32 v118, v35, v189
	v_fmac_f32_e32 v118, v36, v190
	v_fmac_f32_e32 v118, v37, v191
	ds_read_b128 v[2:5], v10 offset:32
	ds_read_b128 v[6:9], v10 offset:4128
	ds_read_b128 v[22:25], v10 offset:8224
	ds_read_b128 v[30:33], v10 offset:12320
	ds_read_b128 v[34:37], v10 offset:16416
	s_waitcnt lgkmcnt(5)
	v_fmac_f32_e32 v119, v38, v188
	v_fmac_f32_e32 v119, v39, v189
	v_fmac_f32_e32 v119, v40, v190
	v_fmac_f32_e32 v119, v41, v191
	v_fmac_f32_e32 v120, v42, v188
	v_fmac_f32_e32 v120, v43, v189
	v_fmac_f32_e32 v120, v44, v190
	v_fmac_f32_e32 v120, v45, v191
	v_fmac_f32_e32 v121, v46, v188
	v_fmac_f32_e32 v121, v47, v189
	v_fmac_f32_e32 v121, v48, v190
	v_fmac_f32_e32 v121, v49, v191
	v_fmac_f32_e32 v112, v50, v188
	v_fmac_f32_e32 v112, v51, v189
	v_fmac_f32_e32 v112, v52, v190
	v_fmac_f32_e32 v112, v53, v191
	v_fmac_f32_e32 v113, v60, v188
	v_fmac_f32_e32 v113, v61, v189
	v_fmac_f32_e32 v113, v62, v190
	v_fmac_f32_e32 v113, v63, v191
	ds_read_b128 v[38:41], v10 offset:20512
	ds_read_b128 v[42:45], v10 offset:24608
	ds_read_b128 v[46:49], v10 offset:28704
	ds_read_b128 v[50:53], v10 offset:32800
	ds_read_b128 v[60:63], v10 offset:36896
	s_waitcnt lgkmcnt(5)
	v_fmac_f32_e32 v114, v2, v192
	v_fmac_f32_e32 v114, v3, v193
	v_fmac_f32_e32 v114, v4, v194
	v_fmac_f32_e32 v114, v5, v195
	v_fmac_f32_e32 v115, v6, v192
	v_fmac_f32_e32 v115, v7, v193
	v_fmac_f32_e32 v115, v8, v194
	v_fmac_f32_e32 v115, v9, v195
	v_fmac_f32_e32 v116, v22, v192
	v_fmac_f32_e32 v116, v23, v193
	v_fmac_f32_e32 v116, v24, v194
	v_fmac_f32_e32 v116, v25, v195
	v_fmac_f32_e32 v117, v30, v192
	v_fmac_f32_e32 v117, v31, v193
	v_fmac_f32_e32 v117, v32, v194
	v_fmac_f32_e32 v117, v33, v195
	v_fmac_f32_e32 v118, v34, v192
	v_fmac_f32_e32 v118, v35, v193
	v_fmac_f32_e32 v118, v36, v194
	v_fmac_f32_e32 v118, v37, v195
	ds_read_b128 v[2:5], v10 offset:48
	ds_read_b128 v[6:9], v10 offset:4144
	ds_read_b128 v[22:25], v10 offset:8240
	ds_read_b128 v[30:33], v10 offset:12336
	ds_read_b128 v[34:37], v10 offset:16432
	s_waitcnt lgkmcnt(5)
	v_fmac_f32_e32 v119, v38, v192
	v_fmac_f32_e32 v119, v39, v193
	v_fmac_f32_e32 v119, v40, v194
	v_fmac_f32_e32 v119, v41, v195
	v_fmac_f32_e32 v120, v42, v192
	v_fmac_f32_e32 v120, v43, v193
	v_fmac_f32_e32 v120, v44, v194
	v_fmac_f32_e32 v120, v45, v195
	v_fmac_f32_e32 v121, v46, v192
	v_fmac_f32_e32 v121, v47, v193
	v_fmac_f32_e32 v121, v48, v194
	v_fmac_f32_e32 v121, v49, v195
	v_fmac_f32_e32 v112, v50, v192
	v_fmac_f32_e32 v112, v51, v193
	v_fmac_f32_e32 v112, v52, v194
	v_fmac_f32_e32 v112, v53, v195
	v_fmac_f32_e32 v113, v60, v192
	v_fmac_f32_e32 v113, v61, v193
	v_fmac_f32_e32 v113, v62, v194
	v_fmac_f32_e32 v113, v63, v195
	ds_read_b128 v[38:41], v10 offset:20528
	ds_read_b128 v[42:45], v10 offset:24624
	ds_read_b128 v[46:49], v10 offset:28720
	ds_read_b128 v[50:53], v10 offset:32816
	ds_read_b128 v[60:63], v10 offset:36912
	s_waitcnt lgkmcnt(5)
; #define LAS __attribute__((address_space(3)))
; DI void adaln_layer(const Frame& F, int l, int b_idx, int b_cnt) {
;     ...
;         for (int kb = k0; kb < k0 + 128; kb += 16) {
;             float wv[16];
; #pragma unroll
;             for (int i = 0; i < 16; ++i) { wv[i] = __builtin_nontemporal_load(wp_); wp_ += MODW; }
; #pragma unroll
;             for (int i = 0; i < 16; i += 4) {
; #pragma unroll
;                 for (int s = 0; s < NSEQ; ++s) { const f32x4 c4 = *(const LAS f32x4*)(sc + s * DM + kb + i); acc[s] += (c4[0] * wv[i] + c4[1] * wv[i + 1]) + (c4[2] * wv[i + 2] + c4[3] * wv[i + 3]); } }
	v_fmac_f32_e32 v114, v2, v196
	v_fmac_f32_e32 v114, v3, v197
	v_fmac_f32_e32 v114, v4, v198
	v_fmac_f32_e32 v114, v5, v199
	v_fmac_f32_e32 v115, v6, v196
	v_fmac_f32_e32 v115, v7, v197
	v_fmac_f32_e32 v115, v8, v198
	v_fmac_f32_e32 v115, v9, v199
	v_fmac_f32_e32 v116, v22, v196
	v_fmac_f32_e32 v116, v23, v197
	v_fmac_f32_e32 v116, v24, v198
	v_fmac_f32_e32 v116, v25, v199
	v_fmac_f32_e32 v117, v30, v196
	v_fmac_f32_e32 v117, v31, v197
	v_fmac_f32_e32 v117, v32, v198
	v_fmac_f32_e32 v117, v33, v199
	v_fmac_f32_e32 v118, v34, v196
	v_fmac_f32_e32 v118, v35, v197
	v_fmac_f32_e32 v118, v36, v198
	v_fmac_f32_e32 v118, v37, v199
	s_waitcnt lgkmcnt(0)
	v_fmac_f32_e32 v119, v38, v196
	v_fmac_f32_e32 v119, v39, v197
	v_fmac_f32_e32 v119, v40, v198
	v_fmac_f32_e32 v119, v41, v199
	v_fmac_f32_e32 v120, v42, v196
	v_fmac_f32_e32 v120, v43, v197
	v_fmac_f32_e32 v120, v44, v198
	v_fmac_f32_e32 v120, v45, v199
	v_fmac_f32_e32 v121, v46, v196
	v_fmac_f32_e32 v121, v47, v197
	v_fmac_f32_e32 v121, v48, v198
	v_fmac_f32_e32 v121, v49, v199
	v_fmac_f32_e32 v112, v50, v196
	v_fmac_f32_e32 v112, v51, v197
	v_fmac_f32_e32 v112, v52, v198
	v_fmac_f32_e32 v112, v53, v199
	v_fmac_f32_e32 v113, v60, v196
	v_fmac_f32_e32 v113, v61, v197
	v_fmac_f32_e32 v113, v62, v198
	v_fmac_f32_e32 v113, v63, v199
	global_load_dword v184, v11, s[18:19] nt
	s_add_u32 s18, s18, 0x9000
	s_addc_u32 s19, s19, 0
	global_load_dword v185, v11, s[18:19] nt
	s_add_u32 s18, s18, 0x9000
	s_addc_u32 s19, s19, 0
	global_load_dword v186, v11, s[18:19] nt
	s_add_u32 s18, s18, 0x9000
	s_addc_u32 s19, s19, 0
	global_load_dword v187, v11, s[18:19] nt
	s_add_u32 s18, s18, 0x9000
	s_addc_u32 s19, s19, 0
	global_load_dword v188, v11, s[18:19] nt
	s_add_u32 s18, s18, 0x9000
	s_addc_u32 s19, s19, 0
	global_load_dword v189, v11, s[18:19] nt
	s_add_u32 s18, s18, 0x9000
	s_addc_u32 s19, s19, 0
	global_load_dword v190, v11, s[18:19] nt
	s_add_u32 s18, s18, 0x9000
	s_addc_u32 s19, s19, 0
	global_load_dword v191, v11, s[18:19] nt
	s_add_u32 s18, s18, 0x9000
	s_addc_u32 s19, s19, 0
	global_load_dword v192, v11, s[18:19] nt
	s_add_u32 s18, s18, 0x9000
	s_addc_u32 s19, s19, 0
	global_load_dword v193, v11, s[18:19] nt
	s_add_u32 s18, s18, 0x9000
	s_addc_u32 s19, s19, 0
	global_load_dword v194, v11, s[18:19] nt
	s_add_u32 s18, s18, 0x9000
	s_addc_u32 s19, s19, 0
	global_load_dword v195, v11, s[18:19] nt
	s_add_u32 s18, s18, 0x9000
	s_addc_u32 s19, s19, 0
	global_load_dword v196, v11, s[18:19] nt
	s_add_u32 s18, s18, 0x9000
	s_addc_u32 s19, s19, 0
	global_load_dword v197, v11, s[18:19] nt
	s_add_u32 s18, s18, 0x9000
	s_addc_u32 s19, s19, 0
	global_load_dword v198, v11, s[18:19] nt
	s_add_u32 s18, s18, 0x9000
	s_addc_u32 s19, s19, 0
	global_load_dword v199, v11, s[18:19] nt
	s_add_u32 s18, s18, 0x9000
	s_addc_u32 s19, s19, 0
	s_waitcnt vmcnt(32)
	ds_read_b128 v[2:5], v10 offset:64
	ds_read_b128 v[6:9], v10 offset:4160
	ds_read_b128 v[22:25], v10 offset:8256
	ds_read_b128 v[30:33], v10 offset:12352
	ds_read_b128 v[34:37], v10 offset:16448
	ds_read_b128 v[38:41], v10 offset:20544
	ds_read_b128 v[42:45], v10 offset:24640
	ds_read_b128 v[46:49], v10 offset:28736
	ds_read_b128 v[50:53], v10 offset:32832
	ds_read_b128 v[60:63], v10 offset:36928
	s_waitcnt lgkmcnt(5)
	v_fmac_f32_e32 v114, v2, v200
	v_fmac_f32_e32 v114, v3, v201
	v_fmac_f32_e32 v114, v4, v202
	v_fmac_f32_e32 v114, v5, v203
	v_fmac_f32_e32 v115, v6, v200
	v_fmac_f32_e32 v115, v7, v201
	v_fmac_f32_e32 v115, v8, v202
	v_fmac_f32_e32 v115, v9, v203
	v_fmac_f32_e32 v116, v22, v200
	v_fmac_f32_e32 v116, v23, v201
	v_fmac_f32_e32 v116, v24, v202
	v_fmac_f32_e32 v116, v25, v203
	v_fmac_f32_e32 v117, v30, v200
	v_fmac_f32_e32 v117, v31, v201
	v_fmac_f32_e32 v117, v32, v202
	v_fmac_f32_e32 v117, v33, v203
	v_fmac_f32_e32 v118, v34, v200
	v_fmac_f32_e32 v118, v35, v201
	v_fmac_f32_e32 v118, v36, v202
	v_fmac_f32_e32 v118, v37, v203
	ds_read_b128 v[2:5], v10 offset:80
	ds_read_b128 v[6:9], v10 offset:4176
	ds_read_b128 v[22:25], v10 offset:8272
	ds_read_b128 v[30:33], v10 offset:12368
	ds_read_b128 v[34:37], v10 offset:16464
	s_waitcnt lgkmcnt(5)
	v_fmac_f32_e32 v119, v38, v200
	v_fmac_f32_e32 v119, v39, v201
	v_fmac_f32_e32 v119, v40, v202
	v_fmac_f32_e32 v119, v41, v203
	v_fmac_f32_e32 v120, v42, v200
	v_fmac_f32_e32 v120, v43, v201
	v_fmac_f32_e32 v120, v44, v202
	v_fmac_f32_e32 v120, v45, v203
	v_fmac_f32_e32 v121, v46, v200
	v_fmac_f32_e32 v121, v47, v201
	v_fmac_f32_e32 v121, v48, v202
	v_fmac_f32_e32 v121, v49, v203
	v_fmac_f32_e32 v112, v50, v200
	v_fmac_f32_e32 v112, v51, v201
	v_fmac_f32_e32 v112, v52, v202
	v_fmac_f32_e32 v112, v53, v203
	v_fmac_f32_e32 v113, v60, v200
	v_fmac_f32_e32 v113, v61, v201
	v_fmac_f32_e32 v113, v62, v202
	v_fmac_f32_e32 v113, v63, v203
	ds_read_b128 v[38:41], v10 offset:20560
	ds_read_b128 v[42:45], v10 offset:24656
	ds_read_b128 v[46:49], v10 offset:28752
	ds_read_b128 v[50:53], v10 offset:32848
	ds_read_b128 v[60:63], v10 offset:36944
	s_waitcnt lgkmcnt(5)
	v_fmac_f32_e32 v114, v2, v204
	v_fmac_f32_e32 v114, v3, v205
	v_fmac_f32_e32 v114, v4, v206
	v_fmac_f32_e32 v114, v5, v207
	v_fmac_f32_e32 v115, v6, v204
	v_fmac_f32_e32 v115, v7, v205
	v_fmac_f32_e32 v115, v8, v206
	v_fmac_f32_e32 v115, v9, v207
	v_fmac_f32_e32 v116, v22, v204
	v_fmac_f32_e32 v116, v23, v205
	v_fmac_f32_e32 v116, v24, v206
	v_fmac_f32_e32 v116, v25, v207
	v_fmac_f32_e32 v117, v30, v204
	v_fmac_f32_e32 v117, v31, v205
	v_fmac_f32_e32 v117, v32, v206
	v_fmac_f32_e32 v117, v33, v207
	v_fmac_f32_e32 v118, v34, v204
	v_fmac_f32_e32 v118, v35, v205
	v_fmac_f32_e32 v118, v36, v206
	v_fmac_f32_e32 v118, v37, v207
	ds_read_b128 v[2:5], v10 offset:96
	ds_read_b128 v[6:9], v10 offset:4192
	ds_read_b128 v[22:25], v10 offset:8288
	ds_read_b128 v[30:33], v10 offset:12384
	ds_read_b128 v[34:37], v10 offset:16480
	s_waitcnt lgkmcnt(5)
; #define LAS __attribute__((address_space(3)))
; DI void adaln_layer(const Frame& F, int l, int b_idx, int b_cnt) {
;     ...
;         for (int kb = k0; kb < k0 + 128; kb += 16) {
;             float wv[16];
; #pragma unroll
;             for (int i = 0; i < 16; ++i) { wv[i] = __builtin_nontemporal_load(wp_); wp_ += MODW; }
; #pragma unroll
;             for (int i = 0; i < 16; i += 4) {
; #pragma unroll
;                 for (int s = 0; s < NSEQ; ++s) { const f32x4 c4 = *(const LAS f32x4*)(sc + s * DM + kb + i); acc[s] += (c4[0] * wv[i] + c4[1] * wv[i + 1]) + (c4[2] * wv[i + 2] + c4[3] * wv[i + 3]); } }
	v_fmac_f32_e32 v119, v38, v204
	v_fmac_f32_e32 v119, v39, v205
	v_fmac_f32_e32 v119, v40, v206
	v_fmac_f32_e32 v119, v41, v207
	v_fmac_f32_e32 v120, v42, v204
	v_fmac_f32_e32 v120, v43, v205
	v_fmac_f32_e32 v120, v44, v206
	v_fmac_f32_e32 v120, v45, v207
	v_fmac_f32_e32 v121, v46, v204
	v_fmac_f32_e32 v121, v47, v205
	v_fmac_f32_e32 v121, v48, v206
	v_fmac_f32_e32 v121, v49, v207
	v_fmac_f32_e32 v112, v50, v204
	v_fmac_f32_e32 v112, v51, v205
	v_fmac_f32_e32 v112, v52, v206
	v_fmac_f32_e32 v112, v53, v207
	v_fmac_f32_e32 v113, v60, v204
	v_fmac_f32_e32 v113, v61, v205
	v_fmac_f32_e32 v113, v62, v206
	v_fmac_f32_e32 v113, v63, v207
	ds_read_b128 v[38:41], v10 offset:20576
	ds_read_b128 v[42:45], v10 offset:24672
	ds_read_b128 v[46:49], v10 offset:28768
	ds_read_b128 v[50:53], v10 offset:32864
	ds_read_b128 v[60:63], v10 offset:36960
	s_waitcnt lgkmcnt(5)
	v_fmac_f32_e32 v114, v2, v208
	v_fmac_f32_e32 v114, v3, v209
	v_fmac_f32_e32 v114, v4, v210
	v_fmac_f32_e32 v114, v5, v211
	v_fmac_f32_e32 v115, v6, v208
	v_fmac_f32_e32 v115, v7, v209
	v_fmac_f32_e32 v115, v8, v210
	v_fmac_f32_e32 v115, v9, v211
	v_fmac_f32_e32 v116, v22, v208
	v_fmac_f32_e32 v116, v23, v209
	v_fmac_f32_e32 v116, v24, v210
	v_fmac_f32_e32 v116, v25, v211
	v_fmac_f32_e32 v117, v30, v208
	v_fmac_f32_e32 v117, v31, v209
	v_fmac_f32_e32 v117, v32, v210
	v_fmac_f32_e32 v117, v33, v211
	v_fmac_f32_e32 v118, v34, v208
	v_fmac_f32_e32 v118, v35, v209
	v_fmac_f32_e32 v118, v36, v210
	v_fmac_f32_e32 v118, v37, v211
	ds_read_b128 v[2:5], v10 offset:112
	ds_read_b128 v[6:9], v10 offset:4208
	ds_read_b128 v[22:25], v10 offset:8304
	ds_read_b128 v[30:33], v10 offset:12400
	ds_read_b128 v[34:37], v10 offset:16496
	s_waitcnt lgkmcnt(5)
	v_fmac_f32_e32 v119, v38, v208
	v_fmac_f32_e32 v119, v39, v209
	v_fmac_f32_e32 v119, v40, v210
	v_fmac_f32_e32 v119, v41, v211
	v_fmac_f32_e32 v120, v42, v208
	v_fmac_f32_e32 v120, v43, v209
	v_fmac_f32_e32 v120, v44, v210
	v_fmac_f32_e32 v120, v45, v211
	v_fmac_f32_e32 v121, v46, v208
	v_fmac_f32_e32 v121, v47, v209
	v_fmac_f32_e32 v121, v48, v210
	v_fmac_f32_e32 v121, v49, v211
	v_fmac_f32_e32 v112, v50, v208
	v_fmac_f32_e32 v112, v51, v209
	v_fmac_f32_e32 v112, v52, v210
	v_fmac_f32_e32 v112, v53, v211
	v_fmac_f32_e32 v113, v60, v208
	v_fmac_f32_e32 v113, v61, v209
	v_fmac_f32_e32 v113, v62, v210
	v_fmac_f32_e32 v113, v63, v211
	ds_read_b128 v[38:41], v10 offset:20592
	ds_read_b128 v[42:45], v10 offset:24688
	ds_read_b128 v[46:49], v10 offset:28784
	ds_read_b128 v[50:53], v10 offset:32880
	ds_read_b128 v[60:63], v10 offset:36976
	s_waitcnt lgkmcnt(5)
	v_fmac_f32_e32 v114, v2, v212
	v_fmac_f32_e32 v114, v3, v213
	v_fmac_f32_e32 v114, v4, v214
	v_fmac_f32_e32 v114, v5, v215
	v_fmac_f32_e32 v115, v6, v212
	v_fmac_f32_e32 v115, v7, v213
	v_fmac_f32_e32 v115, v8, v214
	v_fmac_f32_e32 v115, v9, v215
	v_fmac_f32_e32 v116, v22, v212
	v_fmac_f32_e32 v116, v23, v213
	v_fmac_f32_e32 v116, v24, v214
	v_fmac_f32_e32 v116, v25, v215
	v_fmac_f32_e32 v117, v30, v212
	v_fmac_f32_e32 v117, v31, v213
	v_fmac_f32_e32 v117, v32, v214
	v_fmac_f32_e32 v117, v33, v215
	v_fmac_f32_e32 v118, v34, v212
	v_fmac_f32_e32 v118, v35, v213
	v_fmac_f32_e32 v118, v36, v214
	v_fmac_f32_e32 v118, v37, v215
	s_waitcnt lgkmcnt(0)
	v_fmac_f32_e32 v119, v38, v212
	v_fmac_f32_e32 v119, v39, v213
	v_fmac_f32_e32 v119, v40, v214
	v_fmac_f32_e32 v119, v41, v215
	v_fmac_f32_e32 v120, v42, v212
	v_fmac_f32_e32 v120, v43, v213
	v_fmac_f32_e32 v120, v44, v214
	v_fmac_f32_e32 v120, v45, v215
	v_fmac_f32_e32 v121, v46, v212
	v_fmac_f32_e32 v121, v47, v213
	v_fmac_f32_e32 v121, v48, v214
	v_fmac_f32_e32 v121, v49, v215
	v_fmac_f32_e32 v112, v50, v212
	v_fmac_f32_e32 v112, v51, v213
	v_fmac_f32_e32 v112, v52, v214
	v_fmac_f32_e32 v112, v53, v215
	v_fmac_f32_e32 v113, v60, v212
	v_fmac_f32_e32 v113, v61, v213
	v_fmac_f32_e32 v113, v62, v214
	v_fmac_f32_e32 v113, v63, v215
	global_load_dword v200, v11, s[18:19] nt
	s_add_u32 s18, s18, 0x9000
	s_addc_u32 s19, s19, 0
	global_load_dword v201, v11, s[18:19] nt
	s_add_u32 s18, s18, 0x9000
	s_addc_u32 s19, s19, 0
	global_load_dword v202, v11, s[18:19] nt
	s_add_u32 s18, s18, 0x9000
	s_addc_u32 s19, s19, 0
	global_load_dword v203, v11, s[18:19] nt
	s_add_u32 s18, s18, 0x9000
	s_addc_u32 s19, s19, 0
	global_load_dword v204, v11, s[18:19] nt
	s_add_u32 s18, s18, 0x9000
	s_addc_u32 s19, s19, 0
	global_load_dword v205, v11, s[18:19] nt
	s_add_u32 s18, s18, 0x9000
	s_addc_u32 s19, s19, 0
	global_load_dword v206, v11, s[18:19] nt
	s_add_u32 s18, s18, 0x9000
	s_addc_u32 s19, s19, 0
	global_load_dword v207, v11, s[18:19] nt
	s_add_u32 s18, s18, 0x9000
	s_addc_u32 s19, s19, 0
	global_load_dword v208, v11, s[18:19] nt
	s_add_u32 s18, s18, 0x9000
	s_addc_u32 s19, s19, 0
	global_load_dword v209, v11, s[18:19] nt
	s_add_u32 s18, s18, 0x9000
	s_addc_u32 s19, s19, 0
	global_load_dword v210, v11, s[18:19] nt
	s_add_u32 s18, s18, 0x9000
	s_addc_u32 s19, s19, 0
	global_load_dword v211, v11, s[18:19] nt
	s_add_u32 s18, s18, 0x9000
	s_addc_u32 s19, s19, 0
	global_load_dword v212, v11, s[18:19] nt
	s_add_u32 s18, s18, 0x9000
	s_addc_u32 s19, s19, 0
	global_load_dword v213, v11, s[18:19] nt
	s_add_u32 s18, s18, 0x9000
	s_addc_u32 s19, s19, 0
	global_load_dword v214, v11, s[18:19] nt
	s_add_u32 s18, s18, 0x9000
	s_addc_u32 s19, s19, 0
	global_load_dword v215, v11, s[18:19] nt
	s_add_u32 s18, s18, 0x9000
	s_addc_u32 s19, s19, 0
	s_waitcnt vmcnt(32)
	ds_read_b128 v[2:5], v10 offset:128
	ds_read_b128 v[6:9], v10 offset:4224
	ds_read_b128 v[22:25], v10 offset:8320
	ds_read_b128 v[30:33], v10 offset:12416
	ds_read_b128 v[34:37], v10 offset:16512
	ds_read_b128 v[38:41], v10 offset:20608
	ds_read_b128 v[42:45], v10 offset:24704
	ds_read_b128 v[46:49], v10 offset:28800
	ds_read_b128 v[50:53], v10 offset:32896
	ds_read_b128 v[60:63], v10 offset:36992
	s_waitcnt lgkmcnt(5)
; #define LAS __attribute__((address_space(3)))
; DI void adaln_layer(const Frame& F, int l, int b_idx, int b_cnt) {
;     ...
;         for (int kb = k0; kb < k0 + 128; kb += 16) {
;             float wv[16];
; #pragma unroll
;             for (int i = 0; i < 16; ++i) { wv[i] = __builtin_nontemporal_load(wp_); wp_ += MODW; }
; #pragma unroll
;             for (int i = 0; i < 16; i += 4) {
; #pragma unroll
;                 for (int s = 0; s < NSEQ; ++s) { const f32x4 c4 = *(const LAS f32x4*)(sc + s * DM + kb + i); acc[s] += (c4[0] * wv[i] + c4[1] * wv[i + 1]) + (c4[2] * wv[i + 2] + c4[3] * wv[i + 3]); } }
	v_fmac_f32_e32 v114, v2, v216
	v_fmac_f32_e32 v114, v3, v217
	v_fmac_f32_e32 v114, v4, v218
	v_fmac_f32_e32 v114, v5, v236
	v_fmac_f32_e32 v115, v6, v216
	v_fmac_f32_e32 v115, v7, v217
	v_fmac_f32_e32 v115, v8, v218
	v_fmac_f32_e32 v115, v9, v236
	v_fmac_f32_e32 v116, v22, v216
	v_fmac_f32_e32 v116, v23, v217
	v_fmac_f32_e32 v116, v24, v218
	v_fmac_f32_e32 v116, v25, v236
	v_fmac_f32_e32 v117, v30, v216
	v_fmac_f32_e32 v117, v31, v217
	v_fmac_f32_e32 v117, v32, v218
	v_fmac_f32_e32 v117, v33, v236
	v_fmac_f32_e32 v118, v34, v216
	v_fmac_f32_e32 v118, v35, v217
	v_fmac_f32_e32 v118, v36, v218
	v_fmac_f32_e32 v118, v37, v236
	ds_read_b128 v[2:5], v10 offset:144
	ds_read_b128 v[6:9], v10 offset:4240
	ds_read_b128 v[22:25], v10 offset:8336
	ds_read_b128 v[30:33], v10 offset:12432
	ds_read_b128 v[34:37], v10 offset:16528
	s_waitcnt lgkmcnt(5)
	v_fmac_f32_e32 v119, v38, v216
	v_fmac_f32_e32 v119, v39, v217
	v_fmac_f32_e32 v119, v40, v218
	v_fmac_f32_e32 v119, v41, v236
	v_fmac_f32_e32 v120, v42, v216
	v_fmac_f32_e32 v120, v43, v217
	v_fmac_f32_e32 v120, v44, v218
	v_fmac_f32_e32 v120, v45, v236
	v_fmac_f32_e32 v121, v46, v216
	v_fmac_f32_e32 v121, v47, v217
	v_fmac_f32_e32 v121, v48, v218
	v_fmac_f32_e32 v121, v49, v236
	v_fmac_f32_e32 v112, v50, v216
	v_fmac_f32_e32 v112, v51, v217
	v_fmac_f32_e32 v112, v52, v218
	v_fmac_f32_e32 v112, v53, v236
	v_fmac_f32_e32 v113, v60, v216
	v_fmac_f32_e32 v113, v61, v217
	v_fmac_f32_e32 v113, v62, v218
	v_fmac_f32_e32 v113, v63, v236
	ds_read_b128 v[38:41], v10 offset:20624
	ds_read_b128 v[42:45], v10 offset:24720
	ds_read_b128 v[46:49], v10 offset:28816
	ds_read_b128 v[50:53], v10 offset:32912
	ds_read_b128 v[60:63], v10 offset:37008
	s_waitcnt lgkmcnt(5)
	v_fmac_f32_e32 v114, v2, v237
	v_fmac_f32_e32 v114, v3, v238
	v_fmac_f32_e32 v114, v4, v239
	v_fmac_f32_e32 v114, v5, v240
	v_fmac_f32_e32 v115, v6, v237
	v_fmac_f32_e32 v115, v7, v238
	v_fmac_f32_e32 v115, v8, v239
	v_fmac_f32_e32 v115, v9, v240
	v_fmac_f32_e32 v116, v22, v237
	v_fmac_f32_e32 v116, v23, v238
	v_fmac_f32_e32 v116, v24, v239
	v_fmac_f32_e32 v116, v25, v240
	v_fmac_f32_e32 v117, v30, v237
	v_fmac_f32_e32 v117, v31, v238
	v_fmac_f32_e32 v117, v32, v239
	v_fmac_f32_e32 v117, v33, v240
	v_fmac_f32_e32 v118, v34, v237
	v_fmac_f32_e32 v118, v35, v238
	v_fmac_f32_e32 v118, v36, v239
	v_fmac_f32_e32 v118, v37, v240
	ds_read_b128 v[2:5], v10 offset:160
	ds_read_b128 v[6:9], v10 offset:4256
	ds_read_b128 v[22:25], v10 offset:8352
	ds_read_b128 v[30:33], v10 offset:12448
	ds_read_b128 v[34:37], v10 offset:16544
	s_waitcnt lgkmcnt(5)
	v_fmac_f32_e32 v119, v38, v237
	v_fmac_f32_e32 v119, v39, v238
	v_fmac_f32_e32 v119, v40, v239
	v_fmac_f32_e32 v119, v41, v240
	v_fmac_f32_e32 v120, v42, v237
	v_fmac_f32_e32 v120, v43, v238
	v_fmac_f32_e32 v120, v44, v239
	v_fmac_f32_e32 v120, v45, v240
	v_fmac_f32_e32 v121, v46, v237
	v_fmac_f32_e32 v121, v47, v238
	v_fmac_f32_e32 v121, v48, v239
	v_fmac_f32_e32 v121, v49, v240
	v_fmac_f32_e32 v112, v50, v237
	v_fmac_f32_e32 v112, v51, v238
	v_fmac_f32_e32 v112, v52, v239
	v_fmac_f32_e32 v112, v53, v240
	v_fmac_f32_e32 v113, v60, v237
	v_fmac_f32_e32 v113, v61, v238
	v_fmac_f32_e32 v113, v62, v239
	v_fmac_f32_e32 v113, v63, v240
	ds_read_b128 v[38:41], v10 offset:20640
	ds_read_b128 v[42:45], v10 offset:24736
	ds_read_b128 v[46:49], v10 offset:28832
	ds_read_b128 v[50:53], v10 offset:32928
	ds_read_b128 v[60:63], v10 offset:37024
	s_waitcnt lgkmcnt(5)
	v_fmac_f32_e32 v114, v2, v241
	v_fmac_f32_e32 v114, v3, v242
	v_fmac_f32_e32 v114, v4, v243
	v_fmac_f32_e32 v114, v5, v244
	v_fmac_f32_e32 v115, v6, v241
	v_fmac_f32_e32 v115, v7, v242
	v_fmac_f32_e32 v115, v8, v243
	v_fmac_f32_e32 v115, v9, v244
	v_fmac_f32_e32 v116, v22, v241
	v_fmac_f32_e32 v116, v23, v242
	v_fmac_f32_e32 v116, v24, v243
	v_fmac_f32_e32 v116, v25, v244
	v_fmac_f32_e32 v117, v30, v241
	v_fmac_f32_e32 v117, v31, v242
	v_fmac_f32_e32 v117, v32, v243
	v_fmac_f32_e32 v117, v33, v244
	v_fmac_f32_e32 v118, v34, v241
	v_fmac_f32_e32 v118, v35, v242
	v_fmac_f32_e32 v118, v36, v243
	v_fmac_f32_e32 v118, v37, v244
	ds_read_b128 v[2:5], v10 offset:176
	ds_read_b128 v[6:9], v10 offset:4272
	ds_read_b128 v[22:25], v10 offset:8368
	ds_read_b128 v[30:33], v10 offset:12464
	ds_read_b128 v[34:37], v10 offset:16560
	s_waitcnt lgkmcnt(5)
	v_fmac_f32_e32 v119, v38, v241
	v_fmac_f32_e32 v119, v39, v242
	v_fmac_f32_e32 v119, v40, v243
	v_fmac_f32_e32 v119, v41, v244
	v_fmac_f32_e32 v120, v42, v241
	v_fmac_f32_e32 v120, v43, v242
	v_fmac_f32_e32 v120, v44, v243
	v_fmac_f32_e32 v120, v45, v244
	v_fmac_f32_e32 v121, v46, v241
	v_fmac_f32_e32 v121, v47, v242
	v_fmac_f32_e32 v121, v48, v243
	v_fmac_f32_e32 v121, v49, v244
	v_fmac_f32_e32 v112, v50, v241
	v_fmac_f32_e32 v112, v51, v242
	v_fmac_f32_e32 v112, v52, v243
	v_fmac_f32_e32 v112, v53, v244
	v_fmac_f32_e32 v113, v60, v241
	v_fmac_f32_e32 v113, v61, v242
	v_fmac_f32_e32 v113, v62, v243
	v_fmac_f32_e32 v113, v63, v244
	ds_read_b128 v[38:41], v10 offset:20656
	ds_read_b128 v[42:45], v10 offset:24752
	ds_read_b128 v[46:49], v10 offset:28848
	ds_read_b128 v[50:53], v10 offset:32944
	ds_read_b128 v[60:63], v10 offset:37040
	s_waitcnt lgkmcnt(5)
	v_fmac_f32_e32 v114, v2, v245
	v_fmac_f32_e32 v114, v3, v248
	v_fmac_f32_e32 v114, v4, v249
	v_fmac_f32_e32 v114, v5, v250
	v_fmac_f32_e32 v115, v6, v245
	v_fmac_f32_e32 v115, v7, v248
	v_fmac_f32_e32 v115, v8, v249
	v_fmac_f32_e32 v115, v9, v250
	v_fmac_f32_e32 v116, v22, v245
	v_fmac_f32_e32 v116, v23, v248
	v_fmac_f32_e32 v116, v24, v249
	v_fmac_f32_e32 v116, v25, v250
	v_fmac_f32_e32 v117, v30, v245
	v_fmac_f32_e32 v117, v31, v248
	v_fmac_f32_e32 v117, v32, v249
	v_fmac_f32_e32 v117, v33, v250
	v_fmac_f32_e32 v118, v34, v245
	v_fmac_f32_e32 v118, v35, v248
	v_fmac_f32_e32 v118, v36, v249
	v_fmac_f32_e32 v118, v37, v250
	s_waitcnt lgkmcnt(0)
; #define LAS __attribute__((address_space(3)))
; DI void adaln_layer(const Frame& F, int l, int b_idx, int b_cnt) {
;     ...
;         for (int kb = k0; kb < k0 + 128; kb += 16) {
;             float wv[16];
; #pragma unroll
;             for (int i = 0; i < 16; ++i) { wv[i] = __builtin_nontemporal_load(wp_); wp_ += MODW; }
; #pragma unroll
;             for (int i = 0; i < 16; i += 4) {
; #pragma unroll
;                 for (int s = 0; s < NSEQ; ++s) { const f32x4 c4 = *(const LAS f32x4*)(sc + s * DM + kb + i); acc[s] += (c4[0] * wv[i] + c4[1] * wv[i + 1]) + (c4[2] * wv[i + 2] + c4[3] * wv[i + 3]); } }
	v_fmac_f32_e32 v119, v38, v245
	v_fmac_f32_e32 v119, v39, v248
	v_fmac_f32_e32 v119, v40, v249
	v_fmac_f32_e32 v119, v41, v250
	v_fmac_f32_e32 v120, v42, v245
	v_fmac_f32_e32 v120, v43, v248
	v_fmac_f32_e32 v120, v44, v249
	v_fmac_f32_e32 v120, v45, v250
	v_fmac_f32_e32 v121, v46, v245
	v_fmac_f32_e32 v121, v47, v248
	v_fmac_f32_e32 v121, v48, v249
	v_fmac_f32_e32 v121, v49, v250
	v_fmac_f32_e32 v112, v50, v245
	v_fmac_f32_e32 v112, v51, v248
	v_fmac_f32_e32 v112, v52, v249
	v_fmac_f32_e32 v112, v53, v250
	v_fmac_f32_e32 v113, v60, v245
	v_fmac_f32_e32 v113, v61, v248
	v_fmac_f32_e32 v113, v62, v249
	v_fmac_f32_e32 v113, v63, v250
	global_load_dword v216, v11, s[18:19] nt
	s_add_u32 s18, s18, 0x9000
	s_addc_u32 s19, s19, 0
	global_load_dword v217, v11, s[18:19] nt
	s_add_u32 s18, s18, 0x9000
	s_addc_u32 s19, s19, 0
	global_load_dword v218, v11, s[18:19] nt
	s_add_u32 s18, s18, 0x9000
	s_addc_u32 s19, s19, 0
	global_load_dword v236, v11, s[18:19] nt
	s_add_u32 s18, s18, 0x9000
	s_addc_u32 s19, s19, 0
	global_load_dword v237, v11, s[18:19] nt
	s_add_u32 s18, s18, 0x9000
	s_addc_u32 s19, s19, 0
	global_load_dword v238, v11, s[18:19] nt
	s_add_u32 s18, s18, 0x9000
	s_addc_u32 s19, s19, 0
	global_load_dword v239, v11, s[18:19] nt
	s_add_u32 s18, s18, 0x9000
	s_addc_u32 s19, s19, 0
	global_load_dword v240, v11, s[18:19] nt
	s_add_u32 s18, s18, 0x9000
	s_addc_u32 s19, s19, 0
	global_load_dword v241, v11, s[18:19] nt
	s_add_u32 s18, s18, 0x9000
	s_addc_u32 s19, s19, 0
	global_load_dword v242, v11, s[18:19] nt
	s_add_u32 s18, s18, 0x9000
	s_addc_u32 s19, s19, 0
	global_load_dword v243, v11, s[18:19] nt
	s_add_u32 s18, s18, 0x9000
	s_addc_u32 s19, s19, 0
	global_load_dword v244, v11, s[18:19] nt
	s_add_u32 s18, s18, 0x9000
	s_addc_u32 s19, s19, 0
	global_load_dword v245, v11, s[18:19] nt
	s_add_u32 s18, s18, 0x9000
	s_addc_u32 s19, s19, 0
	global_load_dword v248, v11, s[18:19] nt
	s_add_u32 s18, s18, 0x9000
	s_addc_u32 s19, s19, 0
	global_load_dword v249, v11, s[18:19] nt
	s_add_u32 s18, s18, 0x9000
	s_addc_u32 s19, s19, 0
	global_load_dword v250, v11, s[18:19] nt
	s_add_u32 s18, s18, 0x9000
	s_addc_u32 s19, s19, 0
	s_waitcnt vmcnt(32)
	ds_read_b128 v[2:5], v10 offset:192
	ds_read_b128 v[6:9], v10 offset:4288
	ds_read_b128 v[22:25], v10 offset:8384
	ds_read_b128 v[30:33], v10 offset:12480
	ds_read_b128 v[34:37], v10 offset:16576
	ds_read_b128 v[38:41], v10 offset:20672
	ds_read_b128 v[42:45], v10 offset:24768
	ds_read_b128 v[46:49], v10 offset:28864
	ds_read_b128 v[50:53], v10 offset:32960
	ds_read_b128 v[60:63], v10 offset:37056
	s_waitcnt lgkmcnt(5)
	v_fmac_f32_e32 v114, v2, v184
	v_fmac_f32_e32 v114, v3, v185
	v_fmac_f32_e32 v114, v4, v186
	v_fmac_f32_e32 v114, v5, v187
	v_fmac_f32_e32 v115, v6, v184
	v_fmac_f32_e32 v115, v7, v185
	v_fmac_f32_e32 v115, v8, v186
	v_fmac_f32_e32 v115, v9, v187
	v_fmac_f32_e32 v116, v22, v184
	v_fmac_f32_e32 v116, v23, v185
	v_fmac_f32_e32 v116, v24, v186
	v_fmac_f32_e32 v116, v25, v187
	v_fmac_f32_e32 v117, v30, v184
	v_fmac_f32_e32 v117, v31, v185
	v_fmac_f32_e32 v117, v32, v186
	v_fmac_f32_e32 v117, v33, v187
	v_fmac_f32_e32 v118, v34, v184
	v_fmac_f32_e32 v118, v35, v185
	v_fmac_f32_e32 v118, v36, v186
	v_fmac_f32_e32 v118, v37, v187
	ds_read_b128 v[2:5], v10 offset:208
	ds_read_b128 v[6:9], v10 offset:4304
	ds_read_b128 v[22:25], v10 offset:8400
	ds_read_b128 v[30:33], v10 offset:12496
	ds_read_b128 v[34:37], v10 offset:16592
	s_waitcnt lgkmcnt(5)
	v_fmac_f32_e32 v119, v38, v184
	v_fmac_f32_e32 v119, v39, v185
	v_fmac_f32_e32 v119, v40, v186
	v_fmac_f32_e32 v119, v41, v187
	v_fmac_f32_e32 v120, v42, v184
	v_fmac_f32_e32 v120, v43, v185
	v_fmac_f32_e32 v120, v44, v186
	v_fmac_f32_e32 v120, v45, v187
	v_fmac_f32_e32 v121, v46, v184
	v_fmac_f32_e32 v121, v47, v185
	v_fmac_f32_e32 v121, v48, v186
	v_fmac_f32_e32 v121, v49, v187
	v_fmac_f32_e32 v112, v50, v184
	v_fmac_f32_e32 v112, v51, v185
	v_fmac_f32_e32 v112, v52, v186
	v_fmac_f32_e32 v112, v53, v187
	v_fmac_f32_e32 v113, v60, v184
	v_fmac_f32_e32 v113, v61, v185
	v_fmac_f32_e32 v113, v62, v186
	v_fmac_f32_e32 v113, v63, v187
	ds_read_b128 v[38:41], v10 offset:20688
	ds_read_b128 v[42:45], v10 offset:24784
	ds_read_b128 v[46:49], v10 offset:28880
	ds_read_b128 v[50:53], v10 offset:32976
	ds_read_b128 v[60:63], v10 offset:37072
	s_waitcnt lgkmcnt(5)
	v_fmac_f32_e32 v114, v2, v188
	v_fmac_f32_e32 v114, v3, v189
	v_fmac_f32_e32 v114, v4, v190
	v_fmac_f32_e32 v114, v5, v191
	v_fmac_f32_e32 v115, v6, v188
	v_fmac_f32_e32 v115, v7, v189
	v_fmac_f32_e32 v115, v8, v190
	v_fmac_f32_e32 v115, v9, v191
	v_fmac_f32_e32 v116, v22, v188
	v_fmac_f32_e32 v116, v23, v189
	v_fmac_f32_e32 v116, v24, v190
	v_fmac_f32_e32 v116, v25, v191
	v_fmac_f32_e32 v117, v30, v188
	v_fmac_f32_e32 v117, v31, v189
	v_fmac_f32_e32 v117, v32, v190
	v_fmac_f32_e32 v117, v33, v191
	v_fmac_f32_e32 v118, v34, v188
	v_fmac_f32_e32 v118, v35, v189
	v_fmac_f32_e32 v118, v36, v190
	v_fmac_f32_e32 v118, v37, v191
	ds_read_b128 v[2:5], v10 offset:224
	ds_read_b128 v[6:9], v10 offset:4320
	ds_read_b128 v[22:25], v10 offset:8416
	ds_read_b128 v[30:33], v10 offset:12512
	ds_read_b128 v[34:37], v10 offset:16608
	s_waitcnt lgkmcnt(5)
	v_fmac_f32_e32 v119, v38, v188
	v_fmac_f32_e32 v119, v39, v189
	v_fmac_f32_e32 v119, v40, v190
	v_fmac_f32_e32 v119, v41, v191
	v_fmac_f32_e32 v120, v42, v188
	v_fmac_f32_e32 v120, v43, v189
	v_fmac_f32_e32 v120, v44, v190
	v_fmac_f32_e32 v120, v45, v191
	v_fmac_f32_e32 v121, v46, v188
	v_fmac_f32_e32 v121, v47, v189
	v_fmac_f32_e32 v121, v48, v190
	v_fmac_f32_e32 v121, v49, v191
	v_fmac_f32_e32 v112, v50, v188
	v_fmac_f32_e32 v112, v51, v189
	v_fmac_f32_e32 v112, v52, v190
	v_fmac_f32_e32 v112, v53, v191
	v_fmac_f32_e32 v113, v60, v188
	v_fmac_f32_e32 v113, v61, v189
	v_fmac_f32_e32 v113, v62, v190
	v_fmac_f32_e32 v113, v63, v191
	ds_read_b128 v[38:41], v10 offset:20704
	ds_read_b128 v[42:45], v10 offset:24800
	ds_read_b128 v[46:49], v10 offset:28896
	ds_read_b128 v[50:53], v10 offset:32992
	ds_read_b128 v[60:63], v10 offset:37088
	s_waitcnt lgkmcnt(5)
; #define LAS __attribute__((address_space(3)))
; DI void adaln_layer(const Frame& F, int l, int b_idx, int b_cnt) {
;     ...
;         for (int kb = k0; kb < k0 + 128; kb += 16) {
;             float wv[16];
; #pragma unroll
;             for (int i = 0; i < 16; ++i) { wv[i] = __builtin_nontemporal_load(wp_); wp_ += MODW; }
; #pragma unroll
;             for (int i = 0; i < 16; i += 4) {
; #pragma unroll
;                 for (int s = 0; s < NSEQ; ++s) { const f32x4 c4 = *(const LAS f32x4*)(sc + s * DM + kb + i); acc[s] += (c4[0] * wv[i] + c4[1] * wv[i + 1]) + (c4[2] * wv[i + 2] + c4[3] * wv[i + 3]); } }
	v_fmac_f32_e32 v114, v2, v192
	v_fmac_f32_e32 v114, v3, v193
	v_fmac_f32_e32 v114, v4, v194
	v_fmac_f32_e32 v114, v5, v195
	v_fmac_f32_e32 v115, v6, v192
	v_fmac_f32_e32 v115, v7, v193
	v_fmac_f32_e32 v115, v8, v194
	v_fmac_f32_e32 v115, v9, v195
	v_fmac_f32_e32 v116, v22, v192
	v_fmac_f32_e32 v116, v23, v193
	v_fmac_f32_e32 v116, v24, v194
	v_fmac_f32_e32 v116, v25, v195
	v_fmac_f32_e32 v117, v30, v192
	v_fmac_f32_e32 v117, v31, v193
	v_fmac_f32_e32 v117, v32, v194
	v_fmac_f32_e32 v117, v33, v195
	v_fmac_f32_e32 v118, v34, v192
	v_fmac_f32_e32 v118, v35, v193
	v_fmac_f32_e32 v118, v36, v194
	v_fmac_f32_e32 v118, v37, v195
	ds_read_b128 v[2:5], v10 offset:240
	ds_read_b128 v[6:9], v10 offset:4336
	ds_read_b128 v[22:25], v10 offset:8432
	ds_read_b128 v[30:33], v10 offset:12528
	ds_read_b128 v[34:37], v10 offset:16624
	s_waitcnt lgkmcnt(5)
	v_fmac_f32_e32 v119, v38, v192
	v_fmac_f32_e32 v119, v39, v193
	v_fmac_f32_e32 v119, v40, v194
	v_fmac_f32_e32 v119, v41, v195
	v_fmac_f32_e32 v120, v42, v192
	v_fmac_f32_e32 v120, v43, v193
	v_fmac_f32_e32 v120, v44, v194
	v_fmac_f32_e32 v120, v45, v195
	v_fmac_f32_e32 v121, v46, v192
	v_fmac_f32_e32 v121, v47, v193
	v_fmac_f32_e32 v121, v48, v194
	v_fmac_f32_e32 v121, v49, v195
	v_fmac_f32_e32 v112, v50, v192
	v_fmac_f32_e32 v112, v51, v193
	v_fmac_f32_e32 v112, v52, v194
	v_fmac_f32_e32 v112, v53, v195
	v_fmac_f32_e32 v113, v60, v192
	v_fmac_f32_e32 v113, v61, v193
	v_fmac_f32_e32 v113, v62, v194
	v_fmac_f32_e32 v113, v63, v195
	ds_read_b128 v[38:41], v10 offset:20720
	ds_read_b128 v[42:45], v10 offset:24816
	ds_read_b128 v[46:49], v10 offset:28912
	ds_read_b128 v[50:53], v10 offset:33008
	ds_read_b128 v[60:63], v10 offset:37104
	s_waitcnt lgkmcnt(5)
	v_fmac_f32_e32 v114, v2, v196
	v_fmac_f32_e32 v114, v3, v197
	v_fmac_f32_e32 v114, v4, v198
	v_fmac_f32_e32 v114, v5, v199
	v_fmac_f32_e32 v115, v6, v196
	v_fmac_f32_e32 v115, v7, v197
	v_fmac_f32_e32 v115, v8, v198
	v_fmac_f32_e32 v115, v9, v199
	v_fmac_f32_e32 v116, v22, v196
	v_fmac_f32_e32 v116, v23, v197
	v_fmac_f32_e32 v116, v24, v198
	v_fmac_f32_e32 v116, v25, v199
	v_fmac_f32_e32 v117, v30, v196
	v_fmac_f32_e32 v117, v31, v197
	v_fmac_f32_e32 v117, v32, v198
	v_fmac_f32_e32 v117, v33, v199
	v_fmac_f32_e32 v118, v34, v196
	v_fmac_f32_e32 v118, v35, v197
	v_fmac_f32_e32 v118, v36, v198
	v_fmac_f32_e32 v118, v37, v199
	s_waitcnt lgkmcnt(0)
	v_fmac_f32_e32 v119, v38, v196
	v_fmac_f32_e32 v119, v39, v197
	v_fmac_f32_e32 v119, v40, v198
	v_fmac_f32_e32 v119, v41, v199
	v_fmac_f32_e32 v120, v42, v196
	v_fmac_f32_e32 v120, v43, v197
	v_fmac_f32_e32 v120, v44, v198
	v_fmac_f32_e32 v120, v45, v199
	v_fmac_f32_e32 v121, v46, v196
	v_fmac_f32_e32 v121, v47, v197
	v_fmac_f32_e32 v121, v48, v198
	v_fmac_f32_e32 v121, v49, v199
	v_fmac_f32_e32 v112, v50, v196
	v_fmac_f32_e32 v112, v51, v197
	v_fmac_f32_e32 v112, v52, v198
	v_fmac_f32_e32 v112, v53, v199
	v_fmac_f32_e32 v113, v60, v196
	v_fmac_f32_e32 v113, v61, v197
	v_fmac_f32_e32 v113, v62, v198
	v_fmac_f32_e32 v113, v63, v199
	global_load_dword v184, v11, s[18:19] nt
	s_add_u32 s18, s18, 0x9000
	s_addc_u32 s19, s19, 0
	global_load_dword v185, v11, s[18:19] nt
	s_add_u32 s18, s18, 0x9000
	s_addc_u32 s19, s19, 0
	global_load_dword v186, v11, s[18:19] nt
	s_add_u32 s18, s18, 0x9000
	s_addc_u32 s19, s19, 0
	global_load_dword v187, v11, s[18:19] nt
	s_add_u32 s18, s18, 0x9000
	s_addc_u32 s19, s19, 0
	global_load_dword v188, v11, s[18:19] nt
	s_add_u32 s18, s18, 0x9000
	s_addc_u32 s19, s19, 0
	global_load_dword v189, v11, s[18:19] nt
	s_add_u32 s18, s18, 0x9000
	s_addc_u32 s19, s19, 0
	global_load_dword v190, v11, s[18:19] nt
	s_add_u32 s18, s18, 0x9000
	s_addc_u32 s19, s19, 0
	global_load_dword v191, v11, s[18:19] nt
	s_add_u32 s18, s18, 0x9000
	s_addc_u32 s19, s19, 0
	global_load_dword v192, v11, s[18:19] nt
	s_add_u32 s18, s18, 0x9000
	s_addc_u32 s19, s19, 0
	global_load_dword v193, v11, s[18:19] nt
	s_add_u32 s18, s18, 0x9000
	s_addc_u32 s19, s19, 0
	global_load_dword v194, v11, s[18:19] nt
	s_add_u32 s18, s18, 0x9000
	s_addc_u32 s19, s19, 0
	global_load_dword v195, v11, s[18:19] nt
	s_add_u32 s18, s18, 0x9000
	s_addc_u32 s19, s19, 0
	global_load_dword v196, v11, s[18:19] nt
	s_add_u32 s18, s18, 0x9000
	s_addc_u32 s19, s19, 0
	global_load_dword v197, v11, s[18:19] nt
	s_add_u32 s18, s18, 0x9000
	s_addc_u32 s19, s19, 0
	global_load_dword v198, v11, s[18:19] nt
	s_add_u32 s18, s18, 0x9000
	s_addc_u32 s19, s19, 0
	global_load_dword v199, v11, s[18:19] nt
	s_add_u32 s18, s18, 0x9000
	s_addc_u32 s19, s19, 0
	s_waitcnt vmcnt(32)
	ds_read_b128 v[2:5], v10 offset:256
	ds_read_b128 v[6:9], v10 offset:4352
	ds_read_b128 v[22:25], v10 offset:8448
	ds_read_b128 v[30:33], v10 offset:12544
	ds_read_b128 v[34:37], v10 offset:16640
	ds_read_b128 v[38:41], v10 offset:20736
	ds_read_b128 v[42:45], v10 offset:24832
	ds_read_b128 v[46:49], v10 offset:28928
	ds_read_b128 v[50:53], v10 offset:33024
	ds_read_b128 v[60:63], v10 offset:37120
	s_waitcnt lgkmcnt(5)
	v_fmac_f32_e32 v114, v2, v200
	v_fmac_f32_e32 v114, v3, v201
	v_fmac_f32_e32 v114, v4, v202
	v_fmac_f32_e32 v114, v5, v203
	v_fmac_f32_e32 v115, v6, v200
	v_fmac_f32_e32 v115, v7, v201
	v_fmac_f32_e32 v115, v8, v202
	v_fmac_f32_e32 v115, v9, v203
	v_fmac_f32_e32 v116, v22, v200
	v_fmac_f32_e32 v116, v23, v201
	v_fmac_f32_e32 v116, v24, v202
	v_fmac_f32_e32 v116, v25, v203
	v_fmac_f32_e32 v117, v30, v200
	v_fmac_f32_e32 v117, v31, v201
	v_fmac_f32_e32 v117, v32, v202
	v_fmac_f32_e32 v117, v33, v203
	v_fmac_f32_e32 v118, v34, v200
	v_fmac_f32_e32 v118, v35, v201
	v_fmac_f32_e32 v118, v36, v202
	v_fmac_f32_e32 v118, v37, v203
	ds_read_b128 v[2:5], v10 offset:272
	ds_read_b128 v[6:9], v10 offset:4368
	ds_read_b128 v[22:25], v10 offset:8464
	ds_read_b128 v[30:33], v10 offset:12560
	ds_read_b128 v[34:37], v10 offset:16656
	s_waitcnt lgkmcnt(5)
; #define LAS __attribute__((address_space(3)))
; DI void adaln_layer(const Frame& F, int l, int b_idx, int b_cnt) {
;     ...
;         for (int kb = k0; kb < k0 + 128; kb += 16) {
;             float wv[16];
; #pragma unroll
;             for (int i = 0; i < 16; ++i) { wv[i] = __builtin_nontemporal_load(wp_); wp_ += MODW; }
; #pragma unroll
;             for (int i = 0; i < 16; i += 4) {
; #pragma unroll
;                 for (int s = 0; s < NSEQ; ++s) { const f32x4 c4 = *(const LAS f32x4*)(sc + s * DM + kb + i); acc[s] += (c4[0] * wv[i] + c4[1] * wv[i + 1]) + (c4[2] * wv[i + 2] + c4[3] * wv[i + 3]); } }
	v_fmac_f32_e32 v119, v38, v200
	v_fmac_f32_e32 v119, v39, v201
	v_fmac_f32_e32 v119, v40, v202
	v_fmac_f32_e32 v119, v41, v203
	v_fmac_f32_e32 v120, v42, v200
	v_fmac_f32_e32 v120, v43, v201
	v_fmac_f32_e32 v120, v44, v202
	v_fmac_f32_e32 v120, v45, v203
	v_fmac_f32_e32 v121, v46, v200
	v_fmac_f32_e32 v121, v47, v201
	v_fmac_f32_e32 v121, v48, v202
	v_fmac_f32_e32 v121, v49, v203
	v_fmac_f32_e32 v112, v50, v200
	v_fmac_f32_e32 v112, v51, v201
	v_fmac_f32_e32 v112, v52, v202
	v_fmac_f32_e32 v112, v53, v203
	v_fmac_f32_e32 v113, v60, v200
	v_fmac_f32_e32 v113, v61, v201
	v_fmac_f32_e32 v113, v62, v202
	v_fmac_f32_e32 v113, v63, v203
	ds_read_b128 v[38:41], v10 offset:20752
	ds_read_b128 v[42:45], v10 offset:24848
	ds_read_b128 v[46:49], v10 offset:28944
	ds_read_b128 v[50:53], v10 offset:33040
	ds_read_b128 v[60:63], v10 offset:37136
	s_waitcnt lgkmcnt(5)
	v_fmac_f32_e32 v114, v2, v204
	v_fmac_f32_e32 v114, v3, v205
	v_fmac_f32_e32 v114, v4, v206
	v_fmac_f32_e32 v114, v5, v207
	v_fmac_f32_e32 v115, v6, v204
	v_fmac_f32_e32 v115, v7, v205
	v_fmac_f32_e32 v115, v8, v206
	v_fmac_f32_e32 v115, v9, v207
	v_fmac_f32_e32 v116, v22, v204
	v_fmac_f32_e32 v116, v23, v205
	v_fmac_f32_e32 v116, v24, v206
	v_fmac_f32_e32 v116, v25, v207
	v_fmac_f32_e32 v117, v30, v204
	v_fmac_f32_e32 v117, v31, v205
	v_fmac_f32_e32 v117, v32, v206
	v_fmac_f32_e32 v117, v33, v207
	v_fmac_f32_e32 v118, v34, v204
	v_fmac_f32_e32 v118, v35, v205
	v_fmac_f32_e32 v118, v36, v206
	v_fmac_f32_e32 v118, v37, v207
	ds_read_b128 v[2:5], v10 offset:288
	ds_read_b128 v[6:9], v10 offset:4384
	ds_read_b128 v[22:25], v10 offset:8480
	ds_read_b128 v[30:33], v10 offset:12576
	ds_read_b128 v[34:37], v10 offset:16672
	s_waitcnt lgkmcnt(5)
	v_fmac_f32_e32 v119, v38, v204
	v_fmac_f32_e32 v119, v39, v205
	v_fmac_f32_e32 v119, v40, v206
	v_fmac_f32_e32 v119, v41, v207
	v_fmac_f32_e32 v120, v42, v204
	v_fmac_f32_e32 v120, v43, v205
	v_fmac_f32_e32 v120, v44, v206
	v_fmac_f32_e32 v120, v45, v207
	v_fmac_f32_e32 v121, v46, v204
	v_fmac_f32_e32 v121, v47, v205
	v_fmac_f32_e32 v121, v48, v206
	v_fmac_f32_e32 v121, v49, v207
	v_fmac_f32_e32 v112, v50, v204
	v_fmac_f32_e32 v112, v51, v205
	v_fmac_f32_e32 v112, v52, v206
	v_fmac_f32_e32 v112, v53, v207
	v_fmac_f32_e32 v113, v60, v204
	v_fmac_f32_e32 v113, v61, v205
	v_fmac_f32_e32 v113, v62, v206
	v_fmac_f32_e32 v113, v63, v207
	ds_read_b128 v[38:41], v10 offset:20768
	ds_read_b128 v[42:45], v10 offset:24864
	ds_read_b128 v[46:49], v10 offset:28960
	ds_read_b128 v[50:53], v10 offset:33056
	ds_read_b128 v[60:63], v10 offset:37152
	s_waitcnt lgkmcnt(5)
	v_fmac_f32_e32 v114, v2, v208
	v_fmac_f32_e32 v114, v3, v209
	v_fmac_f32_e32 v114, v4, v210
	v_fmac_f32_e32 v114, v5, v211
	v_fmac_f32_e32 v115, v6, v208
	v_fmac_f32_e32 v115, v7, v209
	v_fmac_f32_e32 v115, v8, v210
	v_fmac_f32_e32 v115, v9, v211
	v_fmac_f32_e32 v116, v22, v208
	v_fmac_f32_e32 v116, v23, v209
	v_fmac_f32_e32 v116, v24, v210
	v_fmac_f32_e32 v116, v25, v211
	v_fmac_f32_e32 v117, v30, v208
	v_fmac_f32_e32 v117, v31, v209
	v_fmac_f32_e32 v117, v32, v210
	v_fmac_f32_e32 v117, v33, v211
	v_fmac_f32_e32 v118, v34, v208
	v_fmac_f32_e32 v118, v35, v209
	v_fmac_f32_e32 v118, v36, v210
	v_fmac_f32_e32 v118, v37, v211
	ds_read_b128 v[2:5], v10 offset:304
	ds_read_b128 v[6:9], v10 offset:4400
	ds_read_b128 v[22:25], v10 offset:8496
	ds_read_b128 v[30:33], v10 offset:12592
	ds_read_b128 v[34:37], v10 offset:16688
	s_waitcnt lgkmcnt(5)
	v_fmac_f32_e32 v119, v38, v208
	v_fmac_f32_e32 v119, v39, v209
	v_fmac_f32_e32 v119, v40, v210
	v_fmac_f32_e32 v119, v41, v211
	v_fmac_f32_e32 v120, v42, v208
	v_fmac_f32_e32 v120, v43, v209
	v_fmac_f32_e32 v120, v44, v210
	v_fmac_f32_e32 v120, v45, v211
	v_fmac_f32_e32 v121, v46, v208
	v_fmac_f32_e32 v121, v47, v209
	v_fmac_f32_e32 v121, v48, v210
	v_fmac_f32_e32 v121, v49, v211
	v_fmac_f32_e32 v112, v50, v208
	v_fmac_f32_e32 v112, v51, v209
	v_fmac_f32_e32 v112, v52, v210
	v_fmac_f32_e32 v112, v53, v211
	v_fmac_f32_e32 v113, v60, v208
	v_fmac_f32_e32 v113, v61, v209
	v_fmac_f32_e32 v113, v62, v210
	v_fmac_f32_e32 v113, v63, v211
	ds_read_b128 v[38:41], v10 offset:20784
	ds_read_b128 v[42:45], v10 offset:24880
	ds_read_b128 v[46:49], v10 offset:28976
	ds_read_b128 v[50:53], v10 offset:33072
	ds_read_b128 v[60:63], v10 offset:37168
	s_waitcnt lgkmcnt(5)
	v_fmac_f32_e32 v114, v2, v212
	v_fmac_f32_e32 v114, v3, v213
	v_fmac_f32_e32 v114, v4, v214
	v_fmac_f32_e32 v114, v5, v215
	v_fmac_f32_e32 v115, v6, v212
	v_fmac_f32_e32 v115, v7, v213
	v_fmac_f32_e32 v115, v8, v214
	v_fmac_f32_e32 v115, v9, v215
	v_fmac_f32_e32 v116, v22, v212
	v_fmac_f32_e32 v116, v23, v213
	v_fmac_f32_e32 v116, v24, v214
	v_fmac_f32_e32 v116, v25, v215
	v_fmac_f32_e32 v117, v30, v212
	v_fmac_f32_e32 v117, v31, v213
	v_fmac_f32_e32 v117, v32, v214
	v_fmac_f32_e32 v117, v33, v215
	v_fmac_f32_e32 v118, v34, v212
	v_fmac_f32_e32 v118, v35, v213
	v_fmac_f32_e32 v118, v36, v214
	v_fmac_f32_e32 v118, v37, v215
	s_waitcnt lgkmcnt(0)
; #define LAS __attribute__((address_space(3)))
; DI void adaln_layer(const Frame& F, int l, int b_idx, int b_cnt) {
;     ...
;         for (int kb = k0; kb < k0 + 128; kb += 16) {
;             float wv[16];
; #pragma unroll
;             for (int i = 0; i < 16; ++i) { wv[i] = __builtin_nontemporal_load(wp_); wp_ += MODW; }
; #pragma unroll
;             for (int i = 0; i < 16; i += 4) {
; #pragma unroll
;                 for (int s = 0; s < NSEQ; ++s) { const f32x4 c4 = *(const LAS f32x4*)(sc + s * DM + kb + i); acc[s] += (c4[0] * wv[i] + c4[1] * wv[i + 1]) + (c4[2] * wv[i + 2] + c4[3] * wv[i + 3]); } }
	v_fmac_f32_e32 v119, v38, v212
	v_fmac_f32_e32 v119, v39, v213
	v_fmac_f32_e32 v119, v40, v214
	v_fmac_f32_e32 v119, v41, v215
	v_fmac_f32_e32 v120, v42, v212
	v_fmac_f32_e32 v120, v43, v213
	v_fmac_f32_e32 v120, v44, v214
	v_fmac_f32_e32 v120, v45, v215
	v_fmac_f32_e32 v121, v46, v212
	v_fmac_f32_e32 v121, v47, v213
	v_fmac_f32_e32 v121, v48, v214
	v_fmac_f32_e32 v121, v49, v215
	v_fmac_f32_e32 v112, v50, v212
	v_fmac_f32_e32 v112, v51, v213
	v_fmac_f32_e32 v112, v52, v214
	v_fmac_f32_e32 v112, v53, v215
	v_fmac_f32_e32 v113, v60, v212
	v_fmac_f32_e32 v113, v61, v213
	v_fmac_f32_e32 v113, v62, v214
	v_fmac_f32_e32 v113, v63, v215
	global_load_dword v200, v11, s[18:19] nt
	s_add_u32 s18, s18, 0x9000
	s_addc_u32 s19, s19, 0
	global_load_dword v201, v11, s[18:19] nt
	s_add_u32 s18, s18, 0x9000
	s_addc_u32 s19, s19, 0
	global_load_dword v202, v11, s[18:19] nt
	s_add_u32 s18, s18, 0x9000
	s_addc_u32 s19, s19, 0
	global_load_dword v203, v11, s[18:19] nt
	s_add_u32 s18, s18, 0x9000
	s_addc_u32 s19, s19, 0
	global_load_dword v204, v11, s[18:19] nt
	s_add_u32 s18, s18, 0x9000
	s_addc_u32 s19, s19, 0
	global_load_dword v205, v11, s[18:19] nt
	s_add_u32 s18, s18, 0x9000
	s_addc_u32 s19, s19, 0
	global_load_dword v206, v11, s[18:19] nt
	s_add_u32 s18, s18, 0x9000
	s_addc_u32 s19, s19, 0
	global_load_dword v207, v11, s[18:19] nt
	s_add_u32 s18, s18, 0x9000
	s_addc_u32 s19, s19, 0
	global_load_dword v208, v11, s[18:19] nt
	s_add_u32 s18, s18, 0x9000
	s_addc_u32 s19, s19, 0
	global_load_dword v209, v11, s[18:19] nt
	s_add_u32 s18, s18, 0x9000
	s_addc_u32 s19, s19, 0
	global_load_dword v210, v11, s[18:19] nt
	s_add_u32 s18, s18, 0x9000
	s_addc_u32 s19, s19, 0
	global_load_dword v211, v11, s[18:19] nt
	s_add_u32 s18, s18, 0x9000
	s_addc_u32 s19, s19, 0
	global_load_dword v212, v11, s[18:19] nt
	s_add_u32 s18, s18, 0x9000
	s_addc_u32 s19, s19, 0
	global_load_dword v213, v11, s[18:19] nt
	s_add_u32 s18, s18, 0x9000
	s_addc_u32 s19, s19, 0
	global_load_dword v214, v11, s[18:19] nt
	s_add_u32 s18, s18, 0x9000
	s_addc_u32 s19, s19, 0
	global_load_dword v215, v11, s[18:19] nt
	s_add_u32 s18, s18, 0x9000
	s_addc_u32 s19, s19, 0
	s_waitcnt vmcnt(32)
	ds_read_b128 v[2:5], v10 offset:320
	ds_read_b128 v[6:9], v10 offset:4416
	ds_read_b128 v[22:25], v10 offset:8512
	ds_read_b128 v[30:33], v10 offset:12608
	ds_read_b128 v[34:37], v10 offset:16704
	ds_read_b128 v[38:41], v10 offset:20800
	ds_read_b128 v[42:45], v10 offset:24896
	ds_read_b128 v[46:49], v10 offset:28992
	ds_read_b128 v[50:53], v10 offset:33088
	ds_read_b128 v[60:63], v10 offset:37184
	s_waitcnt lgkmcnt(5)
	v_fmac_f32_e32 v114, v2, v216
	v_fmac_f32_e32 v114, v3, v217
	v_fmac_f32_e32 v114, v4, v218
	v_fmac_f32_e32 v114, v5, v236
	v_fmac_f32_e32 v115, v6, v216
	v_fmac_f32_e32 v115, v7, v217
	v_fmac_f32_e32 v115, v8, v218
	v_fmac_f32_e32 v115, v9, v236
	v_fmac_f32_e32 v116, v22, v216
	v_fmac_f32_e32 v116, v23, v217
	v_fmac_f32_e32 v116, v24, v218
	v_fmac_f32_e32 v116, v25, v236
	v_fmac_f32_e32 v117, v30, v216
	v_fmac_f32_e32 v117, v31, v217
	v_fmac_f32_e32 v117, v32, v218
	v_fmac_f32_e32 v117, v33, v236
	v_fmac_f32_e32 v118, v34, v216
	v_fmac_f32_e32 v118, v35, v217
	v_fmac_f32_e32 v118, v36, v218
	v_fmac_f32_e32 v118, v37, v236
	ds_read_b128 v[2:5], v10 offset:336
	ds_read_b128 v[6:9], v10 offset:4432
	ds_read_b128 v[22:25], v10 offset:8528
	ds_read_b128 v[30:33], v10 offset:12624
	ds_read_b128 v[34:37], v10 offset:16720
	s_waitcnt lgkmcnt(5)
	v_fmac_f32_e32 v119, v38, v216
	v_fmac_f32_e32 v119, v39, v217
	v_fmac_f32_e32 v119, v40, v218
	v_fmac_f32_e32 v119, v41, v236
	v_fmac_f32_e32 v120, v42, v216
	v_fmac_f32_e32 v120, v43, v217
	v_fmac_f32_e32 v120, v44, v218
	v_fmac_f32_e32 v120, v45, v236
	v_fmac_f32_e32 v121, v46, v216
	v_fmac_f32_e32 v121, v47, v217
	v_fmac_f32_e32 v121, v48, v218
	v_fmac_f32_e32 v121, v49, v236
	v_fmac_f32_e32 v112, v50, v216
	v_fmac_f32_e32 v112, v51, v217
	v_fmac_f32_e32 v112, v52, v218
	v_fmac_f32_e32 v112, v53, v236
	v_fmac_f32_e32 v113, v60, v216
	v_fmac_f32_e32 v113, v61, v217
	v_fmac_f32_e32 v113, v62, v218
	v_fmac_f32_e32 v113, v63, v236
	ds_read_b128 v[38:41], v10 offset:20816
	ds_read_b128 v[42:45], v10 offset:24912
	ds_read_b128 v[46:49], v10 offset:29008
	ds_read_b128 v[50:53], v10 offset:33104
	ds_read_b128 v[60:63], v10 offset:37200
	s_waitcnt lgkmcnt(5)
	v_fmac_f32_e32 v114, v2, v237
	v_fmac_f32_e32 v114, v3, v238
	v_fmac_f32_e32 v114, v4, v239
	v_fmac_f32_e32 v114, v5, v240
	v_fmac_f32_e32 v115, v6, v237
	v_fmac_f32_e32 v115, v7, v238
	v_fmac_f32_e32 v115, v8, v239
	v_fmac_f32_e32 v115, v9, v240
	v_fmac_f32_e32 v116, v22, v237
	v_fmac_f32_e32 v116, v23, v238
	v_fmac_f32_e32 v116, v24, v239
	v_fmac_f32_e32 v116, v25, v240
	v_fmac_f32_e32 v117, v30, v237
	v_fmac_f32_e32 v117, v31, v238
	v_fmac_f32_e32 v117, v32, v239
	v_fmac_f32_e32 v117, v33, v240
	v_fmac_f32_e32 v118, v34, v237
	v_fmac_f32_e32 v118, v35, v238
	v_fmac_f32_e32 v118, v36, v239
	v_fmac_f32_e32 v118, v37, v240
	ds_read_b128 v[2:5], v10 offset:352
	ds_read_b128 v[6:9], v10 offset:4448
	ds_read_b128 v[22:25], v10 offset:8544
	ds_read_b128 v[30:33], v10 offset:12640
	ds_read_b128 v[34:37], v10 offset:16736
	s_waitcnt lgkmcnt(5)
	v_fmac_f32_e32 v119, v38, v237
	v_fmac_f32_e32 v119, v39, v238
	v_fmac_f32_e32 v119, v40, v239
	v_fmac_f32_e32 v119, v41, v240
	v_fmac_f32_e32 v120, v42, v237
	v_fmac_f32_e32 v120, v43, v238
	v_fmac_f32_e32 v120, v44, v239
	v_fmac_f32_e32 v120, v45, v240
	v_fmac_f32_e32 v121, v46, v237
	v_fmac_f32_e32 v121, v47, v238
	v_fmac_f32_e32 v121, v48, v239
	v_fmac_f32_e32 v121, v49, v240
	v_fmac_f32_e32 v112, v50, v237
	v_fmac_f32_e32 v112, v51, v238
	v_fmac_f32_e32 v112, v52, v239
	v_fmac_f32_e32 v112, v53, v240
	v_fmac_f32_e32 v113, v60, v237
	v_fmac_f32_e32 v113, v61, v238
	v_fmac_f32_e32 v113, v62, v239
	v_fmac_f32_e32 v113, v63, v240
	ds_read_b128 v[38:41], v10 offset:20832
	ds_read_b128 v[42:45], v10 offset:24928
	ds_read_b128 v[46:49], v10 offset:29024
	ds_read_b128 v[50:53], v10 offset:33120
	ds_read_b128 v[60:63], v10 offset:37216
	s_waitcnt lgkmcnt(5)
; #define LAS __attribute__((address_space(3)))
; DI void adaln_layer(const Frame& F, int l, int b_idx, int b_cnt) {
;     ...
;         for (int kb = k0; kb < k0 + 128; kb += 16) {
;             float wv[16];
; #pragma unroll
;             for (int i = 0; i < 16; ++i) { wv[i] = __builtin_nontemporal_load(wp_); wp_ += MODW; }
; #pragma unroll
;             for (int i = 0; i < 16; i += 4) {
; #pragma unroll
;                 for (int s = 0; s < NSEQ; ++s) { const f32x4 c4 = *(const LAS f32x4*)(sc + s * DM + kb + i); acc[s] += (c4[0] * wv[i] + c4[1] * wv[i + 1]) + (c4[2] * wv[i + 2] + c4[3] * wv[i + 3]); } }
	v_fmac_f32_e32 v114, v2, v241
	v_fmac_f32_e32 v114, v3, v242
	v_fmac_f32_e32 v114, v4, v243
	v_fmac_f32_e32 v114, v5, v244
	v_fmac_f32_e32 v115, v6, v241
	v_fmac_f32_e32 v115, v7, v242
	v_fmac_f32_e32 v115, v8, v243
	v_fmac_f32_e32 v115, v9, v244
	v_fmac_f32_e32 v116, v22, v241
	v_fmac_f32_e32 v116, v23, v242
	v_fmac_f32_e32 v116, v24, v243
	v_fmac_f32_e32 v116, v25, v244
	v_fmac_f32_e32 v117, v30, v241
	v_fmac_f32_e32 v117, v31, v242
	v_fmac_f32_e32 v117, v32, v243
	v_fmac_f32_e32 v117, v33, v244
	v_fmac_f32_e32 v118, v34, v241
	v_fmac_f32_e32 v118, v35, v242
	v_fmac_f32_e32 v118, v36, v243
	v_fmac_f32_e32 v118, v37, v244
	ds_read_b128 v[2:5], v10 offset:368
	ds_read_b128 v[6:9], v10 offset:4464
	ds_read_b128 v[22:25], v10 offset:8560
	ds_read_b128 v[30:33], v10 offset:12656
	ds_read_b128 v[34:37], v10 offset:16752
	s_waitcnt lgkmcnt(5)
	v_fmac_f32_e32 v119, v38, v241
	v_fmac_f32_e32 v119, v39, v242
	v_fmac_f32_e32 v119, v40, v243
	v_fmac_f32_e32 v119, v41, v244
	v_fmac_f32_e32 v120, v42, v241
	v_fmac_f32_e32 v120, v43, v242
	v_fmac_f32_e32 v120, v44, v243
	v_fmac_f32_e32 v120, v45, v244
	v_fmac_f32_e32 v121, v46, v241
	v_fmac_f32_e32 v121, v47, v242
	v_fmac_f32_e32 v121, v48, v243
	v_fmac_f32_e32 v121, v49, v244
	v_fmac_f32_e32 v112, v50, v241
	v_fmac_f32_e32 v112, v51, v242
	v_fmac_f32_e32 v112, v52, v243
	v_fmac_f32_e32 v112, v53, v244
	v_fmac_f32_e32 v113, v60, v241
	v_fmac_f32_e32 v113, v61, v242
	v_fmac_f32_e32 v113, v62, v243
	v_fmac_f32_e32 v113, v63, v244
	ds_read_b128 v[38:41], v10 offset:20848
	ds_read_b128 v[42:45], v10 offset:24944
	ds_read_b128 v[46:49], v10 offset:29040
	ds_read_b128 v[50:53], v10 offset:33136
	ds_read_b128 v[60:63], v10 offset:37232
	s_waitcnt lgkmcnt(5)
	v_fmac_f32_e32 v114, v2, v245
	v_fmac_f32_e32 v114, v3, v248
	v_fmac_f32_e32 v114, v4, v249
	v_fmac_f32_e32 v114, v5, v250
	v_fmac_f32_e32 v115, v6, v245
	v_fmac_f32_e32 v115, v7, v248
	v_fmac_f32_e32 v115, v8, v249
	v_fmac_f32_e32 v115, v9, v250
	v_fmac_f32_e32 v116, v22, v245
	v_fmac_f32_e32 v116, v23, v248
	v_fmac_f32_e32 v116, v24, v249
	v_fmac_f32_e32 v116, v25, v250
	v_fmac_f32_e32 v117, v30, v245
	v_fmac_f32_e32 v117, v31, v248
	v_fmac_f32_e32 v117, v32, v249
	v_fmac_f32_e32 v117, v33, v250
	v_fmac_f32_e32 v118, v34, v245
	v_fmac_f32_e32 v118, v35, v248
	v_fmac_f32_e32 v118, v36, v249
	v_fmac_f32_e32 v118, v37, v250
	s_waitcnt lgkmcnt(0)
	v_fmac_f32_e32 v119, v38, v245
	v_fmac_f32_e32 v119, v39, v248
	v_fmac_f32_e32 v119, v40, v249
	v_fmac_f32_e32 v119, v41, v250
	v_fmac_f32_e32 v120, v42, v245
	v_fmac_f32_e32 v120, v43, v248
	v_fmac_f32_e32 v120, v44, v249
	v_fmac_f32_e32 v120, v45, v250
	v_fmac_f32_e32 v121, v46, v245
	v_fmac_f32_e32 v121, v47, v248
	v_fmac_f32_e32 v121, v48, v249
	v_fmac_f32_e32 v121, v49, v250
	v_fmac_f32_e32 v112, v50, v245
	v_fmac_f32_e32 v112, v51, v248
	v_fmac_f32_e32 v112, v52, v249
	v_fmac_f32_e32 v112, v53, v250
	v_fmac_f32_e32 v113, v60, v245
	v_fmac_f32_e32 v113, v61, v248
	v_fmac_f32_e32 v113, v62, v249
	v_fmac_f32_e32 v113, v63, v250
	s_waitcnt vmcnt(16)
	ds_read_b128 v[2:5], v10 offset:384
	ds_read_b128 v[6:9], v10 offset:4480
	ds_read_b128 v[22:25], v10 offset:8576
	ds_read_b128 v[30:33], v10 offset:12672
	ds_read_b128 v[34:37], v10 offset:16768
	ds_read_b128 v[38:41], v10 offset:20864
	ds_read_b128 v[42:45], v10 offset:24960
	ds_read_b128 v[46:49], v10 offset:29056
	ds_read_b128 v[50:53], v10 offset:33152
	ds_read_b128 v[60:63], v10 offset:37248
	s_waitcnt lgkmcnt(5)
	v_fmac_f32_e32 v114, v2, v184
	v_fmac_f32_e32 v114, v3, v185
	v_fmac_f32_e32 v114, v4, v186
	v_fmac_f32_e32 v114, v5, v187
	v_fmac_f32_e32 v115, v6, v184
	v_fmac_f32_e32 v115, v7, v185
	v_fmac_f32_e32 v115, v8, v186
	v_fmac_f32_e32 v115, v9, v187
	v_fmac_f32_e32 v116, v22, v184
	v_fmac_f32_e32 v116, v23, v185
	v_fmac_f32_e32 v116, v24, v186
	v_fmac_f32_e32 v116, v25, v187
	v_fmac_f32_e32 v117, v30, v184
	v_fmac_f32_e32 v117, v31, v185
	v_fmac_f32_e32 v117, v32, v186
	v_fmac_f32_e32 v117, v33, v187
	v_fmac_f32_e32 v118, v34, v184
	v_fmac_f32_e32 v118, v35, v185
	v_fmac_f32_e32 v118, v36, v186
	v_fmac_f32_e32 v118, v37, v187
	ds_read_b128 v[2:5], v10 offset:400
	ds_read_b128 v[6:9], v10 offset:4496
	ds_read_b128 v[22:25], v10 offset:8592
	ds_read_b128 v[30:33], v10 offset:12688
	ds_read_b128 v[34:37], v10 offset:16784
	s_waitcnt lgkmcnt(5)
	v_fmac_f32_e32 v119, v38, v184
	v_fmac_f32_e32 v119, v39, v185
	v_fmac_f32_e32 v119, v40, v186
	v_fmac_f32_e32 v119, v41, v187
	v_fmac_f32_e32 v120, v42, v184
	v_fmac_f32_e32 v120, v43, v185
	v_fmac_f32_e32 v120, v44, v186
	v_fmac_f32_e32 v120, v45, v187
	v_fmac_f32_e32 v121, v46, v184
	v_fmac_f32_e32 v121, v47, v185
	v_fmac_f32_e32 v121, v48, v186
	v_fmac_f32_e32 v121, v49, v187
	v_fmac_f32_e32 v112, v50, v184
	v_fmac_f32_e32 v112, v51, v185
	v_fmac_f32_e32 v112, v52, v186
	v_fmac_f32_e32 v112, v53, v187
	v_fmac_f32_e32 v113, v60, v184
	v_fmac_f32_e32 v113, v61, v185
	v_fmac_f32_e32 v113, v62, v186
	v_fmac_f32_e32 v113, v63, v187
	ds_read_b128 v[38:41], v10 offset:20880
	ds_read_b128 v[42:45], v10 offset:24976
	ds_read_b128 v[46:49], v10 offset:29072
	ds_read_b128 v[50:53], v10 offset:33168
	ds_read_b128 v[60:63], v10 offset:37264
	s_waitcnt lgkmcnt(5)
	v_fmac_f32_e32 v114, v2, v188
	v_fmac_f32_e32 v114, v3, v189
	v_fmac_f32_e32 v114, v4, v190
	v_fmac_f32_e32 v114, v5, v191
	v_fmac_f32_e32 v115, v6, v188
	v_fmac_f32_e32 v115, v7, v189
	v_fmac_f32_e32 v115, v8, v190
	v_fmac_f32_e32 v115, v9, v191
	v_fmac_f32_e32 v116, v22, v188
	v_fmac_f32_e32 v116, v23, v189
	v_fmac_f32_e32 v116, v24, v190
	v_fmac_f32_e32 v116, v25, v191
	v_fmac_f32_e32 v117, v30, v188
	v_fmac_f32_e32 v117, v31, v189
	v_fmac_f32_e32 v117, v32, v190
	v_fmac_f32_e32 v117, v33, v191
	v_fmac_f32_e32 v118, v34, v188
	v_fmac_f32_e32 v118, v35, v189
	v_fmac_f32_e32 v118, v36, v190
	v_fmac_f32_e32 v118, v37, v191
	ds_read_b128 v[2:5], v10 offset:416
	ds_read_b128 v[6:9], v10 offset:4512
	ds_read_b128 v[22:25], v10 offset:8608
	ds_read_b128 v[30:33], v10 offset:12704
	ds_read_b128 v[34:37], v10 offset:16800
	s_waitcnt lgkmcnt(5)
; #define LAS __attribute__((address_space(3)))
; DI void adaln_layer(const Frame& F, int l, int b_idx, int b_cnt) {
;     ...
;         for (int kb = k0; kb < k0 + 128; kb += 16) {
;             float wv[16];
; #pragma unroll
;             for (int i = 0; i < 16; ++i) { wv[i] = __builtin_nontemporal_load(wp_); wp_ += MODW; }
; #pragma unroll
;             for (int i = 0; i < 16; i += 4) {
; #pragma unroll
;                 for (int s = 0; s < NSEQ; ++s) { const f32x4 c4 = *(const LAS f32x4*)(sc + s * DM + kb + i); acc[s] += (c4[0] * wv[i] + c4[1] * wv[i + 1]) + (c4[2] * wv[i + 2] + c4[3] * wv[i + 3]); } }
	v_fmac_f32_e32 v119, v38, v188
	v_fmac_f32_e32 v119, v39, v189
	v_fmac_f32_e32 v119, v40, v190
	v_fmac_f32_e32 v119, v41, v191
	v_fmac_f32_e32 v120, v42, v188
	v_fmac_f32_e32 v120, v43, v189
	v_fmac_f32_e32 v120, v44, v190
	v_fmac_f32_e32 v120, v45, v191
	v_fmac_f32_e32 v121, v46, v188
	v_fmac_f32_e32 v121, v47, v189
	v_fmac_f32_e32 v121, v48, v190
	v_fmac_f32_e32 v121, v49, v191
	v_fmac_f32_e32 v112, v50, v188
	v_fmac_f32_e32 v112, v51, v189
	v_fmac_f32_e32 v112, v52, v190
	v_fmac_f32_e32 v112, v53, v191
	v_fmac_f32_e32 v113, v60, v188
	v_fmac_f32_e32 v113, v61, v189
	v_fmac_f32_e32 v113, v62, v190
	v_fmac_f32_e32 v113, v63, v191
	ds_read_b128 v[38:41], v10 offset:20896
	ds_read_b128 v[42:45], v10 offset:24992
	ds_read_b128 v[46:49], v10 offset:29088
	ds_read_b128 v[50:53], v10 offset:33184
	ds_read_b128 v[60:63], v10 offset:37280
	s_waitcnt lgkmcnt(5)
	v_fmac_f32_e32 v114, v2, v192
	v_fmac_f32_e32 v114, v3, v193
	v_fmac_f32_e32 v114, v4, v194
	v_fmac_f32_e32 v114, v5, v195
	v_fmac_f32_e32 v115, v6, v192
	v_fmac_f32_e32 v115, v7, v193
	v_fmac_f32_e32 v115, v8, v194
	v_fmac_f32_e32 v115, v9, v195
	v_fmac_f32_e32 v116, v22, v192
	v_fmac_f32_e32 v116, v23, v193
	v_fmac_f32_e32 v116, v24, v194
	v_fmac_f32_e32 v116, v25, v195
	v_fmac_f32_e32 v117, v30, v192
	v_fmac_f32_e32 v117, v31, v193
	v_fmac_f32_e32 v117, v32, v194
	v_fmac_f32_e32 v117, v33, v195
	v_fmac_f32_e32 v118, v34, v192
	v_fmac_f32_e32 v118, v35, v193
	v_fmac_f32_e32 v118, v36, v194
	v_fmac_f32_e32 v118, v37, v195
	ds_read_b128 v[2:5], v10 offset:432
	ds_read_b128 v[6:9], v10 offset:4528
	ds_read_b128 v[22:25], v10 offset:8624
	ds_read_b128 v[30:33], v10 offset:12720
	ds_read_b128 v[34:37], v10 offset:16816
	s_waitcnt lgkmcnt(5)
	v_fmac_f32_e32 v119, v38, v192
	v_fmac_f32_e32 v119, v39, v193
	v_fmac_f32_e32 v119, v40, v194
	v_fmac_f32_e32 v119, v41, v195
	v_fmac_f32_e32 v120, v42, v192
	v_fmac_f32_e32 v120, v43, v193
	v_fmac_f32_e32 v120, v44, v194
	v_fmac_f32_e32 v120, v45, v195
	v_fmac_f32_e32 v121, v46, v192
	v_fmac_f32_e32 v121, v47, v193
	v_fmac_f32_e32 v121, v48, v194
	v_fmac_f32_e32 v121, v49, v195
	v_fmac_f32_e32 v112, v50, v192
	v_fmac_f32_e32 v112, v51, v193
	v_fmac_f32_e32 v112, v52, v194
	v_fmac_f32_e32 v112, v53, v195
	v_fmac_f32_e32 v113, v60, v192
	v_fmac_f32_e32 v113, v61, v193
	v_fmac_f32_e32 v113, v62, v194
	v_fmac_f32_e32 v113, v63, v195
	ds_read_b128 v[38:41], v10 offset:20912
	ds_read_b128 v[42:45], v10 offset:25008
	ds_read_b128 v[46:49], v10 offset:29104
	ds_read_b128 v[50:53], v10 offset:33200
	ds_read_b128 v[60:63], v10 offset:37296
	s_waitcnt lgkmcnt(5)
	v_fmac_f32_e32 v114, v2, v196
	v_fmac_f32_e32 v114, v3, v197
	v_fmac_f32_e32 v114, v4, v198
	v_fmac_f32_e32 v114, v5, v199
	v_fmac_f32_e32 v115, v6, v196
	v_fmac_f32_e32 v115, v7, v197
	v_fmac_f32_e32 v115, v8, v198
	v_fmac_f32_e32 v115, v9, v199
	v_fmac_f32_e32 v116, v22, v196
	v_fmac_f32_e32 v116, v23, v197
	v_fmac_f32_e32 v116, v24, v198
	v_fmac_f32_e32 v116, v25, v199
	v_fmac_f32_e32 v117, v30, v196
	v_fmac_f32_e32 v117, v31, v197
	v_fmac_f32_e32 v117, v32, v198
	v_fmac_f32_e32 v117, v33, v199
	v_fmac_f32_e32 v118, v34, v196
	v_fmac_f32_e32 v118, v35, v197
	v_fmac_f32_e32 v118, v36, v198
	v_fmac_f32_e32 v118, v37, v199
	s_waitcnt lgkmcnt(0)
	v_fmac_f32_e32 v119, v38, v196
	v_fmac_f32_e32 v119, v39, v197
	v_fmac_f32_e32 v119, v40, v198
	v_fmac_f32_e32 v119, v41, v199
	v_fmac_f32_e32 v120, v42, v196
	v_fmac_f32_e32 v120, v43, v197
	v_fmac_f32_e32 v120, v44, v198
	v_fmac_f32_e32 v120, v45, v199
	v_fmac_f32_e32 v121, v46, v196
	v_fmac_f32_e32 v121, v47, v197
	v_fmac_f32_e32 v121, v48, v198
	v_fmac_f32_e32 v121, v49, v199
	v_fmac_f32_e32 v112, v50, v196
	v_fmac_f32_e32 v112, v51, v197
	v_fmac_f32_e32 v112, v52, v198
	v_fmac_f32_e32 v112, v53, v199
	v_fmac_f32_e32 v113, v60, v196
	v_fmac_f32_e32 v113, v61, v197
	v_fmac_f32_e32 v113, v62, v198
	v_fmac_f32_e32 v113, v63, v199
	s_waitcnt vmcnt(0)
	ds_read_b128 v[2:5], v10 offset:448
	ds_read_b128 v[6:9], v10 offset:4544
	ds_read_b128 v[22:25], v10 offset:8640
	ds_read_b128 v[30:33], v10 offset:12736
	ds_read_b128 v[34:37], v10 offset:16832
	ds_read_b128 v[38:41], v10 offset:20928
	ds_read_b128 v[42:45], v10 offset:25024
	ds_read_b128 v[46:49], v10 offset:29120
	ds_read_b128 v[50:53], v10 offset:33216
	ds_read_b128 v[60:63], v10 offset:37312
	s_waitcnt lgkmcnt(5)
	v_fmac_f32_e32 v114, v2, v200
	v_fmac_f32_e32 v114, v3, v201
	v_fmac_f32_e32 v114, v4, v202
	v_fmac_f32_e32 v114, v5, v203
	v_fmac_f32_e32 v115, v6, v200
	v_fmac_f32_e32 v115, v7, v201
	v_fmac_f32_e32 v115, v8, v202
	v_fmac_f32_e32 v115, v9, v203
	v_fmac_f32_e32 v116, v22, v200
	v_fmac_f32_e32 v116, v23, v201
	v_fmac_f32_e32 v116, v24, v202
	v_fmac_f32_e32 v116, v25, v203
	v_fmac_f32_e32 v117, v30, v200
	v_fmac_f32_e32 v117, v31, v201
	v_fmac_f32_e32 v117, v32, v202
	v_fmac_f32_e32 v117, v33, v203
	v_fmac_f32_e32 v118, v34, v200
	v_fmac_f32_e32 v118, v35, v201
	v_fmac_f32_e32 v118, v36, v202
	v_fmac_f32_e32 v118, v37, v203
	ds_read_b128 v[2:5], v10 offset:464
	ds_read_b128 v[6:9], v10 offset:4560
	ds_read_b128 v[22:25], v10 offset:8656
	ds_read_b128 v[30:33], v10 offset:12752
	ds_read_b128 v[34:37], v10 offset:16848
	s_waitcnt lgkmcnt(5)
	v_fmac_f32_e32 v119, v38, v200
	v_fmac_f32_e32 v119, v39, v201
	v_fmac_f32_e32 v119, v40, v202
	v_fmac_f32_e32 v119, v41, v203
	v_fmac_f32_e32 v120, v42, v200
	v_fmac_f32_e32 v120, v43, v201
	v_fmac_f32_e32 v120, v44, v202
	v_fmac_f32_e32 v120, v45, v203
	v_fmac_f32_e32 v121, v46, v200
	v_fmac_f32_e32 v121, v47, v201
	v_fmac_f32_e32 v121, v48, v202
	v_fmac_f32_e32 v121, v49, v203
	v_fmac_f32_e32 v112, v50, v200
	v_fmac_f32_e32 v112, v51, v201
	v_fmac_f32_e32 v112, v52, v202
	v_fmac_f32_e32 v112, v53, v203
	v_fmac_f32_e32 v113, v60, v200
	v_fmac_f32_e32 v113, v61, v201
	v_fmac_f32_e32 v113, v62, v202
	v_fmac_f32_e32 v113, v63, v203
	ds_read_b128 v[38:41], v10 offset:20944
	ds_read_b128 v[42:45], v10 offset:25040
	ds_read_b128 v[46:49], v10 offset:29136
	ds_read_b128 v[50:53], v10 offset:33232
	ds_read_b128 v[60:63], v10 offset:37328
	s_waitcnt lgkmcnt(5)
; #define LAS __attribute__((address_space(3)))
; DI void adaln_layer(const Frame& F, int l, int b_idx, int b_cnt) {
;     ...
;         for (int kb = k0; kb < k0 + 128; kb += 16) {
;             float wv[16];
; #pragma unroll
;             for (int i = 0; i < 16; ++i) { wv[i] = __builtin_nontemporal_load(wp_); wp_ += MODW; }
; #pragma unroll
;             for (int i = 0; i < 16; i += 4) {
; #pragma unroll
;                 for (int s = 0; s < NSEQ; ++s) { const f32x4 c4 = *(const LAS f32x4*)(sc + s * DM + kb + i); acc[s] += (c4[0] * wv[i] + c4[1] * wv[i + 1]) + (c4[2] * wv[i + 2] + c4[3] * wv[i + 3]); } }
;         }
; #pragma unroll
;         for (int s = 0; s < NSEQ; ++s) part[(F.wave * NSEQ + s) * 64 + F.lane] = acc[s];
;         __syncthreads();
	v_fmac_f32_e32 v114, v2, v204
	v_fmac_f32_e32 v114, v3, v205
	v_fmac_f32_e32 v114, v4, v206
	v_fmac_f32_e32 v114, v5, v207
	v_fmac_f32_e32 v115, v6, v204
	v_fmac_f32_e32 v115, v7, v205
	v_fmac_f32_e32 v115, v8, v206
	v_fmac_f32_e32 v115, v9, v207
	v_fmac_f32_e32 v116, v22, v204
	v_fmac_f32_e32 v116, v23, v205
	v_fmac_f32_e32 v116, v24, v206
	v_fmac_f32_e32 v116, v25, v207
	v_fmac_f32_e32 v117, v30, v204
	v_fmac_f32_e32 v117, v31, v205
	v_fmac_f32_e32 v117, v32, v206
	v_fmac_f32_e32 v117, v33, v207
	v_fmac_f32_e32 v118, v34, v204
	v_fmac_f32_e32 v118, v35, v205
	v_fmac_f32_e32 v118, v36, v206
	v_fmac_f32_e32 v118, v37, v207
	ds_read_b128 v[2:5], v10 offset:480
	ds_read_b128 v[6:9], v10 offset:4576
	ds_read_b128 v[22:25], v10 offset:8672
	ds_read_b128 v[30:33], v10 offset:12768
	ds_read_b128 v[34:37], v10 offset:16864
	s_waitcnt lgkmcnt(5)
	v_fmac_f32_e32 v119, v38, v204
	v_fmac_f32_e32 v119, v39, v205
	v_fmac_f32_e32 v119, v40, v206
	v_fmac_f32_e32 v119, v41, v207
	v_fmac_f32_e32 v120, v42, v204
	v_fmac_f32_e32 v120, v43, v205
	v_fmac_f32_e32 v120, v44, v206
	v_fmac_f32_e32 v120, v45, v207
	v_fmac_f32_e32 v121, v46, v204
	v_fmac_f32_e32 v121, v47, v205
	v_fmac_f32_e32 v121, v48, v206
	v_fmac_f32_e32 v121, v49, v207
	v_fmac_f32_e32 v112, v50, v204
	v_fmac_f32_e32 v112, v51, v205
	v_fmac_f32_e32 v112, v52, v206
	v_fmac_f32_e32 v112, v53, v207
	v_fmac_f32_e32 v113, v60, v204
	v_fmac_f32_e32 v113, v61, v205
	v_fmac_f32_e32 v113, v62, v206
	v_fmac_f32_e32 v113, v63, v207
	ds_read_b128 v[38:41], v10 offset:20960
	ds_read_b128 v[42:45], v10 offset:25056
	ds_read_b128 v[46:49], v10 offset:29152
	ds_read_b128 v[50:53], v10 offset:33248
	ds_read_b128 v[60:63], v10 offset:37344
	s_waitcnt lgkmcnt(5)
	v_fmac_f32_e32 v114, v2, v208
	v_fmac_f32_e32 v114, v3, v209
	v_fmac_f32_e32 v114, v4, v210
	v_fmac_f32_e32 v114, v5, v211
	v_fmac_f32_e32 v115, v6, v208
	v_fmac_f32_e32 v115, v7, v209
	v_fmac_f32_e32 v115, v8, v210
	v_fmac_f32_e32 v115, v9, v211
	v_fmac_f32_e32 v116, v22, v208
	v_fmac_f32_e32 v116, v23, v209
	v_fmac_f32_e32 v116, v24, v210
	v_fmac_f32_e32 v116, v25, v211
	v_fmac_f32_e32 v117, v30, v208
	v_fmac_f32_e32 v117, v31, v209
	v_fmac_f32_e32 v117, v32, v210
	v_fmac_f32_e32 v117, v33, v211
	v_fmac_f32_e32 v118, v34, v208
	v_fmac_f32_e32 v118, v35, v209
	v_fmac_f32_e32 v118, v36, v210
	v_fmac_f32_e32 v118, v37, v211
	ds_read_b128 v[2:5], v10 offset:496
	ds_read_b128 v[6:9], v10 offset:4592
	ds_read_b128 v[22:25], v10 offset:8688
	ds_read_b128 v[30:33], v10 offset:12784
	ds_read_b128 v[34:37], v10 offset:16880
	s_waitcnt lgkmcnt(5)
	v_fmac_f32_e32 v119, v38, v208
	v_fmac_f32_e32 v119, v39, v209
	v_fmac_f32_e32 v119, v40, v210
	v_fmac_f32_e32 v119, v41, v211
	v_fmac_f32_e32 v120, v42, v208
	v_fmac_f32_e32 v120, v43, v209
	v_fmac_f32_e32 v120, v44, v210
	v_fmac_f32_e32 v120, v45, v211
	v_fmac_f32_e32 v121, v46, v208
	v_fmac_f32_e32 v121, v47, v209
	v_fmac_f32_e32 v121, v48, v210
	v_fmac_f32_e32 v121, v49, v211
	v_fmac_f32_e32 v112, v50, v208
	v_fmac_f32_e32 v112, v51, v209
	v_fmac_f32_e32 v112, v52, v210
	v_fmac_f32_e32 v112, v53, v211
	v_fmac_f32_e32 v113, v60, v208
	v_fmac_f32_e32 v113, v61, v209
	v_fmac_f32_e32 v113, v62, v210
	v_fmac_f32_e32 v113, v63, v211
	ds_read_b128 v[38:41], v10 offset:20976
	ds_read_b128 v[42:45], v10 offset:25072
	ds_read_b128 v[46:49], v10 offset:29168
	ds_read_b128 v[50:53], v10 offset:33264
	ds_read_b128 v[60:63], v10 offset:37360
	s_waitcnt lgkmcnt(5)
	v_fmac_f32_e32 v114, v2, v212
	v_fmac_f32_e32 v114, v3, v213
	v_fmac_f32_e32 v114, v4, v214
	v_fmac_f32_e32 v114, v5, v215
	v_fmac_f32_e32 v115, v6, v212
	v_fmac_f32_e32 v115, v7, v213
	v_fmac_f32_e32 v115, v8, v214
	v_fmac_f32_e32 v115, v9, v215
	v_fmac_f32_e32 v116, v22, v212
	v_fmac_f32_e32 v116, v23, v213
	v_fmac_f32_e32 v116, v24, v214
	v_fmac_f32_e32 v116, v25, v215
	v_fmac_f32_e32 v117, v30, v212
	v_fmac_f32_e32 v117, v31, v213
	v_fmac_f32_e32 v117, v32, v214
	v_fmac_f32_e32 v117, v33, v215
	v_fmac_f32_e32 v118, v34, v212
	v_fmac_f32_e32 v118, v35, v213
	v_fmac_f32_e32 v118, v36, v214
	v_fmac_f32_e32 v118, v37, v215
	s_waitcnt lgkmcnt(0)
	v_fmac_f32_e32 v119, v38, v212
	v_fmac_f32_e32 v119, v39, v213
	v_fmac_f32_e32 v119, v40, v214
	v_fmac_f32_e32 v119, v41, v215
	v_fmac_f32_e32 v120, v42, v212
	v_fmac_f32_e32 v120, v43, v213
	v_fmac_f32_e32 v120, v44, v214
	v_fmac_f32_e32 v120, v45, v215
	v_fmac_f32_e32 v121, v46, v212
	v_fmac_f32_e32 v121, v47, v213
	v_fmac_f32_e32 v121, v48, v214
	v_fmac_f32_e32 v121, v49, v215
	v_fmac_f32_e32 v112, v50, v212
	v_fmac_f32_e32 v112, v51, v213
	v_fmac_f32_e32 v112, v52, v214
	v_fmac_f32_e32 v112, v53, v215
	v_fmac_f32_e32 v113, v60, v212
	v_fmac_f32_e32 v113, v61, v213
	v_fmac_f32_e32 v113, v62, v214
	v_fmac_f32_e32 v113, v63, v215
	s_mul_i32 s0, s23, 0xa00
	v_add_u32_e32 v2, s0, v1
	ds_write2st64_b32 v2, v114, v115 offset0:160 offset1:161
	ds_write2st64_b32 v2, v116, v117 offset0:162 offset1:163
	ds_write2st64_b32 v2, v118, v119 offset0:164 offset1:165
	ds_write2st64_b32 v2, v120, v121 offset0:166 offset1:167
	ds_write2st64_b32 v2, v112, v113 offset0:168 offset1:169
	s_waitcnt lgkmcnt(0)
	s_barrier
	s_and_saveexec_b64 s[18:19], s[38:39]
	s_cbranch_execz .LBB0_150
	v_lshl_add_u64 v[2:3], v[104:105], 0, s[30:31]
	v_lshl_add_u64 v[4:5], v[106:107], 0, s[30:31]
	s_mov_b64 s[30:31], 0
	v_mov_b32_e32 v6, v130
